# nt loads on all cold read-once streams: f32 inputs in prep + late w_out_b transpose + attention K/V LDS-DMA
# speedup vs baseline: 1.0200x; 1.0033x over previous
.LBB0_680:
	v_readlane_b32 s0, v254, 48
	v_readlane_b32 s1, v254, 49
	s_xor_b64 s[0:1], s[0:1], -1
	v_writelane_b32 v254, s0, 56
	s_andn2_b64 vcc, exec, s[0:1]
	s_nop 0
	v_writelane_b32 v254, s1, 57
	s_cbranch_vccnz .LBB0_682
	v_mov_b32_e32 v0, v170
	v_readlane_b32 s6, v253, 30
	v_readfirstlane_b32 s0, v0
	v_and_b32_e32 v4, 63, v0
	s_ashr_i32 s0, s0, 6
	v_mov_b32_e32 v5, v4
	s_lshl_b32 s1, s0, 3
	v_ashrrev_i32_e32 v6, 3, v5
	v_add_u32_e32 v0, s1, v6
	v_lshrrev_b32_e32 v1, 1, v0
	v_xor_b32_e32 v2, v1, v5
	v_ashrrev_i32_e32 v1, 31, v0
	v_lshlrev_b64 v[0:1], 7, v[0:1]
	v_readlane_b32 s7, v253, 31
	v_lshlrev_b32_e32 v2, 4, v2
	v_and_b32_e32 v2, 0x70, v2
	v_lshl_add_u64 v[0:1], s[6:7], 0, v[0:1]
	s_lshl_b32 s2, s0, 10
	s_add_i32 s3, 0, 0x18000
	s_add_i32 s4, s0, 8
	v_lshl_add_u64 v[0:1], v[0:1], 0, v[2:3]
	s_add_i32 m0, s3, s2
	s_bitset0_b32 m0, 16
	s_bitset1_b32 m0, 14
	s_lshl_b32 s5, s4, 3
	global_load_lds_dwordx4 v[0:1], off nt
	v_add_u32_e32 v0, s5, v6
	v_lshrrev_b32_e32 v1, 1, v0
	v_xor_b32_e32 v2, v1, v5
	v_ashrrev_i32_e32 v1, 31, v0
	v_lshlrev_b64 v[0:1], 7, v[0:1]
	v_lshlrev_b32_e32 v2, 4, v2
	v_lshl_add_u64 v[0:1], s[6:7], 0, v[0:1]
	v_and_b32_e32 v2, 0x70, v2
	s_lshl_b32 s6, s4, 10
	v_lshl_add_u64 v[0:1], v[0:1], 0, v[2:3]
	s_add_i32 m0, s3, s6
	s_bitset0_b32 m0, 16
	s_bitset1_b32 m0, 14
	v_ashrrev_i32_e32 v6, 4, v5
	s_lshl_b32 s0, s0, 2
	global_load_lds_dwordx4 v[0:1], off nt
	v_add_u32_e32 v0, s0, v6
	v_xor_b32_e32 v2, v0, v5
	v_ashrrev_i32_e32 v1, 31, v0
	v_readlane_b32 s8, v253, 32
	v_lshlrev_b64 v[0:1], 15, v[0:1]
	v_readlane_b32 s9, v253, 33
	v_lshlrev_b32_e32 v2, 4, v2
	v_and_b32_e32 v2, 0xf0, v2
	v_lshl_add_u64 v[0:1], s[8:9], 0, v[0:1]
	s_add_i32 s3, 0, 0x1c000
	v_lshl_add_u64 v[0:1], v[0:1], 0, v[2:3]
	s_add_i32 m0, s3, s2
	s_lshl_b32 s4, s4, 2
	global_load_lds_dwordx4 v[0:1], off nt
	v_add_u32_e32 v0, s4, v6
	v_xor_b32_e32 v2, v0, v5
	v_ashrrev_i32_e32 v1, 31, v0
	v_lshlrev_b64 v[0:1], 15, v[0:1]
	v_lshlrev_b32_e32 v2, 4, v2
	v_lshl_add_u64 v[0:1], s[8:9], 0, v[0:1]
	v_and_b32_e32 v2, 0xf0, v2
	v_lshl_add_u64 v[0:1], v[0:1], 0, v[2:3]
	s_add_i32 m0, s3, s6
	v_readlane_b32 s8, v253, 34
	global_load_lds_dwordx4 v[0:1], off nt
	v_readlane_b32 s9, v253, 35
	v_ashrrev_i32_e32 v5, 3, v4
	v_add_u32_e32 v0, s1, v5
	v_lshrrev_b32_e32 v1, 1, v0
	v_xor_b32_e32 v2, v1, v4
	v_ashrrev_i32_e32 v1, 31, v0
	v_lshlrev_b64 v[0:1], 7, v[0:1]
	v_lshlrev_b32_e32 v2, 4, v2
	v_lshl_add_u64 v[0:1], s[8:9], 0, v[0:1]
	v_and_b32_e32 v2, 0x70, v2
	s_add_i32 s1, s2, 0
	v_lshl_add_u64 v[0:1], v[0:1], 0, v[2:3]
	s_mov_b32 m0, s1
	s_add_i32 s2, s6, 0
	global_load_lds_dwordx4 v[0:1], off nt
	v_add_u32_e32 v0, s5, v5
	v_lshrrev_b32_e32 v1, 1, v0
	v_xor_b32_e32 v2, v1, v4
	v_ashrrev_i32_e32 v1, 31, v0
	v_lshlrev_b64 v[0:1], 7, v[0:1]
	v_lshlrev_b32_e32 v2, 4, v2
	v_lshl_add_u64 v[0:1], s[8:9], 0, v[0:1]
	v_and_b32_e32 v2, 0x70, v2
	v_lshl_add_u64 v[0:1], v[0:1], 0, v[2:3]
	s_mov_b32 m0, s2
	v_ashrrev_i32_e32 v5, 4, v4
	global_load_lds_dwordx4 v[0:1], off nt
	v_add_u32_e32 v0, s0, v5
	v_xor_b32_e32 v2, v0, v4
	v_ashrrev_i32_e32 v1, 31, v0
	v_readlane_b32 s6, v253, 37
	v_lshlrev_b64 v[0:1], 15, v[0:1]
	v_readlane_b32 s7, v253, 38
	v_lshlrev_b32_e32 v2, 4, v2
	v_and_b32_e32 v2, 0xf0, v2
	v_lshl_add_u64 v[0:1], s[6:7], 0, v[0:1]
	v_lshl_add_u64 v[0:1], v[0:1], 0, v[2:3]
	s_add_i32 m0, s1, 0x4000
	s_bitset0_b32 m0, 14
	s_bitset1_b32 m0, 16
	s_nop 0
	global_load_lds_dwordx4 v[0:1], off nt
	v_add_u32_e32 v0, s4, v5
	v_xor_b32_e32 v2, v0, v4
	v_ashrrev_i32_e32 v1, 31, v0
	v_lshlrev_b64 v[0:1], 15, v[0:1]
	v_lshlrev_b32_e32 v2, 4, v2
	v_lshl_add_u64 v[0:1], s[6:7], 0, v[0:1]
	v_and_b32_e32 v2, 0xf0, v2
	v_lshl_add_u64 v[0:1], v[0:1], 0, v[2:3]
	s_add_i32 m0, s2, 0x4000
	s_bitset0_b32 m0, 14
	s_bitset1_b32 m0, 16
	s_nop 0
	global_load_lds_dwordx4 v[0:1], off nt

.Lat738_i0_nopend:
	s_add_u32 s83, s4, 1
	s_mov_b32 s84, s5
	s_mul_i32 s74, s84, 4096
	s_lshl_b32 s75, s83, 7
	s_add_u32 s74, s74, s75
	s_lshl_b32 s75, s74, 7
	s_add_u32 s16, s60, s75
	s_addc_u32 s17, s61, 0
	s_lshl_b32 s75, s74, 1
	s_add_u32 s24, s64, s75
	s_addc_u32 s25, s65, 0
	s_add_u32 m0, s70, 0x4000
	s_nop 0
	global_load_lds_dwordx4 v232, s[16:17] nt
	s_add_u32 m0, s70, 0x6000
	s_nop 0
	global_load_lds_dwordx4 v233, s[16:17] nt
	s_add_u32 m0, s70, 0x14000
	s_nop 0
	global_load_lds_dwordx4 v234, s[24:25] nt
	s_add_u32 m0, s70, 0x16000
	s_nop 0
	global_load_lds_dwordx4 v235, s[24:25] nt
	s_lshl_b32 s74, s83, 7
	s_add_u32 s74, s74, s84
	s_lshl_b32 s75, s74, 7
	s_add_u32 s10, s30, s75
	s_addc_u32 s11, s31, 0
	s_add_u32 s12, s34, s75
	s_addc_u32 s13, s35, 0
	s_lshl_b32 s75, s74, 2
	s_add_u32 s14, s58, s75
	s_addc_u32 s15, s59, 0
	global_load_dwordx4 v[104:107], v236, s[10:11]
	global_load_dwordx4 v[108:111], v236, s[10:11] offset:64
	s_waitcnt lgkmcnt(0)
	v_mfma_f32_16x16x32_bf16 v[44:47], v[4:7], v[96:99], 0
	v_mfma_f32_16x16x32_bf16 v[48:51], v[12:15], v[96:99], 0
	v_mfma_f32_16x16x32_bf16 v[52:55], v[20:23], v[96:99], 0
	v_mfma_f32_16x16x32_bf16 v[56:59], v[28:31], v[96:99], 0
	v_mfma_f32_16x16x32_bf16 v[60:63], v[36:39], v[96:99], 0
	v_mfma_f32_16x16x32_bf16 v[44:47], v[8:11], v[100:103], v[44:47]
	v_mfma_f32_16x16x32_bf16 v[48:51], v[16:19], v[100:103], v[48:51]
	v_mfma_f32_16x16x32_bf16 v[52:55], v[24:27], v[100:103], v[52:55]
	v_mfma_f32_16x16x32_bf16 v[56:59], v[32:35], v[100:103], v[56:59]
	v_mfma_f32_16x16x32_bf16 v[60:63], v[40:43], v[100:103], v[60:63]
	s_cmp_gt_u32 s6, 5
	s_cselect_b32 s74, s77, s78
	v_add_u32_e32 v146, s74, v230
	v_xor_b32_e32 v147, 64, v146
	ds_read_b128 v[4:7], v146 offset:10240
	ds_read_b128 v[8:11], v147 offset:10240
	s_cmp_gt_u32 s6, 6
	s_cselect_b32 s74, s77, s78
	v_add_u32_e32 v146, s74, v230
	v_xor_b32_e32 v147, 64, v146
	ds_read_b128 v[12:15], v146 offset:12288
	ds_read_b128 v[16:19], v147 offset:12288
	s_cmp_gt_u32 s6, 7
	s_cselect_b32 s74, s77, s78
	v_add_u32_e32 v146, s74, v230
	v_xor_b32_e32 v147, 64, v146
	ds_read_b128 v[20:23], v146 offset:14336
	ds_read_b128 v[24:27], v147 offset:14336
	s_cmp_gt_u32 s6, 8
	s_cselect_b32 s74, s77, s78
	v_add_u32_e32 v146, s74, v230
	v_xor_b32_e32 v147, 64, v146
	ds_read_b128 v[28:31], v146 offset:16384
	ds_read_b128 v[32:35], v147 offset:16384
	s_nop 1
	v_fma_f32 v44, v44, s79, v185
	v_fma_f32 v45, v45, s79, v186
	v_fma_f32 v46, v46, s79, v187
	v_fma_f32 v47, v47, s79, v188
	v_fma_f32 v48, v48, s79, v189
	v_fma_f32 v49, v49, s79, v190
	v_fma_f32 v50, v50, s79, v191
	v_fma_f32 v51, v51, s79, v192
	v_fma_f32 v52, v52, s79, v193
	v_fma_f32 v53, v53, s79, v194
	v_fma_f32 v54, v54, s79, v195
	v_fma_f32 v55, v55, s79, v196
	v_fma_f32 v56, v56, s79, v197
	v_fma_f32 v57, v57, s79, v198
	v_fma_f32 v58, v58, s79, v199
	v_fma_f32 v59, v59, s79, v200
	v_fma_f32 v60, v60, s79, v201
	v_fma_f32 v61, v61, s79, v202
	v_fma_f32 v62, v62, s79, v203
	v_fma_f32 v63, v63, s79, v204
	s_waitcnt lgkmcnt(0)
	v_mfma_f32_16x16x32_bf16 v[64:67], v[4:7], v[96:99], 0
	v_mfma_f32_16x16x32_bf16 v[68:71], v[12:15], v[96:99], 0
	v_mfma_f32_16x16x32_bf16 v[72:75], v[20:23], v[96:99], 0
	v_mfma_f32_16x16x32_bf16 v[76:79], v[28:31], v[96:99], 0
	v_mfma_f32_16x16x32_bf16 v[64:67], v[8:11], v[100:103], v[64:67]
	v_mfma_f32_16x16x32_bf16 v[68:71], v[16:19], v[100:103], v[68:71]
	v_mfma_f32_16x16x32_bf16 v[72:75], v[24:27], v[100:103], v[72:75]
	v_mfma_f32_16x16x32_bf16 v[76:79], v[32:35], v[100:103], v[76:79]
	s_cmp_gt_u32 s6, 0
	s_cselect_b32 s74, 0, 0xffff0000
	v_add_u32_e32 v146, s74, v221
	ds_read_b64 v[4:5], v146 offset:49152
	ds_read_b64 v[8:9], v146 offset:53248
	ds_read_b64 v[12:13], v146 offset:57344
	ds_read_b64 v[16:17], v146 offset:61440
	s_cmp_gt_u32 s6, 1
	s_cselect_b32 s74, 0, 0xffff0000
	v_add_u32_e32 v146, s74, v222
	ds_read_b64 v[6:7], v146 offset:49152
	ds_read_b64 v[10:11], v146 offset:53248
	ds_read_b64 v[14:15], v146 offset:57344
	ds_read_b64 v[18:19], v146 offset:61440
	s_nop 1
	v_fma_f32 v64, v64, s79, v205
	v_fma_f32 v65, v65, s79, v206
	v_fma_f32 v66, v66, s79, v207
	v_fma_f32 v67, v67, s79, v208
	v_fma_f32 v68, v68, s79, v209
	v_fma_f32 v69, v69, s79, v210
	v_fma_f32 v70, v70, s79, v211
	v_fma_f32 v71, v71, s79, v212
	v_fma_f32 v72, v72, s79, v213
	v_fma_f32 v73, v73, s79, v214
	v_fma_f32 v74, v74, s79, v215
	v_fma_f32 v75, v75, s79, v216
	v_fma_f32 v76, v76, s79, v217
	v_fma_f32 v77, v77, s79, v218
	v_fma_f32 v78, v78, s79, v219
	v_fma_f32 v79, v79, s79, v220
	s_cmp_gt_u32 s6, 2
	s_cselect_b32 s74, 0, 0xffff0000
	v_add_u32_e32 v146, s74, v223
	ds_read_b64 v[20:21], v146 offset:49152
	ds_read_b64 v[24:25], v146 offset:53248
	ds_read_b64 v[28:29], v146 offset:57344
	ds_read_b64 v[32:33], v146 offset:61440
	s_cmp_gt_u32 s6, 3
	s_cselect_b32 s74, 0, 0xffff0000
	v_add_u32_e32 v146, s74, v224
	ds_read_b64 v[22:23], v146 offset:49152
	ds_read_b64 v[26:27], v146 offset:53248
	ds_read_b64 v[30:31], v146 offset:57344
	ds_read_b64 v[34:35], v146 offset:61440
	s_cmp_lg_u32 s4, 0
	s_cbranch_scc1 .Lat738_i0_nomask
	s_cmp_le_u32 s6, 0
	s_cbranch_scc1 .Lat738_i0_nomask
	v_mov_b32_e32 v44, v244
	v_mov_b32_e32 v45, v244
	v_mov_b32_e32 v46, v244
	v_mov_b32_e32 v47, v244
	s_cmp_le_u32 s6, 1
	s_cbranch_scc1 .Lat738_i0_nomask
	v_mov_b32_e32 v48, v244
	v_mov_b32_e32 v49, v244
	v_mov_b32_e32 v50, v244
	v_mov_b32_e32 v51, v244
	s_cmp_le_u32 s6, 2
	s_cbranch_scc1 .Lat738_i0_nomask
	v_mov_b32_e32 v52, v244
	v_mov_b32_e32 v53, v244
	v_mov_b32_e32 v54, v244
	v_mov_b32_e32 v55, v244
	s_cmp_le_u32 s6, 3
	s_cbranch_scc1 .Lat738_i0_nomask
	v_mov_b32_e32 v56, v244
	v_mov_b32_e32 v57, v244
	v_mov_b32_e32 v58, v244
	v_mov_b32_e32 v59, v244
	s_cmp_le_u32 s6, 4
	s_cbranch_scc1 .Lat738_i0_nomask
	v_mov_b32_e32 v60, v244
	v_mov_b32_e32 v61, v244
	v_mov_b32_e32 v62, v244
	v_mov_b32_e32 v63, v244
	s_cmp_le_u32 s6, 5
	s_cbranch_scc1 .Lat738_i0_nomask
	v_mov_b32_e32 v64, v244
	v_mov_b32_e32 v65, v244
	v_mov_b32_e32 v66, v244
	v_mov_b32_e32 v67, v244
	s_cmp_le_u32 s6, 6
	s_cbranch_scc1 .Lat738_i0_nomask
	v_mov_b32_e32 v68, v244
	v_mov_b32_e32 v69, v244
	v_mov_b32_e32 v70, v244
	v_mov_b32_e32 v71, v244
	s_cmp_le_u32 s6, 7
	s_cbranch_scc1 .Lat738_i0_nomask
	v_mov_b32_e32 v72, v244
	v_mov_b32_e32 v73, v244
	v_mov_b32_e32 v74, v244
	v_mov_b32_e32 v75, v244
.Lat738_i0_nomask:
	v_max3_f32 v245, v44, v45, v46
	v_max3_f32 v245, v245, v47, v48
	v_max3_f32 v245, v245, v49, v50
	v_max3_f32 v245, v245, v51, v52
	v_max3_f32 v245, v245, v53, v54
	v_max3_f32 v245, v245, v55, v56
	v_max3_f32 v245, v245, v57, v58
	v_max3_f32 v245, v245, v59, v60
	v_max3_f32 v245, v245, v61, v62
	v_max3_f32 v245, v245, v63, v64
	v_max3_f32 v245, v245, v65, v66
	v_max3_f32 v245, v245, v67, v68
	v_max3_f32 v245, v245, v69, v70
	v_max3_f32 v245, v245, v71, v72
	v_max3_f32 v245, v245, v73, v74
	v_max3_f32 v245, v245, v75, v76
	v_max3_f32 v245, v245, v77, v78
	v_max_f32_e32 v245, v245, v79
	ds_bpermute_b32 v148, v239, v245
	s_waitcnt lgkmcnt(0)
	v_max_f32_e32 v245, v245, v148
	ds_bpermute_b32 v148, v240, v245
	s_waitcnt lgkmcnt(0)
	v_max_f32_e32 v245, v245, v148
	v_sub_f32_e32 v44, v44, v245
	v_sub_f32_e32 v45, v45, v245
	v_sub_f32_e32 v46, v46, v245
	v_sub_f32_e32 v47, v47, v245
	v_exp_f32_e32 v44, v44
	v_exp_f32_e32 v45, v45
	v_exp_f32_e32 v46, v46
	v_exp_f32_e32 v47, v47
	v_sub_f32_e32 v48, v48, v245
	v_sub_f32_e32 v49, v49, v245
	v_sub_f32_e32 v50, v50, v245
	v_sub_f32_e32 v51, v51, v245
	v_exp_f32_e32 v48, v48
	v_exp_f32_e32 v49, v49
	v_exp_f32_e32 v50, v50
	v_exp_f32_e32 v51, v51
	v_mov_b32_e32 v149, v44
	v_mov_b32_e32 v150, v45
	v_mov_b32_e32 v151, v46
	v_mov_b32_e32 v152, v47
	v_cvt_pk_bf16_f32 v44, v44, v45
	v_cvt_pk_bf16_f32 v45, v46, v47
	v_sub_f32_e32 v52, v52, v245
	v_sub_f32_e32 v53, v53, v245
	v_sub_f32_e32 v54, v54, v245
	v_sub_f32_e32 v55, v55, v245
	v_exp_f32_e32 v52, v52
	v_exp_f32_e32 v53, v53
	v_exp_f32_e32 v54, v54
	v_exp_f32_e32 v55, v55
	v_add_f32_e32 v149, v149, v48
	v_add_f32_e32 v150, v150, v49
	v_add_f32_e32 v151, v151, v50
	v_add_f32_e32 v152, v152, v51
	v_cvt_pk_bf16_f32 v46, v48, v49
	v_cvt_pk_bf16_f32 v47, v50, v51
	v_sub_f32_e32 v56, v56, v245
	v_sub_f32_e32 v57, v57, v245
	v_sub_f32_e32 v58, v58, v245
	v_sub_f32_e32 v59, v59, v245
	v_exp_f32_e32 v56, v56
	v_exp_f32_e32 v57, v57
	v_exp_f32_e32 v58, v58
	v_exp_f32_e32 v59, v59
	v_add_f32_e32 v149, v149, v52
	v_add_f32_e32 v150, v150, v53
	v_add_f32_e32 v151, v151, v54
	v_add_f32_e32 v152, v152, v55
	v_cvt_pk_bf16_f32 v52, v52, v53
	v_cvt_pk_bf16_f32 v53, v54, v55
	v_sub_f32_e32 v60, v60, v245
	v_sub_f32_e32 v61, v61, v245
	v_sub_f32_e32 v62, v62, v245
	v_sub_f32_e32 v63, v63, v245
	v_exp_f32_e32 v60, v60
	v_exp_f32_e32 v61, v61
	v_exp_f32_e32 v62, v62
	v_exp_f32_e32 v63, v63
	v_add_f32_e32 v149, v149, v56
	v_add_f32_e32 v150, v150, v57
	v_add_f32_e32 v151, v151, v58
	v_add_f32_e32 v152, v152, v59
	v_cvt_pk_bf16_f32 v54, v56, v57
	v_cvt_pk_bf16_f32 v55, v58, v59
	v_sub_f32_e32 v64, v64, v245
	v_sub_f32_e32 v65, v65, v245
	v_sub_f32_e32 v66, v66, v245
	v_sub_f32_e32 v67, v67, v245
	v_exp_f32_e32 v64, v64
	v_exp_f32_e32 v65, v65
	v_exp_f32_e32 v66, v66
	v_exp_f32_e32 v67, v67
	v_add_f32_e32 v149, v149, v60
	v_add_f32_e32 v150, v150, v61
	v_add_f32_e32 v151, v151, v62
	v_add_f32_e32 v152, v152, v63
	v_cvt_pk_bf16_f32 v60, v60, v61
	v_cvt_pk_bf16_f32 v61, v62, v63
	v_sub_f32_e32 v68, v68, v245
	v_sub_f32_e32 v69, v69, v245
	v_sub_f32_e32 v70, v70, v245
	v_sub_f32_e32 v71, v71, v245
	v_exp_f32_e32 v68, v68
	v_exp_f32_e32 v69, v69
	v_exp_f32_e32 v70, v70
	v_exp_f32_e32 v71, v71
	v_add_f32_e32 v149, v149, v64
	v_add_f32_e32 v150, v150, v65
	v_add_f32_e32 v151, v151, v66
	v_add_f32_e32 v152, v152, v67
	v_cvt_pk_bf16_f32 v62, v64, v65
	v_cvt_pk_bf16_f32 v63, v66, v67
	v_sub_f32_e32 v72, v72, v245
	v_sub_f32_e32 v73, v73, v245
	v_sub_f32_e32 v74, v74, v245
	v_sub_f32_e32 v75, v75, v245
	v_exp_f32_e32 v72, v72
	v_exp_f32_e32 v73, v73
	v_exp_f32_e32 v74, v74
	v_exp_f32_e32 v75, v75
	v_add_f32_e32 v149, v149, v68
	v_add_f32_e32 v150, v150, v69
	v_add_f32_e32 v151, v151, v70
	v_add_f32_e32 v152, v152, v71
	v_cvt_pk_bf16_f32 v68, v68, v69
	v_cvt_pk_bf16_f32 v69, v70, v71
	v_sub_f32_e32 v76, v76, v245
	v_sub_f32_e32 v77, v77, v245
	v_sub_f32_e32 v78, v78, v245
	v_sub_f32_e32 v79, v79, v245
	v_exp_f32_e32 v76, v76
	v_exp_f32_e32 v77, v77
	v_exp_f32_e32 v78, v78
	v_exp_f32_e32 v79, v79
	v_add_f32_e32 v149, v149, v72
	v_add_f32_e32 v150, v150, v73
	v_add_f32_e32 v151, v151, v74
	v_add_f32_e32 v152, v152, v75
	v_cvt_pk_bf16_f32 v70, v72, v73
	v_cvt_pk_bf16_f32 v71, v74, v75
	s_nop 0
	v_add_f32_e32 v149, v149, v76
	v_add_f32_e32 v150, v150, v77
	v_add_f32_e32 v151, v151, v78
	v_add_f32_e32 v152, v152, v79
	v_cvt_pk_bf16_f32 v76, v76, v77
	v_cvt_pk_bf16_f32 v77, v78, v79
	v_mov_b32_e32 v78, 0
	v_mov_b32_e32 v79, 0
	v_add_f32_e32 v149, v149, v150
	v_add_f32_e32 v151, v151, v152
	v_add_f32_e32 v246, v149, v151
	s_waitcnt lgkmcnt(0)
	v_mfma_f32_16x16x32_bf16 v[80:83], v[4:7], v[44:47], 0
	v_mfma_f32_16x16x32_bf16 v[84:87], v[8:11], v[44:47], 0
	v_mfma_f32_16x16x32_bf16 v[88:91], v[12:15], v[44:47], 0
	v_mfma_f32_16x16x32_bf16 v[92:95], v[16:19], v[44:47], 0
	s_cmp_gt_u32 s6, 4
	s_cselect_b32 s74, 0, 0xffff0000
	v_add_u32_e32 v146, s74, v225
	ds_read_b64 v[4:5], v146 offset:49152
	ds_read_b64 v[8:9], v146 offset:53248
	ds_read_b64 v[12:13], v146 offset:57344
	ds_read_b64 v[16:17], v146 offset:61440
	s_cmp_gt_u32 s6, 5
	s_cselect_b32 s74, 0, 0xffff0000
	v_add_u32_e32 v146, s74, v226
	ds_read_b64 v[6:7], v146 offset:49152
	ds_read_b64 v[10:11], v146 offset:53248
	ds_read_b64 v[14:15], v146 offset:57344
	ds_read_b64 v[18:19], v146 offset:61440
	v_mfma_f32_16x16x32_bf16 v[80:83], v[20:23], v[52:55], v[80:83]
	v_mfma_f32_16x16x32_bf16 v[84:87], v[24:27], v[52:55], v[84:87]
	v_mfma_f32_16x16x32_bf16 v[88:91], v[28:31], v[52:55], v[88:91]
	v_mfma_f32_16x16x32_bf16 v[92:95], v[32:35], v[52:55], v[92:95]
	s_cmp_gt_u32 s6, 6
	s_cselect_b32 s74, 0, 0xffff0000
	v_add_u32_e32 v146, s74, v227
	ds_read_b64 v[20:21], v146 offset:49152
	ds_read_b64 v[24:25], v146 offset:53248
	ds_read_b64 v[28:29], v146 offset:57344
	ds_read_b64 v[32:33], v146 offset:61440
	s_cmp_gt_u32 s6, 7
	s_cselect_b32 s74, 0, 0xffff0000
	v_add_u32_e32 v146, s74, v228
	ds_read_b64 v[22:23], v146 offset:49152
	ds_read_b64 v[26:27], v146 offset:53248
	ds_read_b64 v[30:31], v146 offset:57344
	ds_read_b64 v[34:35], v146 offset:61440
	ds_bpermute_b32 v148, v239, v246
	s_waitcnt lgkmcnt(9)
	v_mfma_f32_16x16x32_bf16 v[80:83], v[4:7], v[60:63], v[80:83]
	v_mfma_f32_16x16x32_bf16 v[84:87], v[8:11], v[60:63], v[84:87]
	v_mfma_f32_16x16x32_bf16 v[88:91], v[12:15], v[60:63], v[88:91]
	v_mfma_f32_16x16x32_bf16 v[92:95], v[16:19], v[60:63], v[92:95]
	s_cmp_gt_u32 s6, 8
	s_cselect_b32 s74, 0, 0xffff0000
	v_add_u32_e32 v146, s74, v229
	ds_read_b64 v[4:5], v146 offset:49152
	ds_read_b64 v[8:9], v146 offset:53248
	ds_read_b64 v[12:13], v146 offset:57344
	ds_read_b64 v[16:17], v146 offset:61440
	v_mov_b32_e32 v6, 0
	v_mov_b32_e32 v7, 0
	v_mov_b32_e32 v10, 0
	v_mov_b32_e32 v11, 0
	v_mov_b32_e32 v14, 0
	v_mov_b32_e32 v15, 0
	v_mov_b32_e32 v18, 0
	v_mov_b32_e32 v19, 0
	s_waitcnt lgkmcnt(5)
	v_mfma_f32_16x16x32_bf16 v[80:83], v[20:23], v[68:71], v[80:83]
	v_mfma_f32_16x16x32_bf16 v[84:87], v[24:27], v[68:71], v[84:87]
	v_mfma_f32_16x16x32_bf16 v[88:91], v[28:31], v[68:71], v[88:91]
	v_mfma_f32_16x16x32_bf16 v[92:95], v[32:35], v[68:71], v[92:95]
	s_waitcnt lgkmcnt(0)
	v_add_f32_e32 v246, v246, v148
	s_nop 0
	v_mfma_f32_16x16x32_bf16 v[80:83], v[4:7], v[76:79], v[80:83]
	v_mfma_f32_16x16x32_bf16 v[84:87], v[8:11], v[76:79], v[84:87]
	v_mfma_f32_16x16x32_bf16 v[88:91], v[12:15], v[76:79], v[88:91]
	v_mfma_f32_16x16x32_bf16 v[92:95], v[16:19], v[76:79], v[92:95]
	ds_bpermute_b32 v148, v240, v246
	s_waitcnt lgkmcnt(0)
	v_add_f32_e32 v246, v246, v148
	v_rcp_f32_e32 v149, v246
	v_log_f32_e32 v150, v246
	s_nop 0
	v_add_f32_e32 v151, v245, v150
	v_mul_f32_e32 v151, 0x3f317218, v151
	v_mov_b32_e32 v140, v151
	v_mul_f32_e32 v80, v80, v149
	v_mul_f32_e32 v81, v81, v149
	v_mul_f32_e32 v82, v82, v149
	v_mul_f32_e32 v83, v83, v149
	v_mul_f32_e32 v84, v84, v149
	v_mul_f32_e32 v85, v85, v149
	v_mul_f32_e32 v86, v86, v149
	v_mul_f32_e32 v87, v87, v149
	v_mul_f32_e32 v88, v88, v149
	v_mul_f32_e32 v89, v89, v149
	v_mul_f32_e32 v90, v90, v149
	v_mul_f32_e32 v91, v91, v149
	v_mul_f32_e32 v92, v92, v149
	v_mul_f32_e32 v93, v93, v149
	v_mul_f32_e32 v94, v94, v149
	v_mul_f32_e32 v95, v95, v149
	v_cvt_pk_bf16_f32 v132, v80, v81
	v_cvt_pk_bf16_f32 v133, v82, v83
	v_cvt_pk_bf16_f32 v134, v84, v85
	v_cvt_pk_bf16_f32 v135, v86, v87
	v_cvt_pk_bf16_f32 v136, v88, v89
	v_cvt_pk_bf16_f32 v137, v90, v91
	v_cvt_pk_bf16_f32 v138, v92, v93
	v_cvt_pk_bf16_f32 v139, v94, v95
	s_mov_b64 s[26:27], s[86:87]
	s_mov_b64 s[28:29], s[88:89]
	s_mov_b64 s[86:87], s[12:13]
	s_mov_b64 s[88:89], s[14:15]
	s_mov_b32 s4, s83
	s_mov_b32 s5, s84
	s_waitcnt vmcnt(0)
	s_barrier
	ds_read_b128 v[4:7], v230 offset:0
	ds_read_b128 v[8:11], v231 offset:0
	ds_read_b128 v[12:15], v230 offset:2048
	ds_read_b128 v[16:19], v231 offset:2048
	ds_read_b128 v[20:23], v230 offset:4096
	ds_read_b128 v[24:27], v231 offset:4096
	ds_read_b128 v[28:31], v230 offset:6144
	ds_read_b128 v[32:35], v231 offset:6144
	ds_read_b128 v[36:39], v230 offset:8192
	ds_read_b128 v[40:43], v231 offset:8192
	global_store_dwordx2 v237, v[132:133], s[26:27]
	global_store_dwordx2 v237, v[134:135], s[26:27] offset:32
	global_store_dwordx2 v237, v[136:137], s[26:27] offset:64
	global_store_dwordx2 v237, v[138:139], s[26:27] offset:96
	s_mov_b64 s[90:91], exec
	s_mov_b64 exec, 0xffff
	global_store_dword v238, v140, s[28:29]
	s_mov_b64 exec, s[90:91]
	s_add_u32 s83, s4, 1
	s_mov_b32 s84, s5
	s_mul_i32 s74, s84, 4096
	s_lshl_b32 s75, s83, 7
	s_add_u32 s74, s74, s75
	s_lshl_b32 s75, s74, 7
	s_add_u32 s16, s60, s75
	s_addc_u32 s17, s61, 0
	s_lshl_b32 s75, s74, 1
	s_add_u32 s24, s64, s75
	s_addc_u32 s25, s65, 0
	s_add_u32 m0, s70, 0x8000
	s_nop 0
	global_load_lds_dwordx4 v232, s[16:17] nt
	s_add_u32 m0, s70, 0xa000
	s_nop 0
	global_load_lds_dwordx4 v233, s[16:17] nt
	s_add_u32 m0, s70, 0x18000
	s_nop 0
	global_load_lds_dwordx4 v234, s[24:25] nt
	s_add_u32 m0, s70, 0x1a000
	s_nop 0
	global_load_lds_dwordx4 v235, s[24:25] nt
	s_lshl_b32 s74, s83, 7
	s_add_u32 s74, s74, s84
	s_lshl_b32 s75, s74, 7
	s_add_u32 s10, s30, s75
	s_addc_u32 s11, s31, 0
	s_add_u32 s12, s34, s75
	s_addc_u32 s13, s35, 0
	s_lshl_b32 s75, s74, 2
	s_add_u32 s14, s58, s75
	s_addc_u32 s15, s59, 0
	global_load_dwordx4 v[96:99], v236, s[10:11]
	global_load_dwordx4 v[100:103], v236, s[10:11] offset:64
	s_waitcnt lgkmcnt(0)
	v_mfma_f32_16x16x32_bf16 v[44:47], v[4:7], v[104:107], 0
	v_mfma_f32_16x16x32_bf16 v[48:51], v[12:15], v[104:107], 0
	v_mfma_f32_16x16x32_bf16 v[52:55], v[20:23], v[104:107], 0
	v_mfma_f32_16x16x32_bf16 v[56:59], v[28:31], v[104:107], 0
	v_mfma_f32_16x16x32_bf16 v[60:63], v[36:39], v[104:107], 0
	v_mfma_f32_16x16x32_bf16 v[44:47], v[8:11], v[108:111], v[44:47]
	v_mfma_f32_16x16x32_bf16 v[48:51], v[16:19], v[108:111], v[48:51]
	v_mfma_f32_16x16x32_bf16 v[52:55], v[24:27], v[108:111], v[52:55]
	v_mfma_f32_16x16x32_bf16 v[56:59], v[32:35], v[108:111], v[56:59]
	v_mfma_f32_16x16x32_bf16 v[60:63], v[40:43], v[108:111], v[60:63]
	ds_read_b128 v[4:7], v230 offset:10240
	ds_read_b128 v[8:11], v231 offset:10240
	ds_read_b128 v[12:15], v230 offset:12288
	ds_read_b128 v[16:19], v231 offset:12288
	ds_read_b128 v[20:23], v230 offset:14336
	ds_read_b128 v[24:27], v231 offset:14336
	ds_read_b128 v[28:31], v230 offset:16384
	ds_read_b128 v[32:35], v231 offset:16384
	s_nop 1
	v_fma_f32 v44, v44, s79, v185
	v_fma_f32 v45, v45, s79, v186
	v_fma_f32 v46, v46, s79, v187
	v_fma_f32 v47, v47, s79, v188
	v_fma_f32 v48, v48, s79, v189
	v_fma_f32 v49, v49, s79, v190
	v_fma_f32 v50, v50, s79, v191
	v_fma_f32 v51, v51, s79, v192
	v_fma_f32 v52, v52, s79, v193
	v_fma_f32 v53, v53, s79, v194
	v_fma_f32 v54, v54, s79, v195
	v_fma_f32 v55, v55, s79, v196
	v_fma_f32 v56, v56, s79, v197
	v_fma_f32 v57, v57, s79, v198
	v_fma_f32 v58, v58, s79, v199
	v_fma_f32 v59, v59, s79, v200
	v_fma_f32 v60, v60, s79, v201
	v_fma_f32 v61, v61, s79, v202
	v_fma_f32 v62, v62, s79, v203
	v_fma_f32 v63, v63, s79, v204
	s_waitcnt lgkmcnt(0)
	v_mfma_f32_16x16x32_bf16 v[64:67], v[4:7], v[104:107], 0
	v_mfma_f32_16x16x32_bf16 v[68:71], v[12:15], v[104:107], 0
	v_mfma_f32_16x16x32_bf16 v[72:75], v[20:23], v[104:107], 0
	v_mfma_f32_16x16x32_bf16 v[76:79], v[28:31], v[104:107], 0
	v_mfma_f32_16x16x32_bf16 v[64:67], v[8:11], v[108:111], v[64:67]
	v_mfma_f32_16x16x32_bf16 v[68:71], v[16:19], v[108:111], v[68:71]
	v_mfma_f32_16x16x32_bf16 v[72:75], v[24:27], v[108:111], v[72:75]
	v_mfma_f32_16x16x32_bf16 v[76:79], v[32:35], v[108:111], v[76:79]
	ds_read_b64 v[4:5], v221 offset:0
	ds_read_b64 v[8:9], v221 offset:4096
	ds_read_b64 v[12:13], v221 offset:8192
	ds_read_b64 v[16:17], v221 offset:12288
	ds_read_b64 v[6:7], v222 offset:0
	ds_read_b64 v[10:11], v222 offset:4096
	ds_read_b64 v[14:15], v222 offset:8192
	ds_read_b64 v[18:19], v222 offset:12288
	s_nop 1
	v_fma_f32 v64, v64, s79, v205
	v_fma_f32 v65, v65, s79, v206
	v_fma_f32 v66, v66, s79, v207
	v_fma_f32 v67, v67, s79, v208
	v_fma_f32 v68, v68, s79, v209
	v_fma_f32 v69, v69, s79, v210
	v_fma_f32 v70, v70, s79, v211
	v_fma_f32 v71, v71, s79, v212
	v_fma_f32 v72, v72, s79, v213
	v_fma_f32 v73, v73, s79, v214
	v_fma_f32 v74, v74, s79, v215
	v_fma_f32 v75, v75, s79, v216
	v_fma_f32 v76, v76, s79, v217
	v_fma_f32 v77, v77, s79, v218
	v_fma_f32 v78, v78, s79, v219
	v_fma_f32 v79, v79, s79, v220
	ds_read_b64 v[20:21], v223 offset:0
	ds_read_b64 v[24:25], v223 offset:4096
	ds_read_b64 v[28:29], v223 offset:8192
	ds_read_b64 v[32:33], v223 offset:12288
	ds_read_b64 v[22:23], v224 offset:0
	ds_read_b64 v[26:27], v224 offset:4096
	ds_read_b64 v[30:31], v224 offset:8192
	ds_read_b64 v[34:35], v224 offset:12288
	s_cmp_lg_u32 s4, 0
	s_cbranch_scc1 .Lat738_i1_nomask
	s_cmp_le_u32 s6, 0
	s_cbranch_scc1 .Lat738_i1_nomask
	v_mov_b32_e32 v44, v244
	v_mov_b32_e32 v45, v244
	v_mov_b32_e32 v46, v244
	v_mov_b32_e32 v47, v244
	s_cmp_le_u32 s6, 1
	s_cbranch_scc1 .Lat738_i1_nomask
	v_mov_b32_e32 v48, v244
	v_mov_b32_e32 v49, v244
	v_mov_b32_e32 v50, v244
	v_mov_b32_e32 v51, v244
	s_cmp_le_u32 s6, 2
	s_cbranch_scc1 .Lat738_i1_nomask
	v_mov_b32_e32 v52, v244
	v_mov_b32_e32 v53, v244
	v_mov_b32_e32 v54, v244
	v_mov_b32_e32 v55, v244
	s_cmp_le_u32 s6, 3
	s_cbranch_scc1 .Lat738_i1_nomask
	v_mov_b32_e32 v56, v244
	v_mov_b32_e32 v57, v244
	v_mov_b32_e32 v58, v244
	v_mov_b32_e32 v59, v244
	s_cmp_le_u32 s6, 4
	s_cbranch_scc1 .Lat738_i1_nomask
	v_mov_b32_e32 v60, v244
	v_mov_b32_e32 v61, v244
	v_mov_b32_e32 v62, v244
	v_mov_b32_e32 v63, v244
	s_cmp_le_u32 s6, 5
	s_cbranch_scc1 .Lat738_i1_nomask
	v_mov_b32_e32 v64, v244
	v_mov_b32_e32 v65, v244
	v_mov_b32_e32 v66, v244
	v_mov_b32_e32 v67, v244
	s_cmp_le_u32 s6, 6
	s_cbranch_scc1 .Lat738_i1_nomask
	v_mov_b32_e32 v68, v244
	v_mov_b32_e32 v69, v244
	v_mov_b32_e32 v70, v244
	v_mov_b32_e32 v71, v244
	s_cmp_le_u32 s6, 7
	s_cbranch_scc1 .Lat738_i1_nomask
	v_mov_b32_e32 v72, v244
	v_mov_b32_e32 v73, v244
	v_mov_b32_e32 v74, v244
	v_mov_b32_e32 v75, v244
.Lat738_i1_nomask:
	v_max3_f32 v245, v44, v45, v46
	v_max3_f32 v245, v245, v47, v48
	v_max3_f32 v245, v245, v49, v50
	v_max3_f32 v245, v245, v51, v52
	v_max3_f32 v245, v245, v53, v54
	v_max3_f32 v245, v245, v55, v56
	v_max3_f32 v245, v245, v57, v58
	v_max3_f32 v245, v245, v59, v60
	v_max3_f32 v245, v245, v61, v62
	v_max3_f32 v245, v245, v63, v64
	v_max3_f32 v245, v245, v65, v66
	v_max3_f32 v245, v245, v67, v68
	v_max3_f32 v245, v245, v69, v70
	v_max3_f32 v245, v245, v71, v72
	v_max3_f32 v245, v245, v73, v74
	v_max3_f32 v245, v245, v75, v76
	v_max3_f32 v245, v245, v77, v78
	v_max_f32_e32 v245, v245, v79
	ds_bpermute_b32 v148, v239, v245
	s_waitcnt lgkmcnt(0)
	v_max_f32_e32 v245, v245, v148
	ds_bpermute_b32 v148, v240, v245
	s_waitcnt lgkmcnt(0)
	v_max_f32_e32 v245, v245, v148
	v_sub_f32_e32 v44, v44, v245
	v_sub_f32_e32 v45, v45, v245
	v_sub_f32_e32 v46, v46, v245
	v_sub_f32_e32 v47, v47, v245
	v_exp_f32_e32 v44, v44
	v_exp_f32_e32 v45, v45
	v_exp_f32_e32 v46, v46
	v_exp_f32_e32 v47, v47
	v_sub_f32_e32 v48, v48, v245
	v_sub_f32_e32 v49, v49, v245
	v_sub_f32_e32 v50, v50, v245
	v_sub_f32_e32 v51, v51, v245
	v_exp_f32_e32 v48, v48
	v_exp_f32_e32 v49, v49
	v_exp_f32_e32 v50, v50
	v_exp_f32_e32 v51, v51
	v_mov_b32_e32 v149, v44
	v_mov_b32_e32 v150, v45
	v_mov_b32_e32 v151, v46
	v_mov_b32_e32 v152, v47
	v_cvt_pk_bf16_f32 v44, v44, v45
	v_cvt_pk_bf16_f32 v45, v46, v47
	v_sub_f32_e32 v52, v52, v245
	v_sub_f32_e32 v53, v53, v245
	v_sub_f32_e32 v54, v54, v245
	v_sub_f32_e32 v55, v55, v245
	v_exp_f32_e32 v52, v52
	v_exp_f32_e32 v53, v53
	v_exp_f32_e32 v54, v54
	v_exp_f32_e32 v55, v55
	v_add_f32_e32 v149, v149, v48
	v_add_f32_e32 v150, v150, v49
	v_add_f32_e32 v151, v151, v50
	v_add_f32_e32 v152, v152, v51
	v_cvt_pk_bf16_f32 v46, v48, v49
	v_cvt_pk_bf16_f32 v47, v50, v51
	v_sub_f32_e32 v56, v56, v245
	v_sub_f32_e32 v57, v57, v245
	v_sub_f32_e32 v58, v58, v245
	v_sub_f32_e32 v59, v59, v245
	v_exp_f32_e32 v56, v56
	v_exp_f32_e32 v57, v57
	v_exp_f32_e32 v58, v58
	v_exp_f32_e32 v59, v59
	v_add_f32_e32 v149, v149, v52
	v_add_f32_e32 v150, v150, v53
	v_add_f32_e32 v151, v151, v54
	v_add_f32_e32 v152, v152, v55
	v_cvt_pk_bf16_f32 v52, v52, v53
	v_cvt_pk_bf16_f32 v53, v54, v55
	v_sub_f32_e32 v60, v60, v245
	v_sub_f32_e32 v61, v61, v245
	v_sub_f32_e32 v62, v62, v245
	v_sub_f32_e32 v63, v63, v245
	v_exp_f32_e32 v60, v60
	v_exp_f32_e32 v61, v61
	v_exp_f32_e32 v62, v62
	v_exp_f32_e32 v63, v63
	v_add_f32_e32 v149, v149, v56
	v_add_f32_e32 v150, v150, v57
	v_add_f32_e32 v151, v151, v58
	v_add_f32_e32 v152, v152, v59
	v_cvt_pk_bf16_f32 v54, v56, v57
	v_cvt_pk_bf16_f32 v55, v58, v59
	v_sub_f32_e32 v64, v64, v245
	v_sub_f32_e32 v65, v65, v245
	v_sub_f32_e32 v66, v66, v245
	v_sub_f32_e32 v67, v67, v245
	v_exp_f32_e32 v64, v64
	v_exp_f32_e32 v65, v65
	v_exp_f32_e32 v66, v66
	v_exp_f32_e32 v67, v67
	v_add_f32_e32 v149, v149, v60
	v_add_f32_e32 v150, v150, v61
	v_add_f32_e32 v151, v151, v62
	v_add_f32_e32 v152, v152, v63
	v_cvt_pk_bf16_f32 v60, v60, v61
	v_cvt_pk_bf16_f32 v61, v62, v63
	v_sub_f32_e32 v68, v68, v245
	v_sub_f32_e32 v69, v69, v245
	v_sub_f32_e32 v70, v70, v245
	v_sub_f32_e32 v71, v71, v245
	v_exp_f32_e32 v68, v68
	v_exp_f32_e32 v69, v69
	v_exp_f32_e32 v70, v70
	v_exp_f32_e32 v71, v71
	v_add_f32_e32 v149, v149, v64
	v_add_f32_e32 v150, v150, v65
	v_add_f32_e32 v151, v151, v66
	v_add_f32_e32 v152, v152, v67
	v_cvt_pk_bf16_f32 v62, v64, v65
	v_cvt_pk_bf16_f32 v63, v66, v67
	v_sub_f32_e32 v72, v72, v245
	v_sub_f32_e32 v73, v73, v245
	v_sub_f32_e32 v74, v74, v245
	v_sub_f32_e32 v75, v75, v245
	v_exp_f32_e32 v72, v72
	v_exp_f32_e32 v73, v73
	v_exp_f32_e32 v74, v74
	v_exp_f32_e32 v75, v75
	v_add_f32_e32 v149, v149, v68
	v_add_f32_e32 v150, v150, v69
	v_add_f32_e32 v151, v151, v70
	v_add_f32_e32 v152, v152, v71
	v_cvt_pk_bf16_f32 v68, v68, v69
	v_cvt_pk_bf16_f32 v69, v70, v71
	v_sub_f32_e32 v76, v76, v245
	v_sub_f32_e32 v77, v77, v245
	v_sub_f32_e32 v78, v78, v245
	v_sub_f32_e32 v79, v79, v245
	v_exp_f32_e32 v76, v76
	v_exp_f32_e32 v77, v77
	v_exp_f32_e32 v78, v78
	v_exp_f32_e32 v79, v79
	v_add_f32_e32 v149, v149, v72
	v_add_f32_e32 v150, v150, v73
	v_add_f32_e32 v151, v151, v74
	v_add_f32_e32 v152, v152, v75
	v_cvt_pk_bf16_f32 v70, v72, v73
	v_cvt_pk_bf16_f32 v71, v74, v75
	s_nop 0
	v_add_f32_e32 v149, v149, v76
	v_add_f32_e32 v150, v150, v77
	v_add_f32_e32 v151, v151, v78
	v_add_f32_e32 v152, v152, v79
	v_cvt_pk_bf16_f32 v76, v76, v77
	v_cvt_pk_bf16_f32 v77, v78, v79
	v_mov_b32_e32 v78, 0
	v_mov_b32_e32 v79, 0
	v_add_f32_e32 v149, v149, v150
	v_add_f32_e32 v151, v151, v152
	v_add_f32_e32 v246, v149, v151
	s_waitcnt lgkmcnt(0)
	v_mfma_f32_16x16x32_bf16 v[80:83], v[4:7], v[44:47], 0
	v_mfma_f32_16x16x32_bf16 v[84:87], v[8:11], v[44:47], 0
	v_mfma_f32_16x16x32_bf16 v[88:91], v[12:15], v[44:47], 0
	v_mfma_f32_16x16x32_bf16 v[92:95], v[16:19], v[44:47], 0
	ds_read_b64 v[4:5], v225 offset:0
	ds_read_b64 v[8:9], v225 offset:4096
	ds_read_b64 v[12:13], v225 offset:8192
	ds_read_b64 v[16:17], v225 offset:12288
	ds_read_b64 v[6:7], v226 offset:0
	ds_read_b64 v[10:11], v226 offset:4096
	ds_read_b64 v[14:15], v226 offset:8192
	ds_read_b64 v[18:19], v226 offset:12288
	v_mfma_f32_16x16x32_bf16 v[80:83], v[20:23], v[52:55], v[80:83]
	v_mfma_f32_16x16x32_bf16 v[84:87], v[24:27], v[52:55], v[84:87]
	v_mfma_f32_16x16x32_bf16 v[88:91], v[28:31], v[52:55], v[88:91]
	v_mfma_f32_16x16x32_bf16 v[92:95], v[32:35], v[52:55], v[92:95]
	ds_read_b64 v[20:21], v227 offset:0
	ds_read_b64 v[24:25], v227 offset:4096
	ds_read_b64 v[28:29], v227 offset:8192
	ds_read_b64 v[32:33], v227 offset:12288
	ds_read_b64 v[22:23], v228 offset:0
	ds_read_b64 v[26:27], v228 offset:4096
	ds_read_b64 v[30:31], v228 offset:8192
	ds_read_b64 v[34:35], v228 offset:12288
	ds_bpermute_b32 v148, v239, v246
	s_waitcnt lgkmcnt(9)
	v_mfma_f32_16x16x32_bf16 v[80:83], v[4:7], v[60:63], v[80:83]
	v_mfma_f32_16x16x32_bf16 v[84:87], v[8:11], v[60:63], v[84:87]
	v_mfma_f32_16x16x32_bf16 v[88:91], v[12:15], v[60:63], v[88:91]
	v_mfma_f32_16x16x32_bf16 v[92:95], v[16:19], v[60:63], v[92:95]
	ds_read_b64 v[4:5], v229 offset:0
	ds_read_b64 v[8:9], v229 offset:4096
	ds_read_b64 v[12:13], v229 offset:8192
	ds_read_b64 v[16:17], v229 offset:12288
	v_mov_b32_e32 v6, 0
	v_mov_b32_e32 v7, 0
	v_mov_b32_e32 v10, 0
	v_mov_b32_e32 v11, 0
	v_mov_b32_e32 v14, 0
	v_mov_b32_e32 v15, 0
	v_mov_b32_e32 v18, 0
	v_mov_b32_e32 v19, 0
	s_waitcnt lgkmcnt(5)
	v_mfma_f32_16x16x32_bf16 v[80:83], v[20:23], v[68:71], v[80:83]
	v_mfma_f32_16x16x32_bf16 v[84:87], v[24:27], v[68:71], v[84:87]
	v_mfma_f32_16x16x32_bf16 v[88:91], v[28:31], v[68:71], v[88:91]
	v_mfma_f32_16x16x32_bf16 v[92:95], v[32:35], v[68:71], v[92:95]
	s_waitcnt lgkmcnt(0)
	v_add_f32_e32 v246, v246, v148
	s_nop 0
	v_mfma_f32_16x16x32_bf16 v[80:83], v[4:7], v[76:79], v[80:83]
	v_mfma_f32_16x16x32_bf16 v[84:87], v[8:11], v[76:79], v[84:87]
	v_mfma_f32_16x16x32_bf16 v[88:91], v[12:15], v[76:79], v[88:91]
	v_mfma_f32_16x16x32_bf16 v[92:95], v[16:19], v[76:79], v[92:95]
	ds_bpermute_b32 v148, v240, v246
	s_waitcnt lgkmcnt(0)
	v_add_f32_e32 v246, v246, v148
	v_rcp_f32_e32 v149, v246
	v_log_f32_e32 v150, v246
	s_nop 0
	v_add_f32_e32 v151, v245, v150
	v_mul_f32_e32 v151, 0x3f317218, v151
	v_mov_b32_e32 v140, v151
	v_mul_f32_e32 v80, v80, v149
	v_mul_f32_e32 v81, v81, v149
	v_mul_f32_e32 v82, v82, v149
	v_mul_f32_e32 v83, v83, v149
	v_mul_f32_e32 v84, v84, v149
	v_mul_f32_e32 v85, v85, v149
	v_mul_f32_e32 v86, v86, v149
	v_mul_f32_e32 v87, v87, v149
	v_mul_f32_e32 v88, v88, v149
	v_mul_f32_e32 v89, v89, v149
	v_mul_f32_e32 v90, v90, v149
	v_mul_f32_e32 v91, v91, v149
	v_mul_f32_e32 v92, v92, v149
	v_mul_f32_e32 v93, v93, v149
	v_mul_f32_e32 v94, v94, v149
	v_mul_f32_e32 v95, v95, v149
	v_cvt_pk_bf16_f32 v132, v80, v81
	v_cvt_pk_bf16_f32 v133, v82, v83
	v_cvt_pk_bf16_f32 v134, v84, v85
	v_cvt_pk_bf16_f32 v135, v86, v87
	v_cvt_pk_bf16_f32 v136, v88, v89
	v_cvt_pk_bf16_f32 v137, v90, v91
	v_cvt_pk_bf16_f32 v138, v92, v93
	v_cvt_pk_bf16_f32 v139, v94, v95
	s_mov_b64 s[26:27], s[86:87]
	s_mov_b64 s[28:29], s[88:89]
	s_mov_b64 s[86:87], s[12:13]
	s_mov_b64 s[88:89], s[14:15]
	s_mov_b32 s4, s83
	s_mov_b32 s5, s84
	s_waitcnt vmcnt(0)
	s_barrier
	ds_read_b128 v[4:7], v230 offset:16384
	ds_read_b128 v[8:11], v231 offset:16384
	ds_read_b128 v[12:15], v230 offset:18432
	ds_read_b128 v[16:19], v231 offset:18432
	ds_read_b128 v[20:23], v230 offset:20480
	ds_read_b128 v[24:27], v231 offset:20480
	ds_read_b128 v[28:31], v230 offset:22528
	ds_read_b128 v[32:35], v231 offset:22528
	ds_read_b128 v[36:39], v230 offset:24576
	ds_read_b128 v[40:43], v231 offset:24576
	global_store_dwordx2 v237, v[132:133], s[26:27]
	global_store_dwordx2 v237, v[134:135], s[26:27] offset:32
	global_store_dwordx2 v237, v[136:137], s[26:27] offset:64
	global_store_dwordx2 v237, v[138:139], s[26:27] offset:96
	s_mov_b64 s[90:91], exec
	s_mov_b64 exec, 0xffff
	global_store_dword v238, v140, s[28:29]
	s_mov_b64 exec, s[90:91]
	s_add_u32 s83, s4, 1
	s_mov_b32 s84, s5
	s_mul_i32 s74, s84, 4096
	s_lshl_b32 s75, s83, 7
	s_add_u32 s74, s74, s75
	s_lshl_b32 s75, s74, 7
	s_add_u32 s16, s60, s75
	s_addc_u32 s17, s61, 0
	s_lshl_b32 s75, s74, 1
	s_add_u32 s24, s64, s75
	s_addc_u32 s25, s65, 0
	s_add_u32 m0, s70, 0xc000
	s_nop 0
	global_load_lds_dwordx4 v232, s[16:17] nt
	s_add_u32 m0, s70, 0xe000
	s_nop 0
	global_load_lds_dwordx4 v233, s[16:17] nt
	s_add_u32 m0, s70, 0x1c000
	s_nop 0
	global_load_lds_dwordx4 v234, s[24:25] nt
	s_add_u32 m0, s70, 0x1e000
	s_nop 0
	global_load_lds_dwordx4 v235, s[24:25] nt
	s_lshl_b32 s74, s83, 7
	s_add_u32 s74, s74, s84
	s_lshl_b32 s75, s74, 7
	s_add_u32 s10, s30, s75
	s_addc_u32 s11, s31, 0
	s_add_u32 s12, s34, s75
	s_addc_u32 s13, s35, 0
	s_lshl_b32 s75, s74, 2
	s_add_u32 s14, s58, s75
	s_addc_u32 s15, s59, 0
	global_load_dwordx4 v[104:107], v236, s[10:11]
	global_load_dwordx4 v[108:111], v236, s[10:11] offset:64
	s_waitcnt lgkmcnt(0)
	v_mfma_f32_16x16x32_bf16 v[44:47], v[4:7], v[96:99], 0
	v_mfma_f32_16x16x32_bf16 v[48:51], v[12:15], v[96:99], 0
	v_mfma_f32_16x16x32_bf16 v[52:55], v[20:23], v[96:99], 0
	v_mfma_f32_16x16x32_bf16 v[56:59], v[28:31], v[96:99], 0
	v_mfma_f32_16x16x32_bf16 v[60:63], v[36:39], v[96:99], 0
	v_mfma_f32_16x16x32_bf16 v[44:47], v[8:11], v[100:103], v[44:47]
	v_mfma_f32_16x16x32_bf16 v[48:51], v[16:19], v[100:103], v[48:51]
	v_mfma_f32_16x16x32_bf16 v[52:55], v[24:27], v[100:103], v[52:55]
	v_mfma_f32_16x16x32_bf16 v[56:59], v[32:35], v[100:103], v[56:59]
	v_mfma_f32_16x16x32_bf16 v[60:63], v[40:43], v[100:103], v[60:63]
	ds_read_b128 v[4:7], v230 offset:26624
	ds_read_b128 v[8:11], v231 offset:26624
	ds_read_b128 v[12:15], v230 offset:28672
	ds_read_b128 v[16:19], v231 offset:28672
	ds_read_b128 v[20:23], v230 offset:30720
	ds_read_b128 v[24:27], v231 offset:30720
	ds_read_b128 v[28:31], v230 offset:32768
	ds_read_b128 v[32:35], v231 offset:32768
	s_nop 1
	v_fma_f32 v44, v44, s79, v185
	v_fma_f32 v45, v45, s79, v186
	v_fma_f32 v46, v46, s79, v187
	v_fma_f32 v47, v47, s79, v188
	v_fma_f32 v48, v48, s79, v189
	v_fma_f32 v49, v49, s79, v190
	v_fma_f32 v50, v50, s79, v191
	v_fma_f32 v51, v51, s79, v192
	v_fma_f32 v52, v52, s79, v193
	v_fma_f32 v53, v53, s79, v194
	v_fma_f32 v54, v54, s79, v195
	v_fma_f32 v55, v55, s79, v196
	v_fma_f32 v56, v56, s79, v197
	v_fma_f32 v57, v57, s79, v198
	v_fma_f32 v58, v58, s79, v199
	v_fma_f32 v59, v59, s79, v200
	v_fma_f32 v60, v60, s79, v201
	v_fma_f32 v61, v61, s79, v202
	v_fma_f32 v62, v62, s79, v203
	v_fma_f32 v63, v63, s79, v204
	s_waitcnt lgkmcnt(0)
	v_mfma_f32_16x16x32_bf16 v[64:67], v[4:7], v[96:99], 0
	v_mfma_f32_16x16x32_bf16 v[68:71], v[12:15], v[96:99], 0
	v_mfma_f32_16x16x32_bf16 v[72:75], v[20:23], v[96:99], 0
	v_mfma_f32_16x16x32_bf16 v[76:79], v[28:31], v[96:99], 0
	v_mfma_f32_16x16x32_bf16 v[64:67], v[8:11], v[100:103], v[64:67]
	v_mfma_f32_16x16x32_bf16 v[68:71], v[16:19], v[100:103], v[68:71]
	v_mfma_f32_16x16x32_bf16 v[72:75], v[24:27], v[100:103], v[72:75]
	v_mfma_f32_16x16x32_bf16 v[76:79], v[32:35], v[100:103], v[76:79]
	ds_read_b64 v[4:5], v221 offset:16384
	ds_read_b64 v[8:9], v221 offset:20480
	ds_read_b64 v[12:13], v221 offset:24576
	ds_read_b64 v[16:17], v221 offset:28672
	ds_read_b64 v[6:7], v222 offset:16384
	ds_read_b64 v[10:11], v222 offset:20480
	ds_read_b64 v[14:15], v222 offset:24576
	ds_read_b64 v[18:19], v222 offset:28672
	s_nop 1
	v_fma_f32 v64, v64, s79, v205
	v_fma_f32 v65, v65, s79, v206
	v_fma_f32 v66, v66, s79, v207
	v_fma_f32 v67, v67, s79, v208
	v_fma_f32 v68, v68, s79, v209
	v_fma_f32 v69, v69, s79, v210
	v_fma_f32 v70, v70, s79, v211
	v_fma_f32 v71, v71, s79, v212
	v_fma_f32 v72, v72, s79, v213
	v_fma_f32 v73, v73, s79, v214
	v_fma_f32 v74, v74, s79, v215
	v_fma_f32 v75, v75, s79, v216
	v_fma_f32 v76, v76, s79, v217
	v_fma_f32 v77, v77, s79, v218
	v_fma_f32 v78, v78, s79, v219
	v_fma_f32 v79, v79, s79, v220
	ds_read_b64 v[20:21], v223 offset:16384
	ds_read_b64 v[24:25], v223 offset:20480
	ds_read_b64 v[28:29], v223 offset:24576
	ds_read_b64 v[32:33], v223 offset:28672
	ds_read_b64 v[22:23], v224 offset:16384
	ds_read_b64 v[26:27], v224 offset:20480
	ds_read_b64 v[30:31], v224 offset:24576
	ds_read_b64 v[34:35], v224 offset:28672
	s_cmp_lg_u32 s4, 0
	s_cbranch_scc1 .Lat738_i2_nomask
	s_cmp_le_u32 s6, 0
	s_cbranch_scc1 .Lat738_i2_nomask
	v_mov_b32_e32 v44, v244
	v_mov_b32_e32 v45, v244
	v_mov_b32_e32 v46, v244
	v_mov_b32_e32 v47, v244
	s_cmp_le_u32 s6, 1
	s_cbranch_scc1 .Lat738_i2_nomask
	v_mov_b32_e32 v48, v244
	v_mov_b32_e32 v49, v244
	v_mov_b32_e32 v50, v244
	v_mov_b32_e32 v51, v244
	s_cmp_le_u32 s6, 2
	s_cbranch_scc1 .Lat738_i2_nomask
	v_mov_b32_e32 v52, v244
	v_mov_b32_e32 v53, v244
	v_mov_b32_e32 v54, v244
	v_mov_b32_e32 v55, v244
	s_cmp_le_u32 s6, 3
	s_cbranch_scc1 .Lat738_i2_nomask
	v_mov_b32_e32 v56, v244
	v_mov_b32_e32 v57, v244
	v_mov_b32_e32 v58, v244
	v_mov_b32_e32 v59, v244
	s_cmp_le_u32 s6, 4
	s_cbranch_scc1 .Lat738_i2_nomask
	v_mov_b32_e32 v60, v244
	v_mov_b32_e32 v61, v244
	v_mov_b32_e32 v62, v244
	v_mov_b32_e32 v63, v244
	s_cmp_le_u32 s6, 5
	s_cbranch_scc1 .Lat738_i2_nomask
	v_mov_b32_e32 v64, v244
	v_mov_b32_e32 v65, v244
	v_mov_b32_e32 v66, v244
	v_mov_b32_e32 v67, v244
	s_cmp_le_u32 s6, 6
	s_cbranch_scc1 .Lat738_i2_nomask
	v_mov_b32_e32 v68, v244
	v_mov_b32_e32 v69, v244
	v_mov_b32_e32 v70, v244
	v_mov_b32_e32 v71, v244
	s_cmp_le_u32 s6, 7
	s_cbranch_scc1 .Lat738_i2_nomask
	v_mov_b32_e32 v72, v244
	v_mov_b32_e32 v73, v244
	v_mov_b32_e32 v74, v244
	v_mov_b32_e32 v75, v244
.Lat738_i2_nomask:
	v_max3_f32 v245, v44, v45, v46
	v_max3_f32 v245, v245, v47, v48
	v_max3_f32 v245, v245, v49, v50
	v_max3_f32 v245, v245, v51, v52
	v_max3_f32 v245, v245, v53, v54
	v_max3_f32 v245, v245, v55, v56
	v_max3_f32 v245, v245, v57, v58
	v_max3_f32 v245, v245, v59, v60
	v_max3_f32 v245, v245, v61, v62
	v_max3_f32 v245, v245, v63, v64
	v_max3_f32 v245, v245, v65, v66
	v_max3_f32 v245, v245, v67, v68
	v_max3_f32 v245, v245, v69, v70
	v_max3_f32 v245, v245, v71, v72
	v_max3_f32 v245, v245, v73, v74
	v_max3_f32 v245, v245, v75, v76
	v_max3_f32 v245, v245, v77, v78
	v_max_f32_e32 v245, v245, v79
	ds_bpermute_b32 v148, v239, v245
	s_waitcnt lgkmcnt(0)
	v_max_f32_e32 v245, v245, v148
	ds_bpermute_b32 v148, v240, v245
	s_waitcnt lgkmcnt(0)
	v_max_f32_e32 v245, v245, v148
	v_sub_f32_e32 v44, v44, v245
	v_sub_f32_e32 v45, v45, v245
	v_sub_f32_e32 v46, v46, v245
	v_sub_f32_e32 v47, v47, v245
	v_exp_f32_e32 v44, v44
	v_exp_f32_e32 v45, v45
	v_exp_f32_e32 v46, v46
	v_exp_f32_e32 v47, v47
	v_sub_f32_e32 v48, v48, v245
	v_sub_f32_e32 v49, v49, v245
	v_sub_f32_e32 v50, v50, v245
	v_sub_f32_e32 v51, v51, v245
	v_exp_f32_e32 v48, v48
	v_exp_f32_e32 v49, v49
	v_exp_f32_e32 v50, v50
	v_exp_f32_e32 v51, v51
	v_mov_b32_e32 v149, v44
	v_mov_b32_e32 v150, v45
	v_mov_b32_e32 v151, v46
	v_mov_b32_e32 v152, v47
	v_cvt_pk_bf16_f32 v44, v44, v45
	v_cvt_pk_bf16_f32 v45, v46, v47
	v_sub_f32_e32 v52, v52, v245
	v_sub_f32_e32 v53, v53, v245
	v_sub_f32_e32 v54, v54, v245
	v_sub_f32_e32 v55, v55, v245
	v_exp_f32_e32 v52, v52
	v_exp_f32_e32 v53, v53
	v_exp_f32_e32 v54, v54
	v_exp_f32_e32 v55, v55
	v_add_f32_e32 v149, v149, v48
	v_add_f32_e32 v150, v150, v49
	v_add_f32_e32 v151, v151, v50
	v_add_f32_e32 v152, v152, v51
	v_cvt_pk_bf16_f32 v46, v48, v49
	v_cvt_pk_bf16_f32 v47, v50, v51
	v_sub_f32_e32 v56, v56, v245
	v_sub_f32_e32 v57, v57, v245
	v_sub_f32_e32 v58, v58, v245
	v_sub_f32_e32 v59, v59, v245
	v_exp_f32_e32 v56, v56
	v_exp_f32_e32 v57, v57
	v_exp_f32_e32 v58, v58
	v_exp_f32_e32 v59, v59
	v_add_f32_e32 v149, v149, v52
	v_add_f32_e32 v150, v150, v53
	v_add_f32_e32 v151, v151, v54
	v_add_f32_e32 v152, v152, v55
	v_cvt_pk_bf16_f32 v52, v52, v53
	v_cvt_pk_bf16_f32 v53, v54, v55
	v_sub_f32_e32 v60, v60, v245
	v_sub_f32_e32 v61, v61, v245
	v_sub_f32_e32 v62, v62, v245
	v_sub_f32_e32 v63, v63, v245
	v_exp_f32_e32 v60, v60
	v_exp_f32_e32 v61, v61
	v_exp_f32_e32 v62, v62
	v_exp_f32_e32 v63, v63
	v_add_f32_e32 v149, v149, v56
	v_add_f32_e32 v150, v150, v57
	v_add_f32_e32 v151, v151, v58
	v_add_f32_e32 v152, v152, v59
	v_cvt_pk_bf16_f32 v54, v56, v57
	v_cvt_pk_bf16_f32 v55, v58, v59
	v_sub_f32_e32 v64, v64, v245
	v_sub_f32_e32 v65, v65, v245
	v_sub_f32_e32 v66, v66, v245
	v_sub_f32_e32 v67, v67, v245
	v_exp_f32_e32 v64, v64
	v_exp_f32_e32 v65, v65
	v_exp_f32_e32 v66, v66
	v_exp_f32_e32 v67, v67
	v_add_f32_e32 v149, v149, v60
	v_add_f32_e32 v150, v150, v61
	v_add_f32_e32 v151, v151, v62
	v_add_f32_e32 v152, v152, v63
	v_cvt_pk_bf16_f32 v60, v60, v61
	v_cvt_pk_bf16_f32 v61, v62, v63
	v_sub_f32_e32 v68, v68, v245
	v_sub_f32_e32 v69, v69, v245
	v_sub_f32_e32 v70, v70, v245
	v_sub_f32_e32 v71, v71, v245
	v_exp_f32_e32 v68, v68
	v_exp_f32_e32 v69, v69
	v_exp_f32_e32 v70, v70
	v_exp_f32_e32 v71, v71
	v_add_f32_e32 v149, v149, v64
	v_add_f32_e32 v150, v150, v65
	v_add_f32_e32 v151, v151, v66
	v_add_f32_e32 v152, v152, v67
	v_cvt_pk_bf16_f32 v62, v64, v65
	v_cvt_pk_bf16_f32 v63, v66, v67
	v_sub_f32_e32 v72, v72, v245
	v_sub_f32_e32 v73, v73, v245
	v_sub_f32_e32 v74, v74, v245
	v_sub_f32_e32 v75, v75, v245
	v_exp_f32_e32 v72, v72
	v_exp_f32_e32 v73, v73
	v_exp_f32_e32 v74, v74
	v_exp_f32_e32 v75, v75
	v_add_f32_e32 v149, v149, v68
	v_add_f32_e32 v150, v150, v69
	v_add_f32_e32 v151, v151, v70
	v_add_f32_e32 v152, v152, v71
	v_cvt_pk_bf16_f32 v68, v68, v69
	v_cvt_pk_bf16_f32 v69, v70, v71
	v_sub_f32_e32 v76, v76, v245
	v_sub_f32_e32 v77, v77, v245
	v_sub_f32_e32 v78, v78, v245
	v_sub_f32_e32 v79, v79, v245
	v_exp_f32_e32 v76, v76
	v_exp_f32_e32 v77, v77
	v_exp_f32_e32 v78, v78
	v_exp_f32_e32 v79, v79
	v_add_f32_e32 v149, v149, v72
	v_add_f32_e32 v150, v150, v73
	v_add_f32_e32 v151, v151, v74
	v_add_f32_e32 v152, v152, v75
	v_cvt_pk_bf16_f32 v70, v72, v73
	v_cvt_pk_bf16_f32 v71, v74, v75
	s_nop 0
	v_add_f32_e32 v149, v149, v76
	v_add_f32_e32 v150, v150, v77
	v_add_f32_e32 v151, v151, v78
	v_add_f32_e32 v152, v152, v79
	v_cvt_pk_bf16_f32 v76, v76, v77
	v_cvt_pk_bf16_f32 v77, v78, v79
	v_mov_b32_e32 v78, 0
	v_mov_b32_e32 v79, 0
	v_add_f32_e32 v149, v149, v150
	v_add_f32_e32 v151, v151, v152
	v_add_f32_e32 v246, v149, v151
	s_waitcnt lgkmcnt(0)
	v_mfma_f32_16x16x32_bf16 v[80:83], v[4:7], v[44:47], 0
	v_mfma_f32_16x16x32_bf16 v[84:87], v[8:11], v[44:47], 0
	v_mfma_f32_16x16x32_bf16 v[88:91], v[12:15], v[44:47], 0
	v_mfma_f32_16x16x32_bf16 v[92:95], v[16:19], v[44:47], 0
	ds_read_b64 v[4:5], v225 offset:16384
	ds_read_b64 v[8:9], v225 offset:20480
	ds_read_b64 v[12:13], v225 offset:24576
	ds_read_b64 v[16:17], v225 offset:28672
	ds_read_b64 v[6:7], v226 offset:16384
	ds_read_b64 v[10:11], v226 offset:20480
	ds_read_b64 v[14:15], v226 offset:24576
	ds_read_b64 v[18:19], v226 offset:28672
	v_mfma_f32_16x16x32_bf16 v[80:83], v[20:23], v[52:55], v[80:83]
	v_mfma_f32_16x16x32_bf16 v[84:87], v[24:27], v[52:55], v[84:87]
	v_mfma_f32_16x16x32_bf16 v[88:91], v[28:31], v[52:55], v[88:91]
	v_mfma_f32_16x16x32_bf16 v[92:95], v[32:35], v[52:55], v[92:95]
	ds_read_b64 v[20:21], v227 offset:16384
	ds_read_b64 v[24:25], v227 offset:20480
	ds_read_b64 v[28:29], v227 offset:24576
	ds_read_b64 v[32:33], v227 offset:28672
	ds_read_b64 v[22:23], v228 offset:16384
	ds_read_b64 v[26:27], v228 offset:20480
	ds_read_b64 v[30:31], v228 offset:24576
	ds_read_b64 v[34:35], v228 offset:28672
	ds_bpermute_b32 v148, v239, v246
	s_waitcnt lgkmcnt(9)
	v_mfma_f32_16x16x32_bf16 v[80:83], v[4:7], v[60:63], v[80:83]
	v_mfma_f32_16x16x32_bf16 v[84:87], v[8:11], v[60:63], v[84:87]
	v_mfma_f32_16x16x32_bf16 v[88:91], v[12:15], v[60:63], v[88:91]
	v_mfma_f32_16x16x32_bf16 v[92:95], v[16:19], v[60:63], v[92:95]
	ds_read_b64 v[4:5], v229 offset:16384
	ds_read_b64 v[8:9], v229 offset:20480
	ds_read_b64 v[12:13], v229 offset:24576
	ds_read_b64 v[16:17], v229 offset:28672
	v_mov_b32_e32 v6, 0
	v_mov_b32_e32 v7, 0
	v_mov_b32_e32 v10, 0
	v_mov_b32_e32 v11, 0
	v_mov_b32_e32 v14, 0
	v_mov_b32_e32 v15, 0
	v_mov_b32_e32 v18, 0
	v_mov_b32_e32 v19, 0
	s_waitcnt lgkmcnt(5)
	v_mfma_f32_16x16x32_bf16 v[80:83], v[20:23], v[68:71], v[80:83]
	v_mfma_f32_16x16x32_bf16 v[84:87], v[24:27], v[68:71], v[84:87]
	v_mfma_f32_16x16x32_bf16 v[88:91], v[28:31], v[68:71], v[88:91]
	v_mfma_f32_16x16x32_bf16 v[92:95], v[32:35], v[68:71], v[92:95]
	s_waitcnt lgkmcnt(0)
	v_add_f32_e32 v246, v246, v148
	s_nop 0
	v_mfma_f32_16x16x32_bf16 v[80:83], v[4:7], v[76:79], v[80:83]
	v_mfma_f32_16x16x32_bf16 v[84:87], v[8:11], v[76:79], v[84:87]
	v_mfma_f32_16x16x32_bf16 v[88:91], v[12:15], v[76:79], v[88:91]
	v_mfma_f32_16x16x32_bf16 v[92:95], v[16:19], v[76:79], v[92:95]
	ds_bpermute_b32 v148, v240, v246
	s_waitcnt lgkmcnt(0)
	v_add_f32_e32 v246, v246, v148
	v_rcp_f32_e32 v149, v246
	v_log_f32_e32 v150, v246
	s_nop 0
	v_add_f32_e32 v151, v245, v150
	v_mul_f32_e32 v151, 0x3f317218, v151
	v_mov_b32_e32 v140, v151
	v_mul_f32_e32 v80, v80, v149
	v_mul_f32_e32 v81, v81, v149
	v_mul_f32_e32 v82, v82, v149
	v_mul_f32_e32 v83, v83, v149
	v_mul_f32_e32 v84, v84, v149
	v_mul_f32_e32 v85, v85, v149
	v_mul_f32_e32 v86, v86, v149
	v_mul_f32_e32 v87, v87, v149
	v_mul_f32_e32 v88, v88, v149
	v_mul_f32_e32 v89, v89, v149
	v_mul_f32_e32 v90, v90, v149
	v_mul_f32_e32 v91, v91, v149
	v_mul_f32_e32 v92, v92, v149
	v_mul_f32_e32 v93, v93, v149
	v_mul_f32_e32 v94, v94, v149
	v_mul_f32_e32 v95, v95, v149
	v_cvt_pk_bf16_f32 v132, v80, v81
	v_cvt_pk_bf16_f32 v133, v82, v83
	v_cvt_pk_bf16_f32 v134, v84, v85
	v_cvt_pk_bf16_f32 v135, v86, v87
	v_cvt_pk_bf16_f32 v136, v88, v89
	v_cvt_pk_bf16_f32 v137, v90, v91
	v_cvt_pk_bf16_f32 v138, v92, v93
	v_cvt_pk_bf16_f32 v139, v94, v95
	s_mov_b64 s[26:27], s[86:87]
	s_mov_b64 s[28:29], s[88:89]
	s_mov_b64 s[86:87], s[12:13]
	s_mov_b64 s[88:89], s[14:15]
	s_mov_b32 s4, s83
	s_mov_b32 s5, s84
	s_waitcnt vmcnt(0)
	s_barrier
	ds_read_b128 v[4:7], v230 offset:32768
	ds_read_b128 v[8:11], v231 offset:32768
	ds_read_b128 v[12:15], v230 offset:34816
	ds_read_b128 v[16:19], v231 offset:34816
	ds_read_b128 v[20:23], v230 offset:36864
	ds_read_b128 v[24:27], v231 offset:36864
	ds_read_b128 v[28:31], v230 offset:38912
	ds_read_b128 v[32:35], v231 offset:38912
	ds_read_b128 v[36:39], v230 offset:40960
	ds_read_b128 v[40:43], v231 offset:40960
	global_store_dwordx2 v237, v[132:133], s[26:27]
	global_store_dwordx2 v237, v[134:135], s[26:27] offset:32
	global_store_dwordx2 v237, v[136:137], s[26:27] offset:64
	global_store_dwordx2 v237, v[138:139], s[26:27] offset:96
	s_mov_b64 s[90:91], exec
	s_mov_b64 exec, 0xffff
	global_store_dword v238, v140, s[28:29]
	s_mov_b64 exec, s[90:91]
	s_cmp_eq_u32 s7, 1
	s_cbranch_scc1 .Lat738_i3_nonext
	s_add_u32 s83, s4, 1
	s_mov_b32 s84, s5
	s_mul_i32 s74, s84, 4096
	s_lshl_b32 s75, s83, 7
	s_add_u32 s74, s74, s75
	s_lshl_b32 s75, s74, 7
	s_add_u32 s16, s60, s75
	s_addc_u32 s17, s61, 0
	s_lshl_b32 s75, s74, 1
	s_add_u32 s24, s64, s75
	s_addc_u32 s25, s65, 0
	s_add_u32 m0, s70, 0x0
	s_nop 0
	global_load_lds_dwordx4 v232, s[16:17] nt
	s_add_u32 m0, s70, 0x2000
	s_nop 0
	global_load_lds_dwordx4 v233, s[16:17] nt
	s_add_u32 m0, s70, 0x10000
	s_nop 0
	global_load_lds_dwordx4 v234, s[24:25] nt
	s_add_u32 m0, s70, 0x12000
	s_nop 0
	global_load_lds_dwordx4 v235, s[24:25] nt
	s_lshl_b32 s74, s83, 7
	s_add_u32 s74, s74, s84
	s_lshl_b32 s75, s74, 7
	s_add_u32 s10, s30, s75
	s_addc_u32 s11, s31, 0
	s_add_u32 s12, s34, s75
	s_addc_u32 s13, s35, 0
	s_lshl_b32 s75, s74, 2
	s_add_u32 s14, s58, s75
	s_addc_u32 s15, s59, 0
	global_load_dwordx4 v[96:99], v236, s[10:11]
	global_load_dwordx4 v[100:103], v236, s[10:11] offset:64

.LBB0_759:
	s_and_b64 vcc, exec, s[6:7]
	s_cbranch_vccz .LBB0_789
	v_readlane_b32 s0, v254, 54
	v_readlane_b32 s1, v254, 55
	v_mov_b32_e32 v0, v170
	s_and_b64 vcc, exec, s[0:1]
	s_cbranch_vccnz .LBB0_765
	v_lshlrev_b32_e32 v1, 2, v0
	v_and_b32_e32 v18, 60, v1
	v_readlane_b32 s0, v253, 45
	v_lshlrev_b32_e32 v2, 2, v18
	v_readlane_b32 s1, v253, 46
	v_add_u32_e32 v1, 0x200, v0
	v_ashrrev_i32_e32 v12, 4, v0
	v_lshl_add_u64 v[4:5], s[0:1], 0, v[2:3]
	v_readlane_b32 s0, v253, 44
	v_ashrrev_i32_e32 v13, 4, v1
	v_ashrrev_i32_e32 v14, 3, v0
	v_add_u32_e32 v6, s0, v12
	v_add_u32_e32 v8, s0, v13
	v_ashrrev_i32_e32 v7, 31, v6
	v_ashrrev_i32_e32 v9, 31, v8
	v_lshlrev_b64 v[6:7], 12, v[6:7]
	v_lshlrev_b64 v[8:9], 12, v[8:9]
	v_lshl_add_u64 v[6:7], v[4:5], 0, v[6:7]
	v_lshl_add_u64 v[8:9], v[4:5], 0, v[8:9]
	global_load_dwordx4 v[4:7], v[6:7], off nt
	s_nop 0
	global_load_dwordx4 v[8:11], v[8:9], off nt
	v_lshlrev_b32_e32 v0, 3, v0
	v_add_u32_e32 v1, 0, v2
	v_and_b32_e32 v2, 56, v0
	v_mul_u32_u24_e32 v0, 0x104, v2
	v_lshlrev_b32_e32 v15, 2, v14
	s_movk_i32 s0, 0x104
	v_add3_u32 v15, 0, v0, v15
	v_mul_lo_u32 v0, v12, s0
	v_mul_lo_u32 v17, v13, s0
	v_add_u32_e32 v16, v1, v0
	v_add_u32_e32 v17, v1, v17
	v_lshlrev_b32_e32 v0, 2, v18
	v_lshlrev_b32_e32 v2, 1, v2
	s_branch .LBB0_763

.LBB0_763:
	s_add_i32 s0, s85, s92
	s_cmpk_gt_i32 s0, 0x1ff
	s_cselect_b64 s[4:5], -1, 0
	s_and_b64 vcc, exec, s[4:5]
	s_waitcnt vmcnt(1)
	ds_write2_b32 v16, v4, v5 offset1:1
	ds_write2_b32 v16, v6, v7 offset0:2 offset1:3
	s_waitcnt vmcnt(0)
	ds_write2_b32 v17, v8, v9 offset1:1
	ds_write2_b32 v17, v10, v11 offset0:2 offset1:3
	s_cbranch_vccnz .LBB0_762
	s_ashr_i32 s2, s0, 31
	s_lshr_b32 s2, s2, 24
	s_add_i32 s3, s0, s2
	s_ashr_i32 s2, s3, 8
	s_and_b32 s3, s3, 0xff00
	s_sub_i32 s3, s0, s3
	s_sext_i32_i16 s6, s3
	s_bfe_u32 s6, s6, 0x4001b
	s_add_i32 s6, s3, s6
	s_sext_i32_i16 s7, s6
	s_and_b32 s6, s6, 0xfff0
	s_sub_i32 s3, s3, s6
	v_readlane_b32 s44, v252, 4
	s_sext_i32_i16 s6, s3
	s_ashr_i32 s3, s2, 31
	v_readlane_b32 s58, v252, 18
	v_readlane_b32 s59, v252, 19
	s_lshl_b64 s[2:3], s[2:3], 22
	s_mov_b64 s[14:15], s[58:59]
	s_add_u32 s8, s14, s2
	s_addc_u32 s9, s15, s3
	s_lshl_b32 s2, s7, 2
	s_and_b32 s7, s2, 0xffffffc0
	s_lshl_b32 s2, s6, 6
	s_ashr_i32 s3, s2, 31
	s_lshl_b64 s[2:3], s[2:3], 2
	s_add_u32 s2, s8, s2
	v_add_u32_e32 v6, s7, v12
	v_add_u32_e32 v8, s7, v13
	s_addc_u32 s3, s9, s3
	v_mov_b32_e32 v1, v3
	v_ashrrev_i32_e32 v7, 31, v6
	v_ashrrev_i32_e32 v9, 31, v8
	v_lshl_add_u64 v[4:5], s[2:3], 0, v[0:1]
	v_lshlrev_b64 v[6:7], 12, v[6:7]
	v_lshlrev_b64 v[8:9], 12, v[8:9]
	v_lshl_add_u64 v[6:7], v[4:5], 0, v[6:7]
	v_lshl_add_u64 v[8:9], v[4:5], 0, v[8:9]
	global_load_dwordx4 v[4:7], v[6:7], off nt
	s_nop 0
	global_load_dwordx4 v[8:11], v[8:9], off nt
	v_readlane_b32 s45, v252, 5
	v_readlane_b32 s46, v252, 6
	v_readlane_b32 s47, v252, 7
	v_readlane_b32 s48, v252, 8
	v_readlane_b32 s49, v252, 9
	v_readlane_b32 s50, v252, 10
	v_readlane_b32 s51, v252, 11
	v_readlane_b32 s52, v252, 12
	v_readlane_b32 s53, v252, 13
	v_readlane_b32 s54, v252, 14
	v_readlane_b32 s55, v252, 15
	v_readlane_b32 s56, v252, 16
	v_readlane_b32 s57, v252, 17
	s_branch .LBB0_762
.LBB0_765:
	v_mov_b32_e32 v0, v170
	v_readlane_b32 s6, v253, 49
	v_readfirstlane_b32 s0, v0
	v_and_b32_e32 v63, 63, v0
	s_ashr_i32 s2, s0, 6
	v_mov_b32_e32 v1, v63
	s_lshl_b32 s0, s2, 3
	s_waitcnt vmcnt(2)
	v_ashrrev_i32_e32 v6, 3, v1
	v_add_u32_e32 v4, s0, v6
	v_lshrrev_b32_e32 v2, 1, v4
	v_xor_b32_e32 v2, v2, v1
	v_ashrrev_i32_e32 v5, 31, v4
	v_lshlrev_b64 v[4:5], 7, v[4:5]
	v_readlane_b32 s7, v253, 50
	v_lshlrev_b32_e32 v2, 4, v2
	s_lshl_b32 s35, s2, 10
	s_add_i32 s4, 0, 0x18000
	v_lshl_add_u64 v[4:5], s[6:7], 0, v[4:5]
	v_and_b32_e32 v2, 0x70, v2
	s_add_i32 s3, s4, s35
	s_add_i32 s5, s2, 8
	v_lshl_add_u64 v[4:5], v[4:5], 0, v[2:3]
	v_writelane_b32 v253, s3, 4
	s_mov_b32 m0, s3
	s_bitset0_b32 m0, 16
	s_bitset1_b32 m0, 14
	s_lshl_b32 s3, s5, 3
	global_load_lds_dwordx4 v[4:5], off nt
	v_add_u32_e32 v4, s3, v6
	v_lshrrev_b32_e32 v2, 1, v4
	v_xor_b32_e32 v2, v2, v1
	v_ashrrev_i32_e32 v5, 31, v4
	v_lshlrev_b64 v[4:5], 7, v[4:5]
	v_lshlrev_b32_e32 v2, 4, v2
	s_lshl_b32 s10, s5, 10
	v_lshl_add_u64 v[4:5], s[6:7], 0, v[4:5]
	v_and_b32_e32 v2, 0x70, v2
	s_add_i32 s4, s4, s10
	v_lshl_add_u64 v[4:5], v[4:5], 0, v[2:3]
	s_mov_b32 m0, s4
	s_bitset0_b32 m0, 16
	s_bitset1_b32 m0, 14
	v_ashrrev_i32_e32 v6, 4, v1
	s_lshl_b32 s12, s2, 2
	v_writelane_b32 v253, s4, 1
	global_load_lds_dwordx4 v[4:5], off nt
	v_add_u32_e32 v4, s12, v6
	v_xor_b32_e32 v2, v4, v1
	v_ashrrev_i32_e32 v5, 31, v4
	v_readlane_b32 s6, v253, 32
	v_lshlrev_b64 v[4:5], 15, v[4:5]
	v_readlane_b32 s7, v253, 33
	v_lshlrev_b32_e32 v2, 4, v2
	s_add_i32 s4, 0, 0x1c000
	v_lshl_add_u64 v[4:5], s[6:7], 0, v[4:5]
	v_and_b32_e32 v2, 0xf0, v2
	s_add_i32 s8, s4, s35
	v_lshl_add_u64 v[4:5], v[4:5], 0, v[2:3]
	s_mov_b32 m0, s8
	s_lshl_b32 s14, s5, 2
	global_load_lds_dwordx4 v[4:5], off nt
	v_add_u32_e32 v4, s14, v6
	v_xor_b32_e32 v1, v4, v1
	v_ashrrev_i32_e32 v5, 31, v4
	v_lshlrev_b64 v[4:5], 15, v[4:5]
	v_lshlrev_b32_e32 v1, 4, v1
	v_lshl_add_u64 v[4:5], s[6:7], 0, v[4:5]
	v_and_b32_e32 v2, 0xf0, v1
	s_add_i32 s4, s4, s10
	v_lshl_add_u64 v[4:5], v[4:5], 0, v[2:3]
	s_mov_b32 m0, s4
	v_mov_b32_e32 v1, v63
	global_load_lds_dwordx4 v[4:5], off nt
	v_writelane_b32 v253, s8, 13
	v_ashrrev_i32_e32 v6, 3, v1
	v_add_u32_e32 v4, s0, v6
	v_writelane_b32 v253, s4, 2
	v_lshrrev_b32_e32 v2, 1, v4
	v_xor_b32_e32 v2, v2, v1
	v_ashrrev_i32_e32 v5, 31, v4
	v_readlane_b32 s4, v253, 54
	v_lshlrev_b64 v[4:5], 7, v[4:5]
	v_readlane_b32 s5, v253, 55
	v_lshlrev_b32_e32 v2, 4, v2
	v_and_b32_e32 v2, 0x70, v2
	v_lshl_add_u64 v[4:5], s[4:5], 0, v[4:5]
	s_add_i32 s16, s35, 0
	v_lshl_add_u64 v[4:5], v[4:5], 0, v[2:3]
	s_mov_b32 m0, s16
	s_add_i32 s17, s10, 0
	global_load_lds_dwordx4 v[4:5], off nt
	v_add_u32_e32 v4, s3, v6
	v_lshrrev_b32_e32 v2, 1, v4
	v_xor_b32_e32 v2, v2, v1
	v_ashrrev_i32_e32 v5, 31, v4
	v_lshlrev_b64 v[4:5], 7, v[4:5]
	v_lshlrev_b32_e32 v2, 4, v2
	v_lshl_add_u64 v[4:5], s[4:5], 0, v[4:5]
	v_and_b32_e32 v2, 0x70, v2
	v_lshl_add_u64 v[4:5], v[4:5], 0, v[2:3]
	s_mov_b32 m0, s17
	v_ashrrev_i32_e32 v6, 4, v1
	global_load_lds_dwordx4 v[4:5], off nt
	v_add_u32_e32 v4, s12, v6
	v_xor_b32_e32 v2, v4, v1
	v_ashrrev_i32_e32 v5, 31, v4
	v_readlane_b32 s4, v253, 37
	v_lshlrev_b64 v[4:5], 15, v[4:5]
	v_readlane_b32 s5, v253, 38
	v_lshlrev_b32_e32 v2, 4, v2
	v_and_b32_e32 v2, 0xf0, v2
	v_lshl_add_u64 v[4:5], s[4:5], 0, v[4:5]
	s_add_i32 s6, s16, 0x4000
	v_lshl_add_u64 v[4:5], v[4:5], 0, v[2:3]
	s_mov_b32 m0, s6
	s_bitset0_b32 m0, 14
	s_bitset1_b32 m0, 16
	v_writelane_b32 v254, s6, 58
	global_load_lds_dwordx4 v[4:5], off nt
	v_add_u32_e32 v4, s14, v6
	v_ashrrev_i32_e32 v5, 31, v4
	v_xor_b32_e32 v1, v4, v1
	v_lshlrev_b64 v[4:5], 15, v[4:5]
	v_lshl_add_u64 v[4:5], s[4:5], 0, v[4:5]
	s_add_i32 s4, s17, 0x4000
	v_and_b32_e32 v64, 15, v0
	v_lshlrev_b32_e32 v1, 4, v1
	v_writelane_b32 v254, s4, 59
	s_mov_b32 m0, s4
	s_bitset0_b32 m0, 14
	s_bitset1_b32 m0, 16
	v_readlane_b32 s4, v253, 56
	v_and_b32_e32 v2, 0xf0, v1
	s_lshl_b32 s87, s2, 4
	v_or_b32_e32 v1, s4, v64
	v_add_u32_e32 v28, s87, v1
	v_lshl_add_u64 v[4:5], v[4:5], 0, v[2:3]
	v_ashrrev_i32_e32 v29, 31, v28
	v_readlane_b32 s4, v253, 8
	global_load_lds_dwordx4 v[4:5], off nt
	v_lshlrev_b64 v[4:5], 7, v[28:29]
	v_readlane_b32 s5, v253, 9
	v_and_b32_e32 v2, 48, v0
	s_cmp_gt_i32 s2, 3
	v_lshl_add_u64 v[4:5], s[4:5], 0, v[4:5]
	v_lshl_add_u64 v[4:5], v[4:5], 0, v[2:3]
	global_load_dwordx4 v[8:11], v[4:5], off
	s_nop 0
	global_load_dwordx4 v[4:7], v[4:5], off offset:64
	s_cbranch_scc1 .LBB0_767
	s_setprio 1

.LBB0_789:
	v_mov_b32_e32 v0, v170
	v_readlane_b32 s6, v253, 57
	v_readfirstlane_b32 s0, v0
	v_and_b32_e32 v4, 63, v0
	s_ashr_i32 s0, s0, 6
	v_mov_b32_e32 v5, v4
	s_lshl_b32 s1, s0, 3
	v_ashrrev_i32_e32 v6, 3, v5
	v_add_u32_e32 v0, s1, v6
	v_lshrrev_b32_e32 v1, 1, v0
	v_xor_b32_e32 v2, v1, v5
	v_ashrrev_i32_e32 v1, 31, v0
	v_lshlrev_b64 v[0:1], 7, v[0:1]
	v_readlane_b32 s7, v253, 58
	v_lshlrev_b32_e32 v2, 4, v2
	v_and_b32_e32 v2, 0x70, v2
	v_lshl_add_u64 v[0:1], s[6:7], 0, v[0:1]
	s_lshl_b32 s2, s0, 10
	s_add_i32 s82, 0, 0x18000
	s_add_i32 s3, s0, 8
	v_lshl_add_u64 v[0:1], v[0:1], 0, v[2:3]
	s_add_i32 m0, s82, s2
	s_bitset0_b32 m0, 16
	s_bitset1_b32 m0, 14
	s_lshl_b32 s4, s3, 3
	global_load_lds_dwordx4 v[0:1], off nt
	v_add_u32_e32 v0, s4, v6
	v_lshrrev_b32_e32 v1, 1, v0
	v_xor_b32_e32 v2, v1, v5
	v_ashrrev_i32_e32 v1, 31, v0
	v_lshlrev_b64 v[0:1], 7, v[0:1]
	v_lshlrev_b32_e32 v2, 4, v2
	v_lshl_add_u64 v[0:1], s[6:7], 0, v[0:1]
	v_and_b32_e32 v2, 0x70, v2
	s_lshl_b32 s5, s3, 10
	v_lshl_add_u64 v[0:1], v[0:1], 0, v[2:3]
	s_add_i32 m0, s82, s5
	s_bitset0_b32 m0, 16
	s_bitset1_b32 m0, 14
	v_ashrrev_i32_e32 v6, 4, v5
	s_lshl_b32 s0, s0, 2
	global_load_lds_dwordx4 v[0:1], off nt
	v_add_u32_e32 v0, s0, v6
	v_xor_b32_e32 v2, v0, v5
	v_ashrrev_i32_e32 v1, 31, v0
	v_readlane_b32 s8, v253, 59
	v_lshlrev_b64 v[0:1], 15, v[0:1]
	v_readlane_b32 s9, v253, 60
	v_lshlrev_b32_e32 v2, 4, v2
	v_and_b32_e32 v2, 0xf0, v2
	v_lshl_add_u64 v[0:1], s[8:9], 0, v[0:1]
	s_add_i32 s62, 0, 0x1c000
	v_lshl_add_u64 v[0:1], v[0:1], 0, v[2:3]
	s_add_i32 m0, s62, s2
	s_lshl_b32 s3, s3, 2
	global_load_lds_dwordx4 v[0:1], off nt
	v_add_u32_e32 v0, s3, v6
	v_xor_b32_e32 v2, v0, v5
	v_ashrrev_i32_e32 v1, 31, v0
	v_lshlrev_b64 v[0:1], 15, v[0:1]
	v_lshlrev_b32_e32 v2, 4, v2
	v_lshl_add_u64 v[0:1], s[8:9], 0, v[0:1]
	v_and_b32_e32 v2, 0xf0, v2
	v_lshl_add_u64 v[0:1], v[0:1], 0, v[2:3]
	s_add_i32 m0, s62, s5
	s_nop 0
	global_load_lds_dwordx4 v[0:1], off nt
	s_nop 0
	v_ashrrev_i32_e32 v5, 3, v4
	v_add_u32_e32 v0, s1, v5
	v_lshrrev_b32_e32 v1, 1, v0
	v_xor_b32_e32 v2, v1, v4
	v_ashrrev_i32_e32 v1, 31, v0
	v_lshlrev_b64 v[0:1], 7, v[0:1]
	v_lshlrev_b32_e32 v2, 4, v2
	v_lshl_add_u64 v[0:1], s[6:7], 0, v[0:1]
	v_and_b32_e32 v2, 0x70, v2
	s_add_i32 s1, s2, 0
	v_lshl_add_u64 v[0:1], v[0:1], 0, v[2:3]
	s_mov_b32 m0, s1
	s_add_i32 s2, s5, 0
	global_load_lds_dwordx4 v[0:1], off nt
	v_add_u32_e32 v0, s4, v5
	v_lshrrev_b32_e32 v1, 1, v0
	v_xor_b32_e32 v2, v1, v4
	v_ashrrev_i32_e32 v1, 31, v0
	v_lshlrev_b64 v[0:1], 7, v[0:1]
	v_lshlrev_b32_e32 v2, 4, v2
	v_lshl_add_u64 v[0:1], s[6:7], 0, v[0:1]
	v_and_b32_e32 v2, 0x70, v2
	v_lshl_add_u64 v[0:1], v[0:1], 0, v[2:3]
	s_mov_b32 m0, s2
	v_ashrrev_i32_e32 v5, 4, v4
	global_load_lds_dwordx4 v[0:1], off nt
	v_add_u32_e32 v0, s0, v5
	v_xor_b32_e32 v2, v0, v4
	v_ashrrev_i32_e32 v1, 31, v0
	v_lshlrev_b64 v[0:1], 15, v[0:1]
	v_lshlrev_b32_e32 v2, 4, v2
	v_lshl_add_u64 v[0:1], s[8:9], 0, v[0:1]
	v_and_b32_e32 v2, 0xf0, v2
	v_lshl_add_u64 v[0:1], v[0:1], 0, v[2:3]
	s_add_i32 m0, s1, 0x4000
	s_bitset0_b32 m0, 14
	s_bitset1_b32 m0, 16
	s_nop 0
	global_load_lds_dwordx4 v[0:1], off nt
	v_add_u32_e32 v0, s3, v5
	v_xor_b32_e32 v2, v0, v4
	v_ashrrev_i32_e32 v1, 31, v0
	v_lshlrev_b64 v[0:1], 15, v[0:1]
	v_lshlrev_b32_e32 v2, 4, v2
	v_lshl_add_u64 v[0:1], s[8:9], 0, v[0:1]
	v_and_b32_e32 v2, 0xf0, v2
	v_lshl_add_u64 v[0:1], v[0:1], 0, v[2:3]
	s_add_i32 m0, s2, 0x4000
	s_bitset0_b32 m0, 14
	s_bitset1_b32 m0, 16
	s_nop 0
	global_load_lds_dwordx4 v[0:1], off nt
	s_waitcnt vmcnt(0)
	s_waitcnt vmcnt(0) lgkmcnt(0)
	s_barrier
	s_mov_b64 s[4:5], exec
	v_readlane_b32 s0, v252, 2
	v_readlane_b32 s1, v252, 3
	s_and_b64 s[0:1], s[4:5], s[0:1]
	s_mov_b64 exec, s[0:1]
	s_cbranch_execz .LBB0_841
	v_mov_b32_e32 v0, 0x20000
	ds_read_b64 v[0:1], v0
	s_getreg_b32 s44, hwreg(HW_REG_XCC_ID, 0, 4)
	s_lshl_b32 s44, s44, 7
	s_add_u32 s44, s44, 0xdc03600
	v_mov_b32_e32 v2, s44
	v_mov_b32_e32 v4, 1
	s_waitcnt vmcnt(0) lgkmcnt(0)
	global_atomic_add v5, v2, v4, s[42:43] sc0
	buffer_inv sc1
	s_add_u32 s100, s100, 1
	v_readfirstlane_b32 s46, v0
	v_readfirstlane_b32 s47, v1
	v_mov_b32_e32 v2, 0xdc03e00
	s_nop 3
	s_mul_i32 s48, s46, s100
	s_mul_i32 s49, s47, s100
	s_waitcnt vmcnt(1)
	v_readfirstlane_b32 s50, v5
	s_nop 3
	s_add_u32 s50, s50, 1
	s_cmp_lg_u32 s50, s48
	s_cbranch_scc1 .Lxb6_poll
	buffer_wbl2 sc1
	s_waitcnt vmcnt(0)
	global_atomic_add v2, v4, s[42:43]

.Lat844_i0_nopend:
	s_add_u32 s83, s4, 1
	s_mov_b32 s84, s5
	s_mul_i32 s74, s84, 1024
	s_lshl_b32 s75, s83, 7
	s_add_u32 s74, s74, s75
	s_lshl_b32 s75, s74, 7
	s_add_u32 s16, s60, s75
	s_addc_u32 s17, s61, 0
	s_lshl_b32 s75, s74, 1
	s_add_u32 s24, s64, s75
	s_addc_u32 s25, s65, 0
	s_add_u32 m0, s70, 0x4000
	s_nop 0
	global_load_lds_dwordx4 v232, s[16:17] nt
	s_add_u32 m0, s70, 0x6000
	s_nop 0
	global_load_lds_dwordx4 v233, s[16:17] nt
	s_add_u32 m0, s70, 0x14000
	s_nop 0
	global_load_lds_dwordx4 v234, s[24:25] nt
	s_add_u32 m0, s70, 0x16000
	s_nop 0
	global_load_lds_dwordx4 v235, s[24:25] nt
	s_lshl_b32 s74, s83, 9
	s_add_u32 s74, s74, s84
	s_lshl_b32 s75, s74, 7
	s_add_u32 s10, s30, s75
	s_addc_u32 s11, s31, 0
	s_add_u32 s12, s34, s75
	s_addc_u32 s13, s35, 0
	s_lshl_b32 s75, s74, 2
	s_add_u32 s14, s58, s75
	s_addc_u32 s15, s59, 0
	global_load_dwordx4 v[104:107], v236, s[10:11]
	global_load_dwordx4 v[108:111], v236, s[10:11] offset:64
	global_load_dwordx2 v[122:123], v237, s[12:13]
	global_load_dwordx2 v[124:125], v237, s[12:13] offset:32
	global_load_dwordx2 v[126:127], v237, s[12:13] offset:64
	global_load_dwordx2 v[128:129], v237, s[12:13] offset:96
	global_load_dword v121, v238, s[14:15]
	s_waitcnt lgkmcnt(0)
	v_mfma_f32_16x16x32_bf16 v[44:47], v[4:7], v[96:99], 0
	v_mfma_f32_16x16x32_bf16 v[48:51], v[12:15], v[96:99], 0
	v_mfma_f32_16x16x32_bf16 v[52:55], v[20:23], v[96:99], 0
	v_mfma_f32_16x16x32_bf16 v[56:59], v[28:31], v[96:99], 0
	v_mfma_f32_16x16x32_bf16 v[60:63], v[36:39], v[96:99], 0
	v_mfma_f32_16x16x32_bf16 v[44:47], v[8:11], v[100:103], v[44:47]
	v_mfma_f32_16x16x32_bf16 v[48:51], v[16:19], v[100:103], v[48:51]
	v_mfma_f32_16x16x32_bf16 v[52:55], v[24:27], v[100:103], v[52:55]
	v_mfma_f32_16x16x32_bf16 v[56:59], v[32:35], v[100:103], v[56:59]
	v_mfma_f32_16x16x32_bf16 v[60:63], v[40:43], v[100:103], v[60:63]
	s_cmp_gt_u32 s6, 5
	s_cselect_b32 s74, s77, s78
	v_add_u32_e32 v146, s74, v230
	v_xor_b32_e32 v147, 64, v146
	ds_read_b128 v[4:7], v146 offset:10240
	ds_read_b128 v[8:11], v147 offset:10240
	s_cmp_gt_u32 s6, 6
	s_cselect_b32 s74, s77, s78
	v_add_u32_e32 v146, s74, v230
	v_xor_b32_e32 v147, 64, v146
	ds_read_b128 v[12:15], v146 offset:12288
	ds_read_b128 v[16:19], v147 offset:12288
	s_cmp_gt_u32 s6, 7
	s_cselect_b32 s74, s77, s78
	v_add_u32_e32 v146, s74, v230
	v_xor_b32_e32 v147, 64, v146
	ds_read_b128 v[20:23], v146 offset:14336
	ds_read_b128 v[24:27], v147 offset:14336
	s_cmp_gt_u32 s6, 8
	s_cselect_b32 s74, s77, s78
	v_add_u32_e32 v146, s74, v230
	v_xor_b32_e32 v147, 64, v146
	ds_read_b128 v[28:31], v146 offset:16384
	ds_read_b128 v[32:35], v147 offset:16384
	s_nop 1
	v_fma_f32 v44, v44, s79, v185
	v_fma_f32 v45, v45, s79, v186
	v_fma_f32 v46, v46, s79, v187
	v_fma_f32 v47, v47, s79, v188
	v_fma_f32 v48, v48, s79, v189
	v_fma_f32 v49, v49, s79, v190
	v_fma_f32 v50, v50, s79, v191
	v_fma_f32 v51, v51, s79, v192
	v_fma_f32 v52, v52, s79, v193
	v_fma_f32 v53, v53, s79, v194
	v_fma_f32 v54, v54, s79, v195
	v_fma_f32 v55, v55, s79, v196
	v_fma_f32 v56, v56, s79, v197
	v_fma_f32 v57, v57, s79, v198
	v_fma_f32 v58, v58, s79, v199
	v_fma_f32 v59, v59, s79, v200
	v_fma_f32 v60, v60, s79, v201
	v_fma_f32 v61, v61, s79, v202
	v_fma_f32 v62, v62, s79, v203
	v_fma_f32 v63, v63, s79, v204
	s_waitcnt lgkmcnt(0)
	v_mfma_f32_16x16x32_bf16 v[64:67], v[4:7], v[96:99], 0
	v_mfma_f32_16x16x32_bf16 v[68:71], v[12:15], v[96:99], 0
	v_mfma_f32_16x16x32_bf16 v[72:75], v[20:23], v[96:99], 0
	v_mfma_f32_16x16x32_bf16 v[76:79], v[28:31], v[96:99], 0
	v_mfma_f32_16x16x32_bf16 v[64:67], v[8:11], v[100:103], v[64:67]
	v_mfma_f32_16x16x32_bf16 v[68:71], v[16:19], v[100:103], v[68:71]
	v_mfma_f32_16x16x32_bf16 v[72:75], v[24:27], v[100:103], v[72:75]
	v_mfma_f32_16x16x32_bf16 v[76:79], v[32:35], v[100:103], v[76:79]
	s_cmp_gt_u32 s6, 0
	s_cselect_b32 s74, 0, 0xffff0000
	v_add_u32_e32 v146, s74, v221
	ds_read_b64 v[4:5], v146 offset:49152
	ds_read_b64 v[8:9], v146 offset:53248
	ds_read_b64 v[12:13], v146 offset:57344
	ds_read_b64 v[16:17], v146 offset:61440
	s_cmp_gt_u32 s6, 1
	s_cselect_b32 s74, 0, 0xffff0000
	v_add_u32_e32 v146, s74, v222
	ds_read_b64 v[6:7], v146 offset:49152
	ds_read_b64 v[10:11], v146 offset:53248
	ds_read_b64 v[14:15], v146 offset:57344
	ds_read_b64 v[18:19], v146 offset:61440
	s_nop 1
	v_fma_f32 v64, v64, s79, v205
	v_fma_f32 v65, v65, s79, v206
	v_fma_f32 v66, v66, s79, v207
	v_fma_f32 v67, v67, s79, v208
	v_fma_f32 v68, v68, s79, v209
	v_fma_f32 v69, v69, s79, v210
	v_fma_f32 v70, v70, s79, v211
	v_fma_f32 v71, v71, s79, v212
	v_fma_f32 v72, v72, s79, v213
	v_fma_f32 v73, v73, s79, v214
	v_fma_f32 v74, v74, s79, v215
	v_fma_f32 v75, v75, s79, v216
	v_fma_f32 v76, v76, s79, v217
	v_fma_f32 v77, v77, s79, v218
	v_fma_f32 v78, v78, s79, v219
	v_fma_f32 v79, v79, s79, v220
	s_cmp_gt_u32 s6, 2
	s_cselect_b32 s74, 0, 0xffff0000
	v_add_u32_e32 v146, s74, v223
	ds_read_b64 v[20:21], v146 offset:49152
	ds_read_b64 v[24:25], v146 offset:53248
	ds_read_b64 v[28:29], v146 offset:57344
	ds_read_b64 v[32:33], v146 offset:61440
	s_cmp_gt_u32 s6, 3
	s_cselect_b32 s74, 0, 0xffff0000
	v_add_u32_e32 v146, s74, v224
	ds_read_b64 v[22:23], v146 offset:49152
	ds_read_b64 v[26:27], v146 offset:53248
	ds_read_b64 v[30:31], v146 offset:57344
	ds_read_b64 v[34:35], v146 offset:61440
	s_cmp_lg_u32 s4, 0
	s_cbranch_scc1 .Lat844_i0_nomask
	s_cmp_le_u32 s6, 0
	s_cbranch_scc1 .Lat844_i0_nomask
	v_mov_b32_e32 v44, v244
	v_mov_b32_e32 v45, v244
	v_mov_b32_e32 v46, v244
	v_mov_b32_e32 v47, v244
	s_cmp_le_u32 s6, 1
	s_cbranch_scc1 .Lat844_i0_nomask
	v_mov_b32_e32 v48, v244
	v_mov_b32_e32 v49, v244
	v_mov_b32_e32 v50, v244
	v_mov_b32_e32 v51, v244
	s_cmp_le_u32 s6, 2
	s_cbranch_scc1 .Lat844_i0_nomask
	v_mov_b32_e32 v52, v244
	v_mov_b32_e32 v53, v244
	v_mov_b32_e32 v54, v244
	v_mov_b32_e32 v55, v244
	s_cmp_le_u32 s6, 3
	s_cbranch_scc1 .Lat844_i0_nomask
	v_mov_b32_e32 v56, v244
	v_mov_b32_e32 v57, v244
	v_mov_b32_e32 v58, v244
	v_mov_b32_e32 v59, v244
	s_cmp_le_u32 s6, 4
	s_cbranch_scc1 .Lat844_i0_nomask
	v_mov_b32_e32 v60, v244
	v_mov_b32_e32 v61, v244
	v_mov_b32_e32 v62, v244
	v_mov_b32_e32 v63, v244
	s_cmp_le_u32 s6, 5
	s_cbranch_scc1 .Lat844_i0_nomask
	v_mov_b32_e32 v64, v244
	v_mov_b32_e32 v65, v244
	v_mov_b32_e32 v66, v244
	v_mov_b32_e32 v67, v244
	s_cmp_le_u32 s6, 6
	s_cbranch_scc1 .Lat844_i0_nomask
	v_mov_b32_e32 v68, v244
	v_mov_b32_e32 v69, v244
	v_mov_b32_e32 v70, v244
	v_mov_b32_e32 v71, v244
	s_cmp_le_u32 s6, 7
	s_cbranch_scc1 .Lat844_i0_nomask
	v_mov_b32_e32 v72, v244
	v_mov_b32_e32 v73, v244
	v_mov_b32_e32 v74, v244
	v_mov_b32_e32 v75, v244
.Lat844_i0_nomask:
	v_max3_f32 v245, v44, v45, v46
	v_max3_f32 v245, v245, v47, v48
	v_max3_f32 v245, v245, v49, v50
	v_max3_f32 v245, v245, v51, v52
	v_max3_f32 v245, v245, v53, v54
	v_max3_f32 v245, v245, v55, v56
	v_max3_f32 v245, v245, v57, v58
	v_max3_f32 v245, v245, v59, v60
	v_max3_f32 v245, v245, v61, v62
	v_max3_f32 v245, v245, v63, v64
	v_max3_f32 v245, v245, v65, v66
	v_max3_f32 v245, v245, v67, v68
	v_max3_f32 v245, v245, v69, v70
	v_max3_f32 v245, v245, v71, v72
	v_max3_f32 v245, v245, v73, v74
	v_max3_f32 v245, v245, v75, v76
	v_max3_f32 v245, v245, v77, v78
	v_max_f32_e32 v245, v245, v79
	ds_bpermute_b32 v148, v239, v245
	s_waitcnt lgkmcnt(0)
	v_max_f32_e32 v245, v245, v148
	ds_bpermute_b32 v148, v240, v245
	s_waitcnt lgkmcnt(0)
	v_max_f32_e32 v245, v245, v148
	v_sub_f32_e32 v44, v44, v245
	v_sub_f32_e32 v45, v45, v245
	v_sub_f32_e32 v46, v46, v245
	v_sub_f32_e32 v47, v47, v245
	v_exp_f32_e32 v44, v44
	v_exp_f32_e32 v45, v45
	v_exp_f32_e32 v46, v46
	v_exp_f32_e32 v47, v47
	v_sub_f32_e32 v48, v48, v245
	v_sub_f32_e32 v49, v49, v245
	v_sub_f32_e32 v50, v50, v245
	v_sub_f32_e32 v51, v51, v245
	v_exp_f32_e32 v48, v48
	v_exp_f32_e32 v49, v49
	v_exp_f32_e32 v50, v50
	v_exp_f32_e32 v51, v51
	v_mov_b32_e32 v149, v44
	v_mov_b32_e32 v150, v45
	v_mov_b32_e32 v151, v46
	v_mov_b32_e32 v152, v47
	v_cvt_pk_bf16_f32 v44, v44, v45
	v_cvt_pk_bf16_f32 v45, v46, v47
	v_sub_f32_e32 v52, v52, v245
	v_sub_f32_e32 v53, v53, v245
	v_sub_f32_e32 v54, v54, v245
	v_sub_f32_e32 v55, v55, v245
	v_exp_f32_e32 v52, v52
	v_exp_f32_e32 v53, v53
	v_exp_f32_e32 v54, v54
	v_exp_f32_e32 v55, v55
	v_add_f32_e32 v149, v149, v48
	v_add_f32_e32 v150, v150, v49
	v_add_f32_e32 v151, v151, v50
	v_add_f32_e32 v152, v152, v51
	v_cvt_pk_bf16_f32 v46, v48, v49
	v_cvt_pk_bf16_f32 v47, v50, v51
	v_sub_f32_e32 v56, v56, v245
	v_sub_f32_e32 v57, v57, v245
	v_sub_f32_e32 v58, v58, v245
	v_sub_f32_e32 v59, v59, v245
	v_exp_f32_e32 v56, v56
	v_exp_f32_e32 v57, v57
	v_exp_f32_e32 v58, v58
	v_exp_f32_e32 v59, v59
	v_add_f32_e32 v149, v149, v52
	v_add_f32_e32 v150, v150, v53
	v_add_f32_e32 v151, v151, v54
	v_add_f32_e32 v152, v152, v55
	v_cvt_pk_bf16_f32 v52, v52, v53
	v_cvt_pk_bf16_f32 v53, v54, v55
	v_sub_f32_e32 v60, v60, v245
	v_sub_f32_e32 v61, v61, v245
	v_sub_f32_e32 v62, v62, v245
	v_sub_f32_e32 v63, v63, v245
	v_exp_f32_e32 v60, v60
	v_exp_f32_e32 v61, v61
	v_exp_f32_e32 v62, v62
	v_exp_f32_e32 v63, v63
	v_add_f32_e32 v149, v149, v56
	v_add_f32_e32 v150, v150, v57
	v_add_f32_e32 v151, v151, v58
	v_add_f32_e32 v152, v152, v59
	v_cvt_pk_bf16_f32 v54, v56, v57
	v_cvt_pk_bf16_f32 v55, v58, v59
	v_sub_f32_e32 v64, v64, v245
	v_sub_f32_e32 v65, v65, v245
	v_sub_f32_e32 v66, v66, v245
	v_sub_f32_e32 v67, v67, v245
	v_exp_f32_e32 v64, v64
	v_exp_f32_e32 v65, v65
	v_exp_f32_e32 v66, v66
	v_exp_f32_e32 v67, v67
	v_add_f32_e32 v149, v149, v60
	v_add_f32_e32 v150, v150, v61
	v_add_f32_e32 v151, v151, v62
	v_add_f32_e32 v152, v152, v63
	v_cvt_pk_bf16_f32 v60, v60, v61
	v_cvt_pk_bf16_f32 v61, v62, v63
	v_sub_f32_e32 v68, v68, v245
	v_sub_f32_e32 v69, v69, v245
	v_sub_f32_e32 v70, v70, v245
	v_sub_f32_e32 v71, v71, v245
	v_exp_f32_e32 v68, v68
	v_exp_f32_e32 v69, v69
	v_exp_f32_e32 v70, v70
	v_exp_f32_e32 v71, v71
	v_add_f32_e32 v149, v149, v64
	v_add_f32_e32 v150, v150, v65
	v_add_f32_e32 v151, v151, v66
	v_add_f32_e32 v152, v152, v67
	v_cvt_pk_bf16_f32 v62, v64, v65
	v_cvt_pk_bf16_f32 v63, v66, v67
	v_sub_f32_e32 v72, v72, v245
	v_sub_f32_e32 v73, v73, v245
	v_sub_f32_e32 v74, v74, v245
	v_sub_f32_e32 v75, v75, v245
	v_exp_f32_e32 v72, v72
	v_exp_f32_e32 v73, v73
	v_exp_f32_e32 v74, v74
	v_exp_f32_e32 v75, v75
	v_add_f32_e32 v149, v149, v68
	v_add_f32_e32 v150, v150, v69
	v_add_f32_e32 v151, v151, v70
	v_add_f32_e32 v152, v152, v71
	v_cvt_pk_bf16_f32 v68, v68, v69
	v_cvt_pk_bf16_f32 v69, v70, v71
	v_sub_f32_e32 v76, v76, v245
	v_sub_f32_e32 v77, v77, v245
	v_sub_f32_e32 v78, v78, v245
	v_sub_f32_e32 v79, v79, v245
	v_exp_f32_e32 v76, v76
	v_exp_f32_e32 v77, v77
	v_exp_f32_e32 v78, v78
	v_exp_f32_e32 v79, v79
	v_add_f32_e32 v149, v149, v72
	v_add_f32_e32 v150, v150, v73
	v_add_f32_e32 v151, v151, v74
	v_add_f32_e32 v152, v152, v75
	v_cvt_pk_bf16_f32 v70, v72, v73
	v_cvt_pk_bf16_f32 v71, v74, v75
	s_nop 0
	v_add_f32_e32 v149, v149, v76
	v_add_f32_e32 v150, v150, v77
	v_add_f32_e32 v151, v151, v78
	v_add_f32_e32 v152, v152, v79
	v_cvt_pk_bf16_f32 v76, v76, v77
	v_cvt_pk_bf16_f32 v77, v78, v79
	v_mov_b32_e32 v78, 0
	v_mov_b32_e32 v79, 0
	v_add_f32_e32 v149, v149, v150
	v_add_f32_e32 v151, v151, v152
	v_add_f32_e32 v246, v149, v151
	s_waitcnt lgkmcnt(0)
	v_mfma_f32_16x16x32_bf16 v[80:83], v[4:7], v[44:47], 0
	v_mfma_f32_16x16x32_bf16 v[84:87], v[8:11], v[44:47], 0
	v_mfma_f32_16x16x32_bf16 v[88:91], v[12:15], v[44:47], 0
	v_mfma_f32_16x16x32_bf16 v[92:95], v[16:19], v[44:47], 0
	s_cmp_gt_u32 s6, 4
	s_cselect_b32 s74, 0, 0xffff0000
	v_add_u32_e32 v146, s74, v225
	ds_read_b64 v[4:5], v146 offset:49152
	ds_read_b64 v[8:9], v146 offset:53248
	ds_read_b64 v[12:13], v146 offset:57344
	ds_read_b64 v[16:17], v146 offset:61440
	s_cmp_gt_u32 s6, 5
	s_cselect_b32 s74, 0, 0xffff0000
	v_add_u32_e32 v146, s74, v226
	ds_read_b64 v[6:7], v146 offset:49152
	ds_read_b64 v[10:11], v146 offset:53248
	ds_read_b64 v[14:15], v146 offset:57344
	ds_read_b64 v[18:19], v146 offset:61440
	v_mfma_f32_16x16x32_bf16 v[80:83], v[20:23], v[52:55], v[80:83]
	v_mfma_f32_16x16x32_bf16 v[84:87], v[24:27], v[52:55], v[84:87]
	v_mfma_f32_16x16x32_bf16 v[88:91], v[28:31], v[52:55], v[88:91]
	v_mfma_f32_16x16x32_bf16 v[92:95], v[32:35], v[52:55], v[92:95]
	s_cmp_gt_u32 s6, 6
	s_cselect_b32 s74, 0, 0xffff0000
	v_add_u32_e32 v146, s74, v227
	ds_read_b64 v[20:21], v146 offset:49152
	ds_read_b64 v[24:25], v146 offset:53248
	ds_read_b64 v[28:29], v146 offset:57344
	ds_read_b64 v[32:33], v146 offset:61440
	s_cmp_gt_u32 s6, 7
	s_cselect_b32 s74, 0, 0xffff0000
	v_add_u32_e32 v146, s74, v228
	ds_read_b64 v[22:23], v146 offset:49152
	ds_read_b64 v[26:27], v146 offset:53248
	ds_read_b64 v[30:31], v146 offset:57344
	ds_read_b64 v[34:35], v146 offset:61440
	ds_bpermute_b32 v148, v239, v246
	s_waitcnt lgkmcnt(9)
	v_mfma_f32_16x16x32_bf16 v[80:83], v[4:7], v[60:63], v[80:83]
	v_mfma_f32_16x16x32_bf16 v[84:87], v[8:11], v[60:63], v[84:87]
	v_mfma_f32_16x16x32_bf16 v[88:91], v[12:15], v[60:63], v[88:91]
	v_mfma_f32_16x16x32_bf16 v[92:95], v[16:19], v[60:63], v[92:95]
	s_cmp_gt_u32 s6, 8
	s_cselect_b32 s74, 0, 0xffff0000
	v_add_u32_e32 v146, s74, v229
	ds_read_b64 v[4:5], v146 offset:49152
	ds_read_b64 v[8:9], v146 offset:53248
	ds_read_b64 v[12:13], v146 offset:57344
	ds_read_b64 v[16:17], v146 offset:61440
	v_mov_b32_e32 v6, 0
	v_mov_b32_e32 v7, 0
	v_mov_b32_e32 v10, 0
	v_mov_b32_e32 v11, 0
	v_mov_b32_e32 v14, 0
	v_mov_b32_e32 v15, 0
	v_mov_b32_e32 v18, 0
	v_mov_b32_e32 v19, 0
	s_waitcnt lgkmcnt(5)
	v_mfma_f32_16x16x32_bf16 v[80:83], v[20:23], v[68:71], v[80:83]
	v_mfma_f32_16x16x32_bf16 v[84:87], v[24:27], v[68:71], v[84:87]
	v_mfma_f32_16x16x32_bf16 v[88:91], v[28:31], v[68:71], v[88:91]
	v_mfma_f32_16x16x32_bf16 v[92:95], v[32:35], v[68:71], v[92:95]
	s_waitcnt lgkmcnt(0)
	v_add_f32_e32 v246, v246, v148
	s_nop 0
	v_mfma_f32_16x16x32_bf16 v[80:83], v[4:7], v[76:79], v[80:83]
	v_mfma_f32_16x16x32_bf16 v[84:87], v[8:11], v[76:79], v[84:87]
	v_mfma_f32_16x16x32_bf16 v[88:91], v[12:15], v[76:79], v[88:91]
	v_mfma_f32_16x16x32_bf16 v[92:95], v[16:19], v[76:79], v[92:95]
	ds_bpermute_b32 v148, v240, v246
	s_waitcnt lgkmcnt(0)
	v_add_f32_e32 v246, v246, v148
	v_rcp_f32_e32 v149, v246
	v_log_f32_e32 v150, v246
	s_nop 0
	v_add_f32_e32 v151, v245, v150
	v_mul_f32_e32 v151, 0x3f317218, v151
	v_max_f32_e32 v152, v120, v151
	v_sub_f32_e32 v153, v120, v152
	v_sub_f32_e32 v154, v151, v152
	v_mul_f32_e32 v153, 0x3fb8aa3b, v153
	v_mul_f32_e32 v154, 0x3fb8aa3b, v154
	v_exp_f32_e32 v153, v153
	v_exp_f32_e32 v154, v154
	s_nop 0
	v_add_f32_e32 v155, v153, v154
	v_rcp_f32_e32 v146, v155
	v_log_f32_e32 v150, v155
	s_nop 0
	v_mul_f32_e32 v154, v154, v146
	v_mul_f32_e32 v146, v153, v146
	v_mul_f32_e32 v147, v149, v154
	v_mul_f32_e32 v150, 0x3f317218, v150
	v_add_f32_e32 v140, v152, v150
	v_mul_f32_e32 v80, v80, v147
	v_mul_f32_e32 v81, v81, v147
	v_mul_f32_e32 v82, v82, v147
	v_mul_f32_e32 v83, v83, v147
	v_mul_f32_e32 v84, v84, v147
	v_mul_f32_e32 v85, v85, v147
	v_mul_f32_e32 v86, v86, v147
	v_mul_f32_e32 v87, v87, v147
	v_mul_f32_e32 v88, v88, v147
	v_mul_f32_e32 v89, v89, v147
	v_mul_f32_e32 v90, v90, v147
	v_mul_f32_e32 v91, v91, v147
	v_mul_f32_e32 v92, v92, v147
	v_mul_f32_e32 v93, v93, v147
	v_mul_f32_e32 v94, v94, v147
	v_mul_f32_e32 v95, v95, v147
	v_lshlrev_b32_e32 v141, 16, v112
	v_and_b32_e32 v142, 0xffff0000, v112
	v_lshlrev_b32_e32 v143, 16, v113
	v_and_b32_e32 v144, 0xffff0000, v113
	v_fmac_f32_e32 v80, v146, v141
	v_fmac_f32_e32 v81, v146, v142
	v_fmac_f32_e32 v82, v146, v143
	v_fmac_f32_e32 v83, v146, v144
	v_cvt_pk_bf16_f32 v132, v80, v81
	v_cvt_pk_bf16_f32 v133, v82, v83
	v_lshlrev_b32_e32 v141, 16, v114
	v_and_b32_e32 v142, 0xffff0000, v114
	v_lshlrev_b32_e32 v143, 16, v115
	v_and_b32_e32 v144, 0xffff0000, v115
	v_fmac_f32_e32 v84, v146, v141
	v_fmac_f32_e32 v85, v146, v142
	v_fmac_f32_e32 v86, v146, v143
	v_fmac_f32_e32 v87, v146, v144
	v_cvt_pk_bf16_f32 v134, v84, v85
	v_cvt_pk_bf16_f32 v135, v86, v87
	v_lshlrev_b32_e32 v141, 16, v116
	v_and_b32_e32 v142, 0xffff0000, v116
	v_lshlrev_b32_e32 v143, 16, v117
	v_and_b32_e32 v144, 0xffff0000, v117
	v_fmac_f32_e32 v88, v146, v141
	v_fmac_f32_e32 v89, v146, v142
	v_fmac_f32_e32 v90, v146, v143
	v_fmac_f32_e32 v91, v146, v144
	v_cvt_pk_bf16_f32 v136, v88, v89
	v_cvt_pk_bf16_f32 v137, v90, v91
	v_lshlrev_b32_e32 v141, 16, v118
	v_and_b32_e32 v142, 0xffff0000, v118
	v_lshlrev_b32_e32 v143, 16, v119
	v_and_b32_e32 v144, 0xffff0000, v119
	v_fmac_f32_e32 v92, v146, v141
	v_fmac_f32_e32 v93, v146, v142
	v_fmac_f32_e32 v94, v146, v143
	v_fmac_f32_e32 v95, v146, v144
	v_cvt_pk_bf16_f32 v138, v92, v93
	v_cvt_pk_bf16_f32 v139, v94, v95
	s_mov_b64 s[26:27], s[86:87]
	s_mov_b64 s[28:29], s[88:89]
	s_mov_b64 s[86:87], s[12:13]
	s_mov_b64 s[88:89], s[14:15]
	s_mov_b32 s4, s83
	s_mov_b32 s5, s84
	s_waitcnt vmcnt(0)
	s_barrier
	ds_read_b128 v[4:7], v230 offset:0
	ds_read_b128 v[8:11], v231 offset:0
	ds_read_b128 v[12:15], v230 offset:2048
	ds_read_b128 v[16:19], v231 offset:2048
	ds_read_b128 v[20:23], v230 offset:4096
	ds_read_b128 v[24:27], v231 offset:4096
	ds_read_b128 v[28:31], v230 offset:6144
	ds_read_b128 v[32:35], v231 offset:6144
	ds_read_b128 v[36:39], v230 offset:8192
	ds_read_b128 v[40:43], v231 offset:8192
	global_store_dwordx2 v237, v[132:133], s[26:27]
	global_store_dwordx2 v237, v[134:135], s[26:27] offset:32
	global_store_dwordx2 v237, v[136:137], s[26:27] offset:64
	global_store_dwordx2 v237, v[138:139], s[26:27] offset:96
	s_mov_b64 s[90:91], exec
	s_mov_b64 exec, 0xffff
	global_store_dword v238, v140, s[28:29]
	s_mov_b64 exec, s[90:91]
	s_add_u32 s83, s4, 1
	s_mov_b32 s84, s5
	s_mul_i32 s74, s84, 1024
	s_lshl_b32 s75, s83, 7
	s_add_u32 s74, s74, s75
	s_lshl_b32 s75, s74, 7
	s_add_u32 s16, s60, s75
	s_addc_u32 s17, s61, 0
	s_lshl_b32 s75, s74, 1
	s_add_u32 s24, s64, s75
	s_addc_u32 s25, s65, 0
	s_add_u32 m0, s70, 0x8000
	s_nop 0
	global_load_lds_dwordx4 v232, s[16:17] nt
	s_add_u32 m0, s70, 0xa000
	s_nop 0
	global_load_lds_dwordx4 v233, s[16:17] nt
	s_add_u32 m0, s70, 0x18000
	s_nop 0
	global_load_lds_dwordx4 v234, s[24:25] nt
	s_add_u32 m0, s70, 0x1a000
	s_nop 0
	global_load_lds_dwordx4 v235, s[24:25] nt
	s_lshl_b32 s74, s83, 9
	s_add_u32 s74, s74, s84
	s_lshl_b32 s75, s74, 7
	s_add_u32 s10, s30, s75
	s_addc_u32 s11, s31, 0
	s_add_u32 s12, s34, s75
	s_addc_u32 s13, s35, 0
	s_lshl_b32 s75, s74, 2
	s_add_u32 s14, s58, s75
	s_addc_u32 s15, s59, 0
	global_load_dwordx4 v[96:99], v236, s[10:11]
	global_load_dwordx4 v[100:103], v236, s[10:11] offset:64
	global_load_dwordx2 v[112:113], v237, s[12:13]
	global_load_dwordx2 v[114:115], v237, s[12:13] offset:32
	global_load_dwordx2 v[116:117], v237, s[12:13] offset:64
	global_load_dwordx2 v[118:119], v237, s[12:13] offset:96
	global_load_dword v120, v238, s[14:15]
	s_waitcnt lgkmcnt(0)
	v_mfma_f32_16x16x32_bf16 v[44:47], v[4:7], v[104:107], 0
	v_mfma_f32_16x16x32_bf16 v[48:51], v[12:15], v[104:107], 0
	v_mfma_f32_16x16x32_bf16 v[52:55], v[20:23], v[104:107], 0
	v_mfma_f32_16x16x32_bf16 v[56:59], v[28:31], v[104:107], 0
	v_mfma_f32_16x16x32_bf16 v[60:63], v[36:39], v[104:107], 0
	v_mfma_f32_16x16x32_bf16 v[44:47], v[8:11], v[108:111], v[44:47]
	v_mfma_f32_16x16x32_bf16 v[48:51], v[16:19], v[108:111], v[48:51]
	v_mfma_f32_16x16x32_bf16 v[52:55], v[24:27], v[108:111], v[52:55]
	v_mfma_f32_16x16x32_bf16 v[56:59], v[32:35], v[108:111], v[56:59]
	v_mfma_f32_16x16x32_bf16 v[60:63], v[40:43], v[108:111], v[60:63]
	ds_read_b128 v[4:7], v230 offset:10240
	ds_read_b128 v[8:11], v231 offset:10240
	ds_read_b128 v[12:15], v230 offset:12288
	ds_read_b128 v[16:19], v231 offset:12288
	ds_read_b128 v[20:23], v230 offset:14336
	ds_read_b128 v[24:27], v231 offset:14336
	ds_read_b128 v[28:31], v230 offset:16384
	ds_read_b128 v[32:35], v231 offset:16384
	s_nop 1
	v_fma_f32 v44, v44, s79, v185
	v_fma_f32 v45, v45, s79, v186
	v_fma_f32 v46, v46, s79, v187
	v_fma_f32 v47, v47, s79, v188
	v_fma_f32 v48, v48, s79, v189
	v_fma_f32 v49, v49, s79, v190
	v_fma_f32 v50, v50, s79, v191
	v_fma_f32 v51, v51, s79, v192
	v_fma_f32 v52, v52, s79, v193
	v_fma_f32 v53, v53, s79, v194
	v_fma_f32 v54, v54, s79, v195
	v_fma_f32 v55, v55, s79, v196
	v_fma_f32 v56, v56, s79, v197
	v_fma_f32 v57, v57, s79, v198
	v_fma_f32 v58, v58, s79, v199
	v_fma_f32 v59, v59, s79, v200
	v_fma_f32 v60, v60, s79, v201
	v_fma_f32 v61, v61, s79, v202
	v_fma_f32 v62, v62, s79, v203
	v_fma_f32 v63, v63, s79, v204
	s_waitcnt lgkmcnt(0)
	v_mfma_f32_16x16x32_bf16 v[64:67], v[4:7], v[104:107], 0
	v_mfma_f32_16x16x32_bf16 v[68:71], v[12:15], v[104:107], 0
	v_mfma_f32_16x16x32_bf16 v[72:75], v[20:23], v[104:107], 0
	v_mfma_f32_16x16x32_bf16 v[76:79], v[28:31], v[104:107], 0
	v_mfma_f32_16x16x32_bf16 v[64:67], v[8:11], v[108:111], v[64:67]
	v_mfma_f32_16x16x32_bf16 v[68:71], v[16:19], v[108:111], v[68:71]
	v_mfma_f32_16x16x32_bf16 v[72:75], v[24:27], v[108:111], v[72:75]
	v_mfma_f32_16x16x32_bf16 v[76:79], v[32:35], v[108:111], v[76:79]
	ds_read_b64 v[4:5], v221 offset:0
	ds_read_b64 v[8:9], v221 offset:4096
	ds_read_b64 v[12:13], v221 offset:8192
	ds_read_b64 v[16:17], v221 offset:12288
	ds_read_b64 v[6:7], v222 offset:0
	ds_read_b64 v[10:11], v222 offset:4096
	ds_read_b64 v[14:15], v222 offset:8192
	ds_read_b64 v[18:19], v222 offset:12288
	s_nop 1
	v_fma_f32 v64, v64, s79, v205
	v_fma_f32 v65, v65, s79, v206
	v_fma_f32 v66, v66, s79, v207
	v_fma_f32 v67, v67, s79, v208
	v_fma_f32 v68, v68, s79, v209
	v_fma_f32 v69, v69, s79, v210
	v_fma_f32 v70, v70, s79, v211
	v_fma_f32 v71, v71, s79, v212
	v_fma_f32 v72, v72, s79, v213
	v_fma_f32 v73, v73, s79, v214
	v_fma_f32 v74, v74, s79, v215
	v_fma_f32 v75, v75, s79, v216
	v_fma_f32 v76, v76, s79, v217
	v_fma_f32 v77, v77, s79, v218
	v_fma_f32 v78, v78, s79, v219
	v_fma_f32 v79, v79, s79, v220
	ds_read_b64 v[20:21], v223 offset:0
	ds_read_b64 v[24:25], v223 offset:4096
	ds_read_b64 v[28:29], v223 offset:8192
	ds_read_b64 v[32:33], v223 offset:12288
	ds_read_b64 v[22:23], v224 offset:0
	ds_read_b64 v[26:27], v224 offset:4096
	ds_read_b64 v[30:31], v224 offset:8192
	ds_read_b64 v[34:35], v224 offset:12288
	s_cmp_lg_u32 s4, 0
	s_cbranch_scc1 .Lat844_i1_nomask
	s_cmp_le_u32 s6, 0
	s_cbranch_scc1 .Lat844_i1_nomask
	v_mov_b32_e32 v44, v244
	v_mov_b32_e32 v45, v244
	v_mov_b32_e32 v46, v244
	v_mov_b32_e32 v47, v244
	s_cmp_le_u32 s6, 1
	s_cbranch_scc1 .Lat844_i1_nomask
	v_mov_b32_e32 v48, v244
	v_mov_b32_e32 v49, v244
	v_mov_b32_e32 v50, v244
	v_mov_b32_e32 v51, v244
	s_cmp_le_u32 s6, 2
	s_cbranch_scc1 .Lat844_i1_nomask
	v_mov_b32_e32 v52, v244
	v_mov_b32_e32 v53, v244
	v_mov_b32_e32 v54, v244
	v_mov_b32_e32 v55, v244
	s_cmp_le_u32 s6, 3
	s_cbranch_scc1 .Lat844_i1_nomask
	v_mov_b32_e32 v56, v244
	v_mov_b32_e32 v57, v244
	v_mov_b32_e32 v58, v244
	v_mov_b32_e32 v59, v244
	s_cmp_le_u32 s6, 4
	s_cbranch_scc1 .Lat844_i1_nomask
	v_mov_b32_e32 v60, v244
	v_mov_b32_e32 v61, v244
	v_mov_b32_e32 v62, v244
	v_mov_b32_e32 v63, v244
	s_cmp_le_u32 s6, 5
	s_cbranch_scc1 .Lat844_i1_nomask
	v_mov_b32_e32 v64, v244
	v_mov_b32_e32 v65, v244
	v_mov_b32_e32 v66, v244
	v_mov_b32_e32 v67, v244
	s_cmp_le_u32 s6, 6
	s_cbranch_scc1 .Lat844_i1_nomask
	v_mov_b32_e32 v68, v244
	v_mov_b32_e32 v69, v244
	v_mov_b32_e32 v70, v244
	v_mov_b32_e32 v71, v244
	s_cmp_le_u32 s6, 7
	s_cbranch_scc1 .Lat844_i1_nomask
	v_mov_b32_e32 v72, v244
	v_mov_b32_e32 v73, v244
	v_mov_b32_e32 v74, v244
	v_mov_b32_e32 v75, v244
.Lat844_i1_nomask:
	v_max3_f32 v245, v44, v45, v46
	v_max3_f32 v245, v245, v47, v48
	v_max3_f32 v245, v245, v49, v50
	v_max3_f32 v245, v245, v51, v52
	v_max3_f32 v245, v245, v53, v54
	v_max3_f32 v245, v245, v55, v56
	v_max3_f32 v245, v245, v57, v58
	v_max3_f32 v245, v245, v59, v60
	v_max3_f32 v245, v245, v61, v62
	v_max3_f32 v245, v245, v63, v64
	v_max3_f32 v245, v245, v65, v66
	v_max3_f32 v245, v245, v67, v68
	v_max3_f32 v245, v245, v69, v70
	v_max3_f32 v245, v245, v71, v72
	v_max3_f32 v245, v245, v73, v74
	v_max3_f32 v245, v245, v75, v76
	v_max3_f32 v245, v245, v77, v78
	v_max_f32_e32 v245, v245, v79
	ds_bpermute_b32 v148, v239, v245
	s_waitcnt lgkmcnt(0)
	v_max_f32_e32 v245, v245, v148
	ds_bpermute_b32 v148, v240, v245
	s_waitcnt lgkmcnt(0)
	v_max_f32_e32 v245, v245, v148
	v_sub_f32_e32 v44, v44, v245
	v_sub_f32_e32 v45, v45, v245
	v_sub_f32_e32 v46, v46, v245
	v_sub_f32_e32 v47, v47, v245
	v_exp_f32_e32 v44, v44
	v_exp_f32_e32 v45, v45
	v_exp_f32_e32 v46, v46
	v_exp_f32_e32 v47, v47
	v_sub_f32_e32 v48, v48, v245
	v_sub_f32_e32 v49, v49, v245
	v_sub_f32_e32 v50, v50, v245
	v_sub_f32_e32 v51, v51, v245
	v_exp_f32_e32 v48, v48
	v_exp_f32_e32 v49, v49
	v_exp_f32_e32 v50, v50
	v_exp_f32_e32 v51, v51
	v_mov_b32_e32 v149, v44
	v_mov_b32_e32 v150, v45
	v_mov_b32_e32 v151, v46
	v_mov_b32_e32 v152, v47
	v_cvt_pk_bf16_f32 v44, v44, v45
	v_cvt_pk_bf16_f32 v45, v46, v47
	v_sub_f32_e32 v52, v52, v245
	v_sub_f32_e32 v53, v53, v245
	v_sub_f32_e32 v54, v54, v245
	v_sub_f32_e32 v55, v55, v245
	v_exp_f32_e32 v52, v52
	v_exp_f32_e32 v53, v53
	v_exp_f32_e32 v54, v54
	v_exp_f32_e32 v55, v55
	v_add_f32_e32 v149, v149, v48
	v_add_f32_e32 v150, v150, v49
	v_add_f32_e32 v151, v151, v50
	v_add_f32_e32 v152, v152, v51
	v_cvt_pk_bf16_f32 v46, v48, v49
	v_cvt_pk_bf16_f32 v47, v50, v51
	v_sub_f32_e32 v56, v56, v245
	v_sub_f32_e32 v57, v57, v245
	v_sub_f32_e32 v58, v58, v245
	v_sub_f32_e32 v59, v59, v245
	v_exp_f32_e32 v56, v56
	v_exp_f32_e32 v57, v57
	v_exp_f32_e32 v58, v58
	v_exp_f32_e32 v59, v59
	v_add_f32_e32 v149, v149, v52
	v_add_f32_e32 v150, v150, v53
	v_add_f32_e32 v151, v151, v54
	v_add_f32_e32 v152, v152, v55
	v_cvt_pk_bf16_f32 v52, v52, v53
	v_cvt_pk_bf16_f32 v53, v54, v55
	v_sub_f32_e32 v60, v60, v245
	v_sub_f32_e32 v61, v61, v245
	v_sub_f32_e32 v62, v62, v245
	v_sub_f32_e32 v63, v63, v245
	v_exp_f32_e32 v60, v60
	v_exp_f32_e32 v61, v61
	v_exp_f32_e32 v62, v62
	v_exp_f32_e32 v63, v63
	v_add_f32_e32 v149, v149, v56
	v_add_f32_e32 v150, v150, v57
	v_add_f32_e32 v151, v151, v58
	v_add_f32_e32 v152, v152, v59
	v_cvt_pk_bf16_f32 v54, v56, v57
	v_cvt_pk_bf16_f32 v55, v58, v59
	v_sub_f32_e32 v64, v64, v245
	v_sub_f32_e32 v65, v65, v245
	v_sub_f32_e32 v66, v66, v245
	v_sub_f32_e32 v67, v67, v245
	v_exp_f32_e32 v64, v64
	v_exp_f32_e32 v65, v65
	v_exp_f32_e32 v66, v66
	v_exp_f32_e32 v67, v67
	v_add_f32_e32 v149, v149, v60
	v_add_f32_e32 v150, v150, v61
	v_add_f32_e32 v151, v151, v62
	v_add_f32_e32 v152, v152, v63
	v_cvt_pk_bf16_f32 v60, v60, v61
	v_cvt_pk_bf16_f32 v61, v62, v63
	v_sub_f32_e32 v68, v68, v245
	v_sub_f32_e32 v69, v69, v245
	v_sub_f32_e32 v70, v70, v245
	v_sub_f32_e32 v71, v71, v245
	v_exp_f32_e32 v68, v68
	v_exp_f32_e32 v69, v69
	v_exp_f32_e32 v70, v70
	v_exp_f32_e32 v71, v71
	v_add_f32_e32 v149, v149, v64
	v_add_f32_e32 v150, v150, v65
	v_add_f32_e32 v151, v151, v66
	v_add_f32_e32 v152, v152, v67
	v_cvt_pk_bf16_f32 v62, v64, v65
	v_cvt_pk_bf16_f32 v63, v66, v67
	v_sub_f32_e32 v72, v72, v245
	v_sub_f32_e32 v73, v73, v245
	v_sub_f32_e32 v74, v74, v245
	v_sub_f32_e32 v75, v75, v245
	v_exp_f32_e32 v72, v72
	v_exp_f32_e32 v73, v73
	v_exp_f32_e32 v74, v74
	v_exp_f32_e32 v75, v75
	v_add_f32_e32 v149, v149, v68
	v_add_f32_e32 v150, v150, v69
	v_add_f32_e32 v151, v151, v70
	v_add_f32_e32 v152, v152, v71
	v_cvt_pk_bf16_f32 v68, v68, v69
	v_cvt_pk_bf16_f32 v69, v70, v71
	v_sub_f32_e32 v76, v76, v245
	v_sub_f32_e32 v77, v77, v245
	v_sub_f32_e32 v78, v78, v245
	v_sub_f32_e32 v79, v79, v245
	v_exp_f32_e32 v76, v76
	v_exp_f32_e32 v77, v77
	v_exp_f32_e32 v78, v78
	v_exp_f32_e32 v79, v79
	v_add_f32_e32 v149, v149, v72
	v_add_f32_e32 v150, v150, v73
	v_add_f32_e32 v151, v151, v74
	v_add_f32_e32 v152, v152, v75
	v_cvt_pk_bf16_f32 v70, v72, v73
	v_cvt_pk_bf16_f32 v71, v74, v75
	s_nop 0
	v_add_f32_e32 v149, v149, v76
	v_add_f32_e32 v150, v150, v77
	v_add_f32_e32 v151, v151, v78
	v_add_f32_e32 v152, v152, v79
	v_cvt_pk_bf16_f32 v76, v76, v77
	v_cvt_pk_bf16_f32 v77, v78, v79
	v_mov_b32_e32 v78, 0
	v_mov_b32_e32 v79, 0
	v_add_f32_e32 v149, v149, v150
	v_add_f32_e32 v151, v151, v152
	v_add_f32_e32 v246, v149, v151
	s_waitcnt lgkmcnt(0)
	v_mfma_f32_16x16x32_bf16 v[80:83], v[4:7], v[44:47], 0
	v_mfma_f32_16x16x32_bf16 v[84:87], v[8:11], v[44:47], 0
	v_mfma_f32_16x16x32_bf16 v[88:91], v[12:15], v[44:47], 0
	v_mfma_f32_16x16x32_bf16 v[92:95], v[16:19], v[44:47], 0
	ds_read_b64 v[4:5], v225 offset:0
	ds_read_b64 v[8:9], v225 offset:4096
	ds_read_b64 v[12:13], v225 offset:8192
	ds_read_b64 v[16:17], v225 offset:12288
	ds_read_b64 v[6:7], v226 offset:0
	ds_read_b64 v[10:11], v226 offset:4096
	ds_read_b64 v[14:15], v226 offset:8192
	ds_read_b64 v[18:19], v226 offset:12288
	v_mfma_f32_16x16x32_bf16 v[80:83], v[20:23], v[52:55], v[80:83]
	v_mfma_f32_16x16x32_bf16 v[84:87], v[24:27], v[52:55], v[84:87]
	v_mfma_f32_16x16x32_bf16 v[88:91], v[28:31], v[52:55], v[88:91]
	v_mfma_f32_16x16x32_bf16 v[92:95], v[32:35], v[52:55], v[92:95]
	ds_read_b64 v[20:21], v227 offset:0
	ds_read_b64 v[24:25], v227 offset:4096
	ds_read_b64 v[28:29], v227 offset:8192
	ds_read_b64 v[32:33], v227 offset:12288
	ds_read_b64 v[22:23], v228 offset:0
	ds_read_b64 v[26:27], v228 offset:4096
	ds_read_b64 v[30:31], v228 offset:8192
	ds_read_b64 v[34:35], v228 offset:12288
	ds_bpermute_b32 v148, v239, v246
	s_waitcnt lgkmcnt(9)
	v_mfma_f32_16x16x32_bf16 v[80:83], v[4:7], v[60:63], v[80:83]
	v_mfma_f32_16x16x32_bf16 v[84:87], v[8:11], v[60:63], v[84:87]
	v_mfma_f32_16x16x32_bf16 v[88:91], v[12:15], v[60:63], v[88:91]
	v_mfma_f32_16x16x32_bf16 v[92:95], v[16:19], v[60:63], v[92:95]
	ds_read_b64 v[4:5], v229 offset:0
	ds_read_b64 v[8:9], v229 offset:4096
	ds_read_b64 v[12:13], v229 offset:8192
	ds_read_b64 v[16:17], v229 offset:12288
	v_mov_b32_e32 v6, 0
	v_mov_b32_e32 v7, 0
	v_mov_b32_e32 v10, 0
	v_mov_b32_e32 v11, 0
	v_mov_b32_e32 v14, 0
	v_mov_b32_e32 v15, 0
	v_mov_b32_e32 v18, 0
	v_mov_b32_e32 v19, 0
	s_waitcnt lgkmcnt(5)
	v_mfma_f32_16x16x32_bf16 v[80:83], v[20:23], v[68:71], v[80:83]
	v_mfma_f32_16x16x32_bf16 v[84:87], v[24:27], v[68:71], v[84:87]
	v_mfma_f32_16x16x32_bf16 v[88:91], v[28:31], v[68:71], v[88:91]
	v_mfma_f32_16x16x32_bf16 v[92:95], v[32:35], v[68:71], v[92:95]
	s_waitcnt lgkmcnt(0)
	v_add_f32_e32 v246, v246, v148
	s_nop 0
	v_mfma_f32_16x16x32_bf16 v[80:83], v[4:7], v[76:79], v[80:83]
	v_mfma_f32_16x16x32_bf16 v[84:87], v[8:11], v[76:79], v[84:87]
	v_mfma_f32_16x16x32_bf16 v[88:91], v[12:15], v[76:79], v[88:91]
	v_mfma_f32_16x16x32_bf16 v[92:95], v[16:19], v[76:79], v[92:95]
	ds_bpermute_b32 v148, v240, v246
	s_waitcnt lgkmcnt(0)
	v_add_f32_e32 v246, v246, v148
	v_rcp_f32_e32 v149, v246
	v_log_f32_e32 v150, v246
	s_nop 0
	v_add_f32_e32 v151, v245, v150
	v_mul_f32_e32 v151, 0x3f317218, v151
	v_max_f32_e32 v152, v121, v151
	v_sub_f32_e32 v153, v121, v152
	v_sub_f32_e32 v154, v151, v152
	v_mul_f32_e32 v153, 0x3fb8aa3b, v153
	v_mul_f32_e32 v154, 0x3fb8aa3b, v154
	v_exp_f32_e32 v153, v153
	v_exp_f32_e32 v154, v154
	s_nop 0
	v_add_f32_e32 v155, v153, v154
	v_rcp_f32_e32 v146, v155
	v_log_f32_e32 v150, v155
	s_nop 0
	v_mul_f32_e32 v154, v154, v146
	v_mul_f32_e32 v146, v153, v146
	v_mul_f32_e32 v147, v149, v154
	v_mul_f32_e32 v150, 0x3f317218, v150
	v_add_f32_e32 v140, v152, v150
	v_mul_f32_e32 v80, v80, v147
	v_mul_f32_e32 v81, v81, v147
	v_mul_f32_e32 v82, v82, v147
	v_mul_f32_e32 v83, v83, v147
	v_mul_f32_e32 v84, v84, v147
	v_mul_f32_e32 v85, v85, v147
	v_mul_f32_e32 v86, v86, v147
	v_mul_f32_e32 v87, v87, v147
	v_mul_f32_e32 v88, v88, v147
	v_mul_f32_e32 v89, v89, v147
	v_mul_f32_e32 v90, v90, v147
	v_mul_f32_e32 v91, v91, v147
	v_mul_f32_e32 v92, v92, v147
	v_mul_f32_e32 v93, v93, v147
	v_mul_f32_e32 v94, v94, v147
	v_mul_f32_e32 v95, v95, v147
	v_lshlrev_b32_e32 v141, 16, v122
	v_and_b32_e32 v142, 0xffff0000, v122
	v_lshlrev_b32_e32 v143, 16, v123
	v_and_b32_e32 v144, 0xffff0000, v123
	v_fmac_f32_e32 v80, v146, v141
	v_fmac_f32_e32 v81, v146, v142
	v_fmac_f32_e32 v82, v146, v143
	v_fmac_f32_e32 v83, v146, v144
	v_cvt_pk_bf16_f32 v132, v80, v81
	v_cvt_pk_bf16_f32 v133, v82, v83
	v_lshlrev_b32_e32 v141, 16, v124
	v_and_b32_e32 v142, 0xffff0000, v124
	v_lshlrev_b32_e32 v143, 16, v125
	v_and_b32_e32 v144, 0xffff0000, v125
	v_fmac_f32_e32 v84, v146, v141
	v_fmac_f32_e32 v85, v146, v142
	v_fmac_f32_e32 v86, v146, v143
	v_fmac_f32_e32 v87, v146, v144
	v_cvt_pk_bf16_f32 v134, v84, v85
	v_cvt_pk_bf16_f32 v135, v86, v87
	v_lshlrev_b32_e32 v141, 16, v126
	v_and_b32_e32 v142, 0xffff0000, v126
	v_lshlrev_b32_e32 v143, 16, v127
	v_and_b32_e32 v144, 0xffff0000, v127
	v_fmac_f32_e32 v88, v146, v141
	v_fmac_f32_e32 v89, v146, v142
	v_fmac_f32_e32 v90, v146, v143
	v_fmac_f32_e32 v91, v146, v144
	v_cvt_pk_bf16_f32 v136, v88, v89
	v_cvt_pk_bf16_f32 v137, v90, v91
	v_lshlrev_b32_e32 v141, 16, v128
	v_and_b32_e32 v142, 0xffff0000, v128
	v_lshlrev_b32_e32 v143, 16, v129
	v_and_b32_e32 v144, 0xffff0000, v129
	v_fmac_f32_e32 v92, v146, v141
	v_fmac_f32_e32 v93, v146, v142
	v_fmac_f32_e32 v94, v146, v143
	v_fmac_f32_e32 v95, v146, v144
	v_cvt_pk_bf16_f32 v138, v92, v93
	v_cvt_pk_bf16_f32 v139, v94, v95
	s_mov_b64 s[26:27], s[86:87]
	s_mov_b64 s[28:29], s[88:89]
	s_mov_b64 s[86:87], s[12:13]
	s_mov_b64 s[88:89], s[14:15]
	s_mov_b32 s4, s83
	s_mov_b32 s5, s84
	s_waitcnt vmcnt(0)
	s_barrier
	ds_read_b128 v[4:7], v230 offset:16384
	ds_read_b128 v[8:11], v231 offset:16384
	ds_read_b128 v[12:15], v230 offset:18432
	ds_read_b128 v[16:19], v231 offset:18432
	ds_read_b128 v[20:23], v230 offset:20480
	ds_read_b128 v[24:27], v231 offset:20480
	ds_read_b128 v[28:31], v230 offset:22528
	ds_read_b128 v[32:35], v231 offset:22528
	ds_read_b128 v[36:39], v230 offset:24576
	ds_read_b128 v[40:43], v231 offset:24576
	global_store_dwordx2 v237, v[132:133], s[26:27]
	global_store_dwordx2 v237, v[134:135], s[26:27] offset:32
	global_store_dwordx2 v237, v[136:137], s[26:27] offset:64
	global_store_dwordx2 v237, v[138:139], s[26:27] offset:96
	s_mov_b64 s[90:91], exec
	s_mov_b64 exec, 0xffff
	global_store_dword v238, v140, s[28:29]
	s_mov_b64 exec, s[90:91]
	s_add_u32 s83, s4, 1
	s_mov_b32 s84, s5
	s_mul_i32 s74, s84, 1024
	s_lshl_b32 s75, s83, 7
	s_add_u32 s74, s74, s75
	s_lshl_b32 s75, s74, 7
	s_add_u32 s16, s60, s75
	s_addc_u32 s17, s61, 0
	s_lshl_b32 s75, s74, 1
	s_add_u32 s24, s64, s75
	s_addc_u32 s25, s65, 0
	s_add_u32 m0, s70, 0xc000
	s_nop 0
	global_load_lds_dwordx4 v232, s[16:17] nt
	s_add_u32 m0, s70, 0xe000
	s_nop 0
	global_load_lds_dwordx4 v233, s[16:17] nt
	s_add_u32 m0, s70, 0x1c000
	s_nop 0
	global_load_lds_dwordx4 v234, s[24:25] nt
	s_add_u32 m0, s70, 0x1e000
	s_nop 0
	global_load_lds_dwordx4 v235, s[24:25] nt
	s_lshl_b32 s74, s83, 9
	s_add_u32 s74, s74, s84
	s_lshl_b32 s75, s74, 7
	s_add_u32 s10, s30, s75
	s_addc_u32 s11, s31, 0
	s_add_u32 s12, s34, s75
	s_addc_u32 s13, s35, 0
	s_lshl_b32 s75, s74, 2
	s_add_u32 s14, s58, s75
	s_addc_u32 s15, s59, 0
	global_load_dwordx4 v[104:107], v236, s[10:11]
	global_load_dwordx4 v[108:111], v236, s[10:11] offset:64
	global_load_dwordx2 v[122:123], v237, s[12:13]
	global_load_dwordx2 v[124:125], v237, s[12:13] offset:32
	global_load_dwordx2 v[126:127], v237, s[12:13] offset:64
	global_load_dwordx2 v[128:129], v237, s[12:13] offset:96
	global_load_dword v121, v238, s[14:15]
	s_waitcnt lgkmcnt(0)
	v_mfma_f32_16x16x32_bf16 v[44:47], v[4:7], v[96:99], 0
	v_mfma_f32_16x16x32_bf16 v[48:51], v[12:15], v[96:99], 0
	v_mfma_f32_16x16x32_bf16 v[52:55], v[20:23], v[96:99], 0
	v_mfma_f32_16x16x32_bf16 v[56:59], v[28:31], v[96:99], 0
	v_mfma_f32_16x16x32_bf16 v[60:63], v[36:39], v[96:99], 0
	v_mfma_f32_16x16x32_bf16 v[44:47], v[8:11], v[100:103], v[44:47]
	v_mfma_f32_16x16x32_bf16 v[48:51], v[16:19], v[100:103], v[48:51]
	v_mfma_f32_16x16x32_bf16 v[52:55], v[24:27], v[100:103], v[52:55]
	v_mfma_f32_16x16x32_bf16 v[56:59], v[32:35], v[100:103], v[56:59]
	v_mfma_f32_16x16x32_bf16 v[60:63], v[40:43], v[100:103], v[60:63]
	ds_read_b128 v[4:7], v230 offset:26624
	ds_read_b128 v[8:11], v231 offset:26624
	ds_read_b128 v[12:15], v230 offset:28672
	ds_read_b128 v[16:19], v231 offset:28672
	ds_read_b128 v[20:23], v230 offset:30720
	ds_read_b128 v[24:27], v231 offset:30720
	ds_read_b128 v[28:31], v230 offset:32768
	ds_read_b128 v[32:35], v231 offset:32768
	s_nop 1
	v_fma_f32 v44, v44, s79, v185
	v_fma_f32 v45, v45, s79, v186
	v_fma_f32 v46, v46, s79, v187
	v_fma_f32 v47, v47, s79, v188
	v_fma_f32 v48, v48, s79, v189
	v_fma_f32 v49, v49, s79, v190
	v_fma_f32 v50, v50, s79, v191
	v_fma_f32 v51, v51, s79, v192
	v_fma_f32 v52, v52, s79, v193
	v_fma_f32 v53, v53, s79, v194
	v_fma_f32 v54, v54, s79, v195
	v_fma_f32 v55, v55, s79, v196
	v_fma_f32 v56, v56, s79, v197
	v_fma_f32 v57, v57, s79, v198
	v_fma_f32 v58, v58, s79, v199
	v_fma_f32 v59, v59, s79, v200
	v_fma_f32 v60, v60, s79, v201
	v_fma_f32 v61, v61, s79, v202
	v_fma_f32 v62, v62, s79, v203
	v_fma_f32 v63, v63, s79, v204
	s_waitcnt lgkmcnt(0)
	v_mfma_f32_16x16x32_bf16 v[64:67], v[4:7], v[96:99], 0
	v_mfma_f32_16x16x32_bf16 v[68:71], v[12:15], v[96:99], 0
	v_mfma_f32_16x16x32_bf16 v[72:75], v[20:23], v[96:99], 0
	v_mfma_f32_16x16x32_bf16 v[76:79], v[28:31], v[96:99], 0
	v_mfma_f32_16x16x32_bf16 v[64:67], v[8:11], v[100:103], v[64:67]
	v_mfma_f32_16x16x32_bf16 v[68:71], v[16:19], v[100:103], v[68:71]
	v_mfma_f32_16x16x32_bf16 v[72:75], v[24:27], v[100:103], v[72:75]
	v_mfma_f32_16x16x32_bf16 v[76:79], v[32:35], v[100:103], v[76:79]
	ds_read_b64 v[4:5], v221 offset:16384
	ds_read_b64 v[8:9], v221 offset:20480
	ds_read_b64 v[12:13], v221 offset:24576
	ds_read_b64 v[16:17], v221 offset:28672
	ds_read_b64 v[6:7], v222 offset:16384
	ds_read_b64 v[10:11], v222 offset:20480
	ds_read_b64 v[14:15], v222 offset:24576
	ds_read_b64 v[18:19], v222 offset:28672
	s_nop 1
	v_fma_f32 v64, v64, s79, v205
	v_fma_f32 v65, v65, s79, v206
	v_fma_f32 v66, v66, s79, v207
	v_fma_f32 v67, v67, s79, v208
	v_fma_f32 v68, v68, s79, v209
	v_fma_f32 v69, v69, s79, v210
	v_fma_f32 v70, v70, s79, v211
	v_fma_f32 v71, v71, s79, v212
	v_fma_f32 v72, v72, s79, v213
	v_fma_f32 v73, v73, s79, v214
	v_fma_f32 v74, v74, s79, v215
	v_fma_f32 v75, v75, s79, v216
	v_fma_f32 v76, v76, s79, v217
	v_fma_f32 v77, v77, s79, v218
	v_fma_f32 v78, v78, s79, v219
	v_fma_f32 v79, v79, s79, v220
	ds_read_b64 v[20:21], v223 offset:16384
	ds_read_b64 v[24:25], v223 offset:20480
	ds_read_b64 v[28:29], v223 offset:24576
	ds_read_b64 v[32:33], v223 offset:28672
	ds_read_b64 v[22:23], v224 offset:16384
	ds_read_b64 v[26:27], v224 offset:20480
	ds_read_b64 v[30:31], v224 offset:24576
	ds_read_b64 v[34:35], v224 offset:28672
	s_cmp_lg_u32 s4, 0
	s_cbranch_scc1 .Lat844_i2_nomask
	s_cmp_le_u32 s6, 0
	s_cbranch_scc1 .Lat844_i2_nomask
	v_mov_b32_e32 v44, v244
	v_mov_b32_e32 v45, v244
	v_mov_b32_e32 v46, v244
	v_mov_b32_e32 v47, v244
	s_cmp_le_u32 s6, 1
	s_cbranch_scc1 .Lat844_i2_nomask
	v_mov_b32_e32 v48, v244
	v_mov_b32_e32 v49, v244
	v_mov_b32_e32 v50, v244
	v_mov_b32_e32 v51, v244
	s_cmp_le_u32 s6, 2
	s_cbranch_scc1 .Lat844_i2_nomask
	v_mov_b32_e32 v52, v244
	v_mov_b32_e32 v53, v244
	v_mov_b32_e32 v54, v244
	v_mov_b32_e32 v55, v244
	s_cmp_le_u32 s6, 3
	s_cbranch_scc1 .Lat844_i2_nomask
	v_mov_b32_e32 v56, v244
	v_mov_b32_e32 v57, v244
	v_mov_b32_e32 v58, v244
	v_mov_b32_e32 v59, v244
	s_cmp_le_u32 s6, 4
	s_cbranch_scc1 .Lat844_i2_nomask
	v_mov_b32_e32 v60, v244
	v_mov_b32_e32 v61, v244
	v_mov_b32_e32 v62, v244
	v_mov_b32_e32 v63, v244
	s_cmp_le_u32 s6, 5
	s_cbranch_scc1 .Lat844_i2_nomask
	v_mov_b32_e32 v64, v244
	v_mov_b32_e32 v65, v244
	v_mov_b32_e32 v66, v244
	v_mov_b32_e32 v67, v244
	s_cmp_le_u32 s6, 6
	s_cbranch_scc1 .Lat844_i2_nomask
	v_mov_b32_e32 v68, v244
	v_mov_b32_e32 v69, v244
	v_mov_b32_e32 v70, v244
	v_mov_b32_e32 v71, v244
	s_cmp_le_u32 s6, 7
	s_cbranch_scc1 .Lat844_i2_nomask
	v_mov_b32_e32 v72, v244
	v_mov_b32_e32 v73, v244
	v_mov_b32_e32 v74, v244
	v_mov_b32_e32 v75, v244
.Lat844_i2_nomask:
	v_max3_f32 v245, v44, v45, v46
	v_max3_f32 v245, v245, v47, v48
	v_max3_f32 v245, v245, v49, v50
	v_max3_f32 v245, v245, v51, v52
	v_max3_f32 v245, v245, v53, v54
	v_max3_f32 v245, v245, v55, v56
	v_max3_f32 v245, v245, v57, v58
	v_max3_f32 v245, v245, v59, v60
	v_max3_f32 v245, v245, v61, v62
	v_max3_f32 v245, v245, v63, v64
	v_max3_f32 v245, v245, v65, v66
	v_max3_f32 v245, v245, v67, v68
	v_max3_f32 v245, v245, v69, v70
	v_max3_f32 v245, v245, v71, v72
	v_max3_f32 v245, v245, v73, v74
	v_max3_f32 v245, v245, v75, v76
	v_max3_f32 v245, v245, v77, v78
	v_max_f32_e32 v245, v245, v79
	ds_bpermute_b32 v148, v239, v245
	s_waitcnt lgkmcnt(0)
	v_max_f32_e32 v245, v245, v148
	ds_bpermute_b32 v148, v240, v245
	s_waitcnt lgkmcnt(0)
	v_max_f32_e32 v245, v245, v148
	v_sub_f32_e32 v44, v44, v245
	v_sub_f32_e32 v45, v45, v245
	v_sub_f32_e32 v46, v46, v245
	v_sub_f32_e32 v47, v47, v245
	v_exp_f32_e32 v44, v44
	v_exp_f32_e32 v45, v45
	v_exp_f32_e32 v46, v46
	v_exp_f32_e32 v47, v47
	v_sub_f32_e32 v48, v48, v245
	v_sub_f32_e32 v49, v49, v245
	v_sub_f32_e32 v50, v50, v245
	v_sub_f32_e32 v51, v51, v245
	v_exp_f32_e32 v48, v48
	v_exp_f32_e32 v49, v49
	v_exp_f32_e32 v50, v50
	v_exp_f32_e32 v51, v51
	v_mov_b32_e32 v149, v44
	v_mov_b32_e32 v150, v45
	v_mov_b32_e32 v151, v46
	v_mov_b32_e32 v152, v47
	v_cvt_pk_bf16_f32 v44, v44, v45
	v_cvt_pk_bf16_f32 v45, v46, v47
	v_sub_f32_e32 v52, v52, v245
	v_sub_f32_e32 v53, v53, v245
	v_sub_f32_e32 v54, v54, v245
	v_sub_f32_e32 v55, v55, v245
	v_exp_f32_e32 v52, v52
	v_exp_f32_e32 v53, v53
	v_exp_f32_e32 v54, v54
	v_exp_f32_e32 v55, v55
	v_add_f32_e32 v149, v149, v48
	v_add_f32_e32 v150, v150, v49
	v_add_f32_e32 v151, v151, v50
	v_add_f32_e32 v152, v152, v51
	v_cvt_pk_bf16_f32 v46, v48, v49
	v_cvt_pk_bf16_f32 v47, v50, v51
	v_sub_f32_e32 v56, v56, v245
	v_sub_f32_e32 v57, v57, v245
	v_sub_f32_e32 v58, v58, v245
	v_sub_f32_e32 v59, v59, v245
	v_exp_f32_e32 v56, v56
	v_exp_f32_e32 v57, v57
	v_exp_f32_e32 v58, v58
	v_exp_f32_e32 v59, v59
	v_add_f32_e32 v149, v149, v52
	v_add_f32_e32 v150, v150, v53
	v_add_f32_e32 v151, v151, v54
	v_add_f32_e32 v152, v152, v55
	v_cvt_pk_bf16_f32 v52, v52, v53
	v_cvt_pk_bf16_f32 v53, v54, v55
	v_sub_f32_e32 v60, v60, v245
	v_sub_f32_e32 v61, v61, v245
	v_sub_f32_e32 v62, v62, v245
	v_sub_f32_e32 v63, v63, v245
	v_exp_f32_e32 v60, v60
	v_exp_f32_e32 v61, v61
	v_exp_f32_e32 v62, v62
	v_exp_f32_e32 v63, v63
	v_add_f32_e32 v149, v149, v56
	v_add_f32_e32 v150, v150, v57
	v_add_f32_e32 v151, v151, v58
	v_add_f32_e32 v152, v152, v59
	v_cvt_pk_bf16_f32 v54, v56, v57
	v_cvt_pk_bf16_f32 v55, v58, v59
	v_sub_f32_e32 v64, v64, v245
	v_sub_f32_e32 v65, v65, v245
	v_sub_f32_e32 v66, v66, v245
	v_sub_f32_e32 v67, v67, v245
	v_exp_f32_e32 v64, v64
	v_exp_f32_e32 v65, v65
	v_exp_f32_e32 v66, v66
	v_exp_f32_e32 v67, v67
	v_add_f32_e32 v149, v149, v60
	v_add_f32_e32 v150, v150, v61
	v_add_f32_e32 v151, v151, v62
	v_add_f32_e32 v152, v152, v63
	v_cvt_pk_bf16_f32 v60, v60, v61
	v_cvt_pk_bf16_f32 v61, v62, v63
	v_sub_f32_e32 v68, v68, v245
	v_sub_f32_e32 v69, v69, v245
	v_sub_f32_e32 v70, v70, v245
	v_sub_f32_e32 v71, v71, v245
	v_exp_f32_e32 v68, v68
	v_exp_f32_e32 v69, v69
	v_exp_f32_e32 v70, v70
	v_exp_f32_e32 v71, v71
	v_add_f32_e32 v149, v149, v64
	v_add_f32_e32 v150, v150, v65
	v_add_f32_e32 v151, v151, v66
	v_add_f32_e32 v152, v152, v67
	v_cvt_pk_bf16_f32 v62, v64, v65
	v_cvt_pk_bf16_f32 v63, v66, v67
	v_sub_f32_e32 v72, v72, v245
	v_sub_f32_e32 v73, v73, v245
	v_sub_f32_e32 v74, v74, v245
	v_sub_f32_e32 v75, v75, v245
	v_exp_f32_e32 v72, v72
	v_exp_f32_e32 v73, v73
	v_exp_f32_e32 v74, v74
	v_exp_f32_e32 v75, v75
	v_add_f32_e32 v149, v149, v68
	v_add_f32_e32 v150, v150, v69
	v_add_f32_e32 v151, v151, v70
	v_add_f32_e32 v152, v152, v71
	v_cvt_pk_bf16_f32 v68, v68, v69
	v_cvt_pk_bf16_f32 v69, v70, v71
	v_sub_f32_e32 v76, v76, v245
	v_sub_f32_e32 v77, v77, v245
	v_sub_f32_e32 v78, v78, v245
	v_sub_f32_e32 v79, v79, v245
	v_exp_f32_e32 v76, v76
	v_exp_f32_e32 v77, v77
	v_exp_f32_e32 v78, v78
	v_exp_f32_e32 v79, v79
	v_add_f32_e32 v149, v149, v72
	v_add_f32_e32 v150, v150, v73
	v_add_f32_e32 v151, v151, v74
	v_add_f32_e32 v152, v152, v75
	v_cvt_pk_bf16_f32 v70, v72, v73
	v_cvt_pk_bf16_f32 v71, v74, v75
	s_nop 0
	v_add_f32_e32 v149, v149, v76
	v_add_f32_e32 v150, v150, v77
	v_add_f32_e32 v151, v151, v78
	v_add_f32_e32 v152, v152, v79
	v_cvt_pk_bf16_f32 v76, v76, v77
	v_cvt_pk_bf16_f32 v77, v78, v79
	v_mov_b32_e32 v78, 0
	v_mov_b32_e32 v79, 0
	v_add_f32_e32 v149, v149, v150
	v_add_f32_e32 v151, v151, v152
	v_add_f32_e32 v246, v149, v151
	s_waitcnt lgkmcnt(0)
	v_mfma_f32_16x16x32_bf16 v[80:83], v[4:7], v[44:47], 0
	v_mfma_f32_16x16x32_bf16 v[84:87], v[8:11], v[44:47], 0
	v_mfma_f32_16x16x32_bf16 v[88:91], v[12:15], v[44:47], 0
	v_mfma_f32_16x16x32_bf16 v[92:95], v[16:19], v[44:47], 0
	ds_read_b64 v[4:5], v225 offset:16384
	ds_read_b64 v[8:9], v225 offset:20480
	ds_read_b64 v[12:13], v225 offset:24576
	ds_read_b64 v[16:17], v225 offset:28672
	ds_read_b64 v[6:7], v226 offset:16384
	ds_read_b64 v[10:11], v226 offset:20480
	ds_read_b64 v[14:15], v226 offset:24576
	ds_read_b64 v[18:19], v226 offset:28672
	v_mfma_f32_16x16x32_bf16 v[80:83], v[20:23], v[52:55], v[80:83]
	v_mfma_f32_16x16x32_bf16 v[84:87], v[24:27], v[52:55], v[84:87]
	v_mfma_f32_16x16x32_bf16 v[88:91], v[28:31], v[52:55], v[88:91]
	v_mfma_f32_16x16x32_bf16 v[92:95], v[32:35], v[52:55], v[92:95]
	ds_read_b64 v[20:21], v227 offset:16384
	ds_read_b64 v[24:25], v227 offset:20480
	ds_read_b64 v[28:29], v227 offset:24576
	ds_read_b64 v[32:33], v227 offset:28672
	ds_read_b64 v[22:23], v228 offset:16384
	ds_read_b64 v[26:27], v228 offset:20480
	ds_read_b64 v[30:31], v228 offset:24576
	ds_read_b64 v[34:35], v228 offset:28672
	ds_bpermute_b32 v148, v239, v246
	s_waitcnt lgkmcnt(9)
	v_mfma_f32_16x16x32_bf16 v[80:83], v[4:7], v[60:63], v[80:83]
	v_mfma_f32_16x16x32_bf16 v[84:87], v[8:11], v[60:63], v[84:87]
	v_mfma_f32_16x16x32_bf16 v[88:91], v[12:15], v[60:63], v[88:91]
	v_mfma_f32_16x16x32_bf16 v[92:95], v[16:19], v[60:63], v[92:95]
	ds_read_b64 v[4:5], v229 offset:16384
	ds_read_b64 v[8:9], v229 offset:20480
	ds_read_b64 v[12:13], v229 offset:24576
	ds_read_b64 v[16:17], v229 offset:28672
	v_mov_b32_e32 v6, 0
	v_mov_b32_e32 v7, 0
	v_mov_b32_e32 v10, 0
	v_mov_b32_e32 v11, 0
	v_mov_b32_e32 v14, 0
	v_mov_b32_e32 v15, 0
	v_mov_b32_e32 v18, 0
	v_mov_b32_e32 v19, 0
	s_waitcnt lgkmcnt(5)
	v_mfma_f32_16x16x32_bf16 v[80:83], v[20:23], v[68:71], v[80:83]
	v_mfma_f32_16x16x32_bf16 v[84:87], v[24:27], v[68:71], v[84:87]
	v_mfma_f32_16x16x32_bf16 v[88:91], v[28:31], v[68:71], v[88:91]
	v_mfma_f32_16x16x32_bf16 v[92:95], v[32:35], v[68:71], v[92:95]
	s_waitcnt lgkmcnt(0)
	v_add_f32_e32 v246, v246, v148
	s_nop 0
	v_mfma_f32_16x16x32_bf16 v[80:83], v[4:7], v[76:79], v[80:83]
	v_mfma_f32_16x16x32_bf16 v[84:87], v[8:11], v[76:79], v[84:87]
	v_mfma_f32_16x16x32_bf16 v[88:91], v[12:15], v[76:79], v[88:91]
	v_mfma_f32_16x16x32_bf16 v[92:95], v[16:19], v[76:79], v[92:95]
	ds_bpermute_b32 v148, v240, v246
	s_waitcnt lgkmcnt(0)
	v_add_f32_e32 v246, v246, v148
	v_rcp_f32_e32 v149, v246
	v_log_f32_e32 v150, v246
	s_nop 0
	v_add_f32_e32 v151, v245, v150
	v_mul_f32_e32 v151, 0x3f317218, v151
	v_max_f32_e32 v152, v120, v151
	v_sub_f32_e32 v153, v120, v152
	v_sub_f32_e32 v154, v151, v152
	v_mul_f32_e32 v153, 0x3fb8aa3b, v153
	v_mul_f32_e32 v154, 0x3fb8aa3b, v154
	v_exp_f32_e32 v153, v153
	v_exp_f32_e32 v154, v154
	s_nop 0
	v_add_f32_e32 v155, v153, v154
	v_rcp_f32_e32 v146, v155
	v_log_f32_e32 v150, v155
	s_nop 0
	v_mul_f32_e32 v154, v154, v146
	v_mul_f32_e32 v146, v153, v146
	v_mul_f32_e32 v147, v149, v154
	v_mul_f32_e32 v150, 0x3f317218, v150
	v_add_f32_e32 v140, v152, v150
	v_mul_f32_e32 v80, v80, v147
	v_mul_f32_e32 v81, v81, v147
	v_mul_f32_e32 v82, v82, v147
	v_mul_f32_e32 v83, v83, v147
	v_mul_f32_e32 v84, v84, v147
	v_mul_f32_e32 v85, v85, v147
	v_mul_f32_e32 v86, v86, v147
	v_mul_f32_e32 v87, v87, v147
	v_mul_f32_e32 v88, v88, v147
	v_mul_f32_e32 v89, v89, v147
	v_mul_f32_e32 v90, v90, v147
	v_mul_f32_e32 v91, v91, v147
	v_mul_f32_e32 v92, v92, v147
	v_mul_f32_e32 v93, v93, v147
	v_mul_f32_e32 v94, v94, v147
	v_mul_f32_e32 v95, v95, v147
	v_lshlrev_b32_e32 v141, 16, v112
	v_and_b32_e32 v142, 0xffff0000, v112
	v_lshlrev_b32_e32 v143, 16, v113
	v_and_b32_e32 v144, 0xffff0000, v113
	v_fmac_f32_e32 v80, v146, v141
	v_fmac_f32_e32 v81, v146, v142
	v_fmac_f32_e32 v82, v146, v143
	v_fmac_f32_e32 v83, v146, v144
	v_cvt_pk_bf16_f32 v132, v80, v81
	v_cvt_pk_bf16_f32 v133, v82, v83
	v_lshlrev_b32_e32 v141, 16, v114
	v_and_b32_e32 v142, 0xffff0000, v114
	v_lshlrev_b32_e32 v143, 16, v115
	v_and_b32_e32 v144, 0xffff0000, v115
	v_fmac_f32_e32 v84, v146, v141
	v_fmac_f32_e32 v85, v146, v142
	v_fmac_f32_e32 v86, v146, v143
	v_fmac_f32_e32 v87, v146, v144
	v_cvt_pk_bf16_f32 v134, v84, v85
	v_cvt_pk_bf16_f32 v135, v86, v87
	v_lshlrev_b32_e32 v141, 16, v116
	v_and_b32_e32 v142, 0xffff0000, v116
	v_lshlrev_b32_e32 v143, 16, v117
	v_and_b32_e32 v144, 0xffff0000, v117
	v_fmac_f32_e32 v88, v146, v141
	v_fmac_f32_e32 v89, v146, v142
	v_fmac_f32_e32 v90, v146, v143
	v_fmac_f32_e32 v91, v146, v144
	v_cvt_pk_bf16_f32 v136, v88, v89
	v_cvt_pk_bf16_f32 v137, v90, v91
	v_lshlrev_b32_e32 v141, 16, v118
	v_and_b32_e32 v142, 0xffff0000, v118
	v_lshlrev_b32_e32 v143, 16, v119
	v_and_b32_e32 v144, 0xffff0000, v119
	v_fmac_f32_e32 v92, v146, v141
	v_fmac_f32_e32 v93, v146, v142
	v_fmac_f32_e32 v94, v146, v143
	v_fmac_f32_e32 v95, v146, v144
	v_cvt_pk_bf16_f32 v138, v92, v93
	v_cvt_pk_bf16_f32 v139, v94, v95
	s_mov_b64 s[26:27], s[86:87]
	s_mov_b64 s[28:29], s[88:89]
	s_mov_b64 s[86:87], s[12:13]
	s_mov_b64 s[88:89], s[14:15]
	s_mov_b32 s4, s83
	s_mov_b32 s5, s84
	s_waitcnt vmcnt(0)
	s_barrier
	ds_read_b128 v[4:7], v230 offset:32768
	ds_read_b128 v[8:11], v231 offset:32768
	ds_read_b128 v[12:15], v230 offset:34816
	ds_read_b128 v[16:19], v231 offset:34816
	ds_read_b128 v[20:23], v230 offset:36864
	ds_read_b128 v[24:27], v231 offset:36864
	ds_read_b128 v[28:31], v230 offset:38912
	ds_read_b128 v[32:35], v231 offset:38912
	ds_read_b128 v[36:39], v230 offset:40960
	ds_read_b128 v[40:43], v231 offset:40960
	global_store_dwordx2 v237, v[132:133], s[26:27]
	global_store_dwordx2 v237, v[134:135], s[26:27] offset:32
	global_store_dwordx2 v237, v[136:137], s[26:27] offset:64
	global_store_dwordx2 v237, v[138:139], s[26:27] offset:96
	s_mov_b64 s[90:91], exec
	s_mov_b64 exec, 0xffff
	global_store_dword v238, v140, s[28:29]
	s_mov_b64 exec, s[90:91]
	s_cmp_eq_u32 s7, 1
	s_cbranch_scc1 .Lat844_i3_nonext
	s_add_u32 s83, s4, 1
	s_mov_b32 s84, s5
	s_mul_i32 s74, s84, 1024
	s_lshl_b32 s75, s83, 7
	s_add_u32 s74, s74, s75
	s_lshl_b32 s75, s74, 7
	s_add_u32 s16, s60, s75
	s_addc_u32 s17, s61, 0
	s_lshl_b32 s75, s74, 1
	s_add_u32 s24, s64, s75
	s_addc_u32 s25, s65, 0
	s_add_u32 m0, s70, 0x0
	s_nop 0
	global_load_lds_dwordx4 v232, s[16:17] nt
	s_add_u32 m0, s70, 0x2000
	s_nop 0
	global_load_lds_dwordx4 v233, s[16:17] nt
	s_add_u32 m0, s70, 0x10000
	s_nop 0
	global_load_lds_dwordx4 v234, s[24:25] nt
	s_add_u32 m0, s70, 0x12000
	s_nop 0
	global_load_lds_dwordx4 v235, s[24:25] nt
	s_lshl_b32 s74, s83, 9
	s_add_u32 s74, s74, s84
	s_lshl_b32 s75, s74, 7
	s_add_u32 s10, s30, s75
	s_addc_u32 s11, s31, 0
	s_add_u32 s12, s34, s75
	s_addc_u32 s13, s35, 0
	s_lshl_b32 s75, s74, 2
	s_add_u32 s14, s58, s75
	s_addc_u32 s15, s59, 0
	global_load_dwordx4 v[96:99], v236, s[10:11]
	global_load_dwordx4 v[100:103], v236, s[10:11] offset:64
	global_load_dwordx2 v[112:113], v237, s[12:13]
	global_load_dwordx2 v[114:115], v237, s[12:13] offset:32
	global_load_dwordx2 v[116:117], v237, s[12:13] offset:64
	global_load_dwordx2 v[118:119], v237, s[12:13] offset:96
	global_load_dword v120, v238, s[14:15]

.LBB0_936:
	v_mov_b32_e32 v0, v170
	v_readlane_b32 s6, v254, 7
	v_readfirstlane_b32 s0, v0
	v_and_b32_e32 v4, 63, v0
	s_ashr_i32 s0, s0, 6
	v_mov_b32_e32 v5, v4
	s_lshl_b32 s1, s0, 3
	v_ashrrev_i32_e32 v6, 3, v5
	v_add_u32_e32 v0, s1, v6
	v_lshrrev_b32_e32 v1, 1, v0
	v_xor_b32_e32 v2, v1, v5
	v_ashrrev_i32_e32 v1, 31, v0
	v_lshlrev_b64 v[0:1], 7, v[0:1]
	v_readlane_b32 s7, v254, 8
	v_lshlrev_b32_e32 v2, 4, v2
	v_and_b32_e32 v2, 0x70, v2
	v_lshl_add_u64 v[0:1], s[6:7], 0, v[0:1]
	s_lshl_b32 s2, s0, 10
	s_add_i32 s3, s0, 8
	v_lshl_add_u64 v[0:1], v[0:1], 0, v[2:3]
	s_add_i32 m0, s82, s2
	s_bitset0_b32 m0, 16
	s_bitset1_b32 m0, 14
	s_lshl_b32 s4, s3, 3
	global_load_lds_dwordx4 v[0:1], off nt
	v_add_u32_e32 v0, s4, v6
	v_lshrrev_b32_e32 v1, 1, v0
	v_xor_b32_e32 v2, v1, v5
	v_ashrrev_i32_e32 v1, 31, v0
	v_lshlrev_b64 v[0:1], 7, v[0:1]
	v_lshlrev_b32_e32 v2, 4, v2
	v_lshl_add_u64 v[0:1], s[6:7], 0, v[0:1]
	v_and_b32_e32 v2, 0x70, v2
	s_lshl_b32 s5, s3, 10
	v_lshl_add_u64 v[0:1], v[0:1], 0, v[2:3]
	s_add_i32 m0, s82, s5
	s_bitset0_b32 m0, 16
	s_bitset1_b32 m0, 14
	v_ashrrev_i32_e32 v6, 4, v5
	s_lshl_b32 s0, s0, 2
	global_load_lds_dwordx4 v[0:1], off nt
	v_add_u32_e32 v0, s0, v6
	v_xor_b32_e32 v2, v0, v5
	v_ashrrev_i32_e32 v1, 31, v0
	v_readlane_b32 s12, v254, 13
	v_lshlrev_b64 v[0:1], 15, v[0:1]
	v_readlane_b32 s13, v254, 14
	v_lshlrev_b32_e32 v2, 4, v2
	v_and_b32_e32 v2, 0xf0, v2
	v_lshl_add_u64 v[0:1], s[12:13], 0, v[0:1]
	v_lshl_add_u64 v[0:1], v[0:1], 0, v[2:3]
	s_add_i32 m0, s62, s2
	s_lshl_b32 s3, s3, 2
	global_load_lds_dwordx4 v[0:1], off nt
	v_add_u32_e32 v0, s3, v6
	v_xor_b32_e32 v2, v0, v5
	v_ashrrev_i32_e32 v1, 31, v0
	v_lshlrev_b64 v[0:1], 15, v[0:1]
	v_lshlrev_b32_e32 v2, 4, v2
	v_lshl_add_u64 v[0:1], s[12:13], 0, v[0:1]
	v_and_b32_e32 v2, 0xf0, v2
	v_lshl_add_u64 v[0:1], v[0:1], 0, v[2:3]
	s_add_i32 m0, s62, s5
	s_nop 0
	global_load_lds_dwordx4 v[0:1], off nt
	s_nop 0
	v_ashrrev_i32_e32 v5, 3, v4
	v_add_u32_e32 v0, s1, v5
	v_lshrrev_b32_e32 v1, 1, v0
	v_xor_b32_e32 v2, v1, v4
	v_ashrrev_i32_e32 v1, 31, v0
	v_lshlrev_b64 v[0:1], 7, v[0:1]
	v_lshlrev_b32_e32 v2, 4, v2
	v_lshl_add_u64 v[0:1], s[6:7], 0, v[0:1]
	v_and_b32_e32 v2, 0x70, v2
	s_add_i32 s1, s2, 0
	v_lshl_add_u64 v[0:1], v[0:1], 0, v[2:3]
	s_mov_b32 m0, s1
	s_add_i32 s2, s5, 0
	global_load_lds_dwordx4 v[0:1], off nt
	v_add_u32_e32 v0, s4, v5
	v_lshrrev_b32_e32 v1, 1, v0
	v_xor_b32_e32 v2, v1, v4
	v_ashrrev_i32_e32 v1, 31, v0
	v_lshlrev_b64 v[0:1], 7, v[0:1]
	v_lshlrev_b32_e32 v2, 4, v2
	v_lshl_add_u64 v[0:1], s[6:7], 0, v[0:1]
	v_and_b32_e32 v2, 0x70, v2
	v_lshl_add_u64 v[0:1], v[0:1], 0, v[2:3]
	s_mov_b32 m0, s2
	v_ashrrev_i32_e32 v5, 4, v4
	global_load_lds_dwordx4 v[0:1], off nt
	v_add_u32_e32 v0, s0, v5
	v_xor_b32_e32 v2, v0, v4
	v_ashrrev_i32_e32 v1, 31, v0
	v_lshlrev_b64 v[0:1], 15, v[0:1]
	v_lshlrev_b32_e32 v2, 4, v2
	v_lshl_add_u64 v[0:1], s[12:13], 0, v[0:1]
	v_and_b32_e32 v2, 0xf0, v2
	v_lshl_add_u64 v[0:1], v[0:1], 0, v[2:3]
	s_add_i32 m0, s1, 0x4000
	s_bitset0_b32 m0, 14
	s_bitset1_b32 m0, 16
	s_nop 0
	global_load_lds_dwordx4 v[0:1], off nt
	v_add_u32_e32 v0, s3, v5
	v_xor_b32_e32 v2, v0, v4
	v_ashrrev_i32_e32 v1, 31, v0
	v_lshlrev_b64 v[0:1], 15, v[0:1]
	v_lshlrev_b32_e32 v2, 4, v2
	v_lshl_add_u64 v[0:1], s[12:13], 0, v[0:1]
	v_and_b32_e32 v2, 0xf0, v2
	v_lshl_add_u64 v[0:1], v[0:1], 0, v[2:3]
	s_add_i32 m0, s2, 0x4000
	s_bitset0_b32 m0, 14
	s_bitset1_b32 m0, 16
	s_nop 0
	global_load_lds_dwordx4 v[0:1], off nt
	s_waitcnt vmcnt(0)
	s_waitcnt vmcnt(0) lgkmcnt(0)
	s_barrier
	s_mov_b64 s[4:5], exec
	v_readlane_b32 s0, v252, 2
	v_readlane_b32 s1, v252, 3
	s_and_b64 s[0:1], s[4:5], s[0:1]
	s_mov_b64 exec, s[0:1]
	s_cbranch_execz .LBB0_988
	v_mov_b32_e32 v0, 0x20000
	ds_read_b64 v[0:1], v0
	s_getreg_b32 s44, hwreg(HW_REG_XCC_ID, 0, 4)
	s_lshl_b32 s44, s44, 7
	s_add_u32 s44, s44, 0xdc03600
	v_mov_b32_e32 v2, s44
	v_mov_b32_e32 v4, 1
	s_waitcnt vmcnt(0) lgkmcnt(0)
	global_atomic_add v5, v2, v4, s[42:43] sc0
	buffer_inv sc1
	s_add_u32 s100, s100, 1
	v_readfirstlane_b32 s46, v0
	v_readfirstlane_b32 s47, v1
	v_mov_b32_e32 v2, 0xdc03e00
	s_nop 3
	s_mul_i32 s48, s46, s100
	s_mul_i32 s49, s47, s100
	s_waitcnt vmcnt(1)
	v_readfirstlane_b32 s50, v5
	s_nop 3
	s_add_u32 s50, s50, 1
	s_cmp_lg_u32 s50, s48
	s_cbranch_scc1 .Lxb8_poll
	buffer_wbl2 sc1
	s_waitcnt vmcnt(0)
	global_atomic_add v2, v4, s[42:43]

.Lat991_i0_nopend:
	s_add_u32 s84, s5, s4
	s_xor_b32 s83, s4, 1
	s_mul_i32 s74, s84, 256
	s_lshl_b32 s75, s83, 7
	s_add_u32 s74, s74, s75
	s_lshl_b32 s75, s74, 7
	s_add_u32 s16, s60, s75
	s_addc_u32 s17, s61, 0
	s_lshl_b32 s75, s74, 1
	s_add_u32 s24, s64, s75
	s_addc_u32 s25, s65, 0
	s_add_u32 m0, s70, 0x4000
	s_nop 0
	global_load_lds_dwordx4 v232, s[16:17] nt
	s_add_u32 m0, s70, 0x6000
	s_nop 0
	global_load_lds_dwordx4 v233, s[16:17] nt
	s_add_u32 m0, s70, 0x14000
	s_nop 0
	global_load_lds_dwordx4 v234, s[24:25] nt
	s_add_u32 m0, s70, 0x16000
	s_nop 0
	global_load_lds_dwordx4 v235, s[24:25] nt
	s_lshl_b32 s74, s83, 11
	s_add_u32 s74, s74, s84
	s_lshl_b32 s75, s74, 7
	s_add_u32 s10, s30, s75
	s_addc_u32 s11, s31, 0
	s_add_u32 s12, s34, s75
	s_addc_u32 s13, s35, 0
	s_lshl_b32 s75, s74, 2
	s_add_u32 s14, s58, s75
	s_addc_u32 s15, s59, 0
	global_load_dwordx4 v[104:107], v236, s[10:11]
	global_load_dwordx4 v[108:111], v236, s[10:11] offset:64
	global_load_dwordx2 v[122:123], v237, s[12:13]
	global_load_dwordx2 v[124:125], v237, s[12:13] offset:32
	global_load_dwordx2 v[126:127], v237, s[12:13] offset:64
	global_load_dwordx2 v[128:129], v237, s[12:13] offset:96
	global_load_dword v121, v238, s[14:15]
	s_waitcnt lgkmcnt(0)
	v_mfma_f32_16x16x32_bf16 v[44:47], v[4:7], v[96:99], 0
	v_mfma_f32_16x16x32_bf16 v[48:51], v[12:15], v[96:99], 0
	v_mfma_f32_16x16x32_bf16 v[52:55], v[20:23], v[96:99], 0
	v_mfma_f32_16x16x32_bf16 v[56:59], v[28:31], v[96:99], 0
	v_mfma_f32_16x16x32_bf16 v[60:63], v[36:39], v[96:99], 0
	v_mfma_f32_16x16x32_bf16 v[44:47], v[8:11], v[100:103], v[44:47]
	v_mfma_f32_16x16x32_bf16 v[48:51], v[16:19], v[100:103], v[48:51]
	v_mfma_f32_16x16x32_bf16 v[52:55], v[24:27], v[100:103], v[52:55]
	v_mfma_f32_16x16x32_bf16 v[56:59], v[32:35], v[100:103], v[56:59]
	v_mfma_f32_16x16x32_bf16 v[60:63], v[40:43], v[100:103], v[60:63]
	s_cmp_gt_u32 s6, 5
	s_cselect_b32 s74, s77, s78
	v_add_u32_e32 v146, s74, v230
	v_xor_b32_e32 v147, 64, v146
	ds_read_b128 v[4:7], v146 offset:10240
	ds_read_b128 v[8:11], v147 offset:10240
	s_cmp_gt_u32 s6, 6
	s_cselect_b32 s74, s77, s78
	v_add_u32_e32 v146, s74, v230
	v_xor_b32_e32 v147, 64, v146
	ds_read_b128 v[12:15], v146 offset:12288
	ds_read_b128 v[16:19], v147 offset:12288
	s_cmp_gt_u32 s6, 7
	s_cselect_b32 s74, s77, s78
	v_add_u32_e32 v146, s74, v230
	v_xor_b32_e32 v147, 64, v146
	ds_read_b128 v[20:23], v146 offset:14336
	ds_read_b128 v[24:27], v147 offset:14336
	s_cmp_gt_u32 s6, 8
	s_cselect_b32 s74, s77, s78
	v_add_u32_e32 v146, s74, v230
	v_xor_b32_e32 v147, 64, v146
	ds_read_b128 v[28:31], v146 offset:16384
	ds_read_b128 v[32:35], v147 offset:16384
	s_nop 1
	v_fma_f32 v44, v44, s79, v185
	v_fma_f32 v45, v45, s79, v186
	v_fma_f32 v46, v46, s79, v187
	v_fma_f32 v47, v47, s79, v188
	v_fma_f32 v48, v48, s79, v189
	v_fma_f32 v49, v49, s79, v190
	v_fma_f32 v50, v50, s79, v191
	v_fma_f32 v51, v51, s79, v192
	v_fma_f32 v52, v52, s79, v193
	v_fma_f32 v53, v53, s79, v194
	v_fma_f32 v54, v54, s79, v195
	v_fma_f32 v55, v55, s79, v196
	v_fma_f32 v56, v56, s79, v197
	v_fma_f32 v57, v57, s79, v198
	v_fma_f32 v58, v58, s79, v199
	v_fma_f32 v59, v59, s79, v200
	v_fma_f32 v60, v60, s79, v201
	v_fma_f32 v61, v61, s79, v202
	v_fma_f32 v62, v62, s79, v203
	v_fma_f32 v63, v63, s79, v204
	s_waitcnt lgkmcnt(0)
	v_mfma_f32_16x16x32_bf16 v[64:67], v[4:7], v[96:99], 0
	v_mfma_f32_16x16x32_bf16 v[68:71], v[12:15], v[96:99], 0
	v_mfma_f32_16x16x32_bf16 v[72:75], v[20:23], v[96:99], 0
	v_mfma_f32_16x16x32_bf16 v[76:79], v[28:31], v[96:99], 0
	v_mfma_f32_16x16x32_bf16 v[64:67], v[8:11], v[100:103], v[64:67]
	v_mfma_f32_16x16x32_bf16 v[68:71], v[16:19], v[100:103], v[68:71]
	v_mfma_f32_16x16x32_bf16 v[72:75], v[24:27], v[100:103], v[72:75]
	v_mfma_f32_16x16x32_bf16 v[76:79], v[32:35], v[100:103], v[76:79]
	s_cmp_gt_u32 s6, 0
	s_cselect_b32 s74, 0, 0xffff0000
	v_add_u32_e32 v146, s74, v221
	ds_read_b64 v[4:5], v146 offset:49152
	ds_read_b64 v[8:9], v146 offset:53248
	ds_read_b64 v[12:13], v146 offset:57344
	ds_read_b64 v[16:17], v146 offset:61440
	s_cmp_gt_u32 s6, 1
	s_cselect_b32 s74, 0, 0xffff0000
	v_add_u32_e32 v146, s74, v222
	ds_read_b64 v[6:7], v146 offset:49152
	ds_read_b64 v[10:11], v146 offset:53248
	ds_read_b64 v[14:15], v146 offset:57344
	ds_read_b64 v[18:19], v146 offset:61440
	s_nop 1
	v_fma_f32 v64, v64, s79, v205
	v_fma_f32 v65, v65, s79, v206
	v_fma_f32 v66, v66, s79, v207
	v_fma_f32 v67, v67, s79, v208
	v_fma_f32 v68, v68, s79, v209
	v_fma_f32 v69, v69, s79, v210
	v_fma_f32 v70, v70, s79, v211
	v_fma_f32 v71, v71, s79, v212
	v_fma_f32 v72, v72, s79, v213
	v_fma_f32 v73, v73, s79, v214
	v_fma_f32 v74, v74, s79, v215
	v_fma_f32 v75, v75, s79, v216
	v_fma_f32 v76, v76, s79, v217
	v_fma_f32 v77, v77, s79, v218
	v_fma_f32 v78, v78, s79, v219
	v_fma_f32 v79, v79, s79, v220
	s_cmp_gt_u32 s6, 2
	s_cselect_b32 s74, 0, 0xffff0000
	v_add_u32_e32 v146, s74, v223
	ds_read_b64 v[20:21], v146 offset:49152
	ds_read_b64 v[24:25], v146 offset:53248
	ds_read_b64 v[28:29], v146 offset:57344
	ds_read_b64 v[32:33], v146 offset:61440
	s_cmp_gt_u32 s6, 3
	s_cselect_b32 s74, 0, 0xffff0000
	v_add_u32_e32 v146, s74, v224
	ds_read_b64 v[22:23], v146 offset:49152
	ds_read_b64 v[26:27], v146 offset:53248
	ds_read_b64 v[30:31], v146 offset:57344
	ds_read_b64 v[34:35], v146 offset:61440
	s_cmp_lg_u32 s4, 0
	s_cbranch_scc1 .Lat991_i0_nomask
	s_cmp_le_u32 s6, 0
	s_cbranch_scc1 .Lat991_i0_nomask
	v_mov_b32_e32 v44, v244
	v_mov_b32_e32 v45, v244
	v_mov_b32_e32 v46, v244
	v_mov_b32_e32 v47, v244
	s_cmp_le_u32 s6, 1
	s_cbranch_scc1 .Lat991_i0_nomask
	v_mov_b32_e32 v48, v244
	v_mov_b32_e32 v49, v244
	v_mov_b32_e32 v50, v244
	v_mov_b32_e32 v51, v244
	s_cmp_le_u32 s6, 2
	s_cbranch_scc1 .Lat991_i0_nomask
	v_mov_b32_e32 v52, v244
	v_mov_b32_e32 v53, v244
	v_mov_b32_e32 v54, v244
	v_mov_b32_e32 v55, v244
	s_cmp_le_u32 s6, 3
	s_cbranch_scc1 .Lat991_i0_nomask
	v_mov_b32_e32 v56, v244
	v_mov_b32_e32 v57, v244
	v_mov_b32_e32 v58, v244
	v_mov_b32_e32 v59, v244
	s_cmp_le_u32 s6, 4
	s_cbranch_scc1 .Lat991_i0_nomask
	v_mov_b32_e32 v60, v244
	v_mov_b32_e32 v61, v244
	v_mov_b32_e32 v62, v244
	v_mov_b32_e32 v63, v244
	s_cmp_le_u32 s6, 5
	s_cbranch_scc1 .Lat991_i0_nomask
	v_mov_b32_e32 v64, v244
	v_mov_b32_e32 v65, v244
	v_mov_b32_e32 v66, v244
	v_mov_b32_e32 v67, v244
	s_cmp_le_u32 s6, 6
	s_cbranch_scc1 .Lat991_i0_nomask
	v_mov_b32_e32 v68, v244
	v_mov_b32_e32 v69, v244
	v_mov_b32_e32 v70, v244
	v_mov_b32_e32 v71, v244
	s_cmp_le_u32 s6, 7
	s_cbranch_scc1 .Lat991_i0_nomask
	v_mov_b32_e32 v72, v244
	v_mov_b32_e32 v73, v244
	v_mov_b32_e32 v74, v244
	v_mov_b32_e32 v75, v244
.Lat991_i0_nomask:
	v_max3_f32 v245, v44, v45, v46
	v_max3_f32 v245, v245, v47, v48
	v_max3_f32 v245, v245, v49, v50
	v_max3_f32 v245, v245, v51, v52
	v_max3_f32 v245, v245, v53, v54
	v_max3_f32 v245, v245, v55, v56
	v_max3_f32 v245, v245, v57, v58
	v_max3_f32 v245, v245, v59, v60
	v_max3_f32 v245, v245, v61, v62
	v_max3_f32 v245, v245, v63, v64
	v_max3_f32 v245, v245, v65, v66
	v_max3_f32 v245, v245, v67, v68
	v_max3_f32 v245, v245, v69, v70
	v_max3_f32 v245, v245, v71, v72
	v_max3_f32 v245, v245, v73, v74
	v_max3_f32 v245, v245, v75, v76
	v_max3_f32 v245, v245, v77, v78
	v_max_f32_e32 v245, v245, v79
	ds_bpermute_b32 v148, v239, v245
	s_waitcnt lgkmcnt(0)
	v_max_f32_e32 v245, v245, v148
	ds_bpermute_b32 v148, v240, v245
	s_waitcnt lgkmcnt(0)
	v_max_f32_e32 v245, v245, v148
	v_sub_f32_e32 v44, v44, v245
	v_sub_f32_e32 v45, v45, v245
	v_sub_f32_e32 v46, v46, v245
	v_sub_f32_e32 v47, v47, v245
	v_exp_f32_e32 v44, v44
	v_exp_f32_e32 v45, v45
	v_exp_f32_e32 v46, v46
	v_exp_f32_e32 v47, v47
	v_sub_f32_e32 v48, v48, v245
	v_sub_f32_e32 v49, v49, v245
	v_sub_f32_e32 v50, v50, v245
	v_sub_f32_e32 v51, v51, v245
	v_exp_f32_e32 v48, v48
	v_exp_f32_e32 v49, v49
	v_exp_f32_e32 v50, v50
	v_exp_f32_e32 v51, v51
	v_mov_b32_e32 v149, v44
	v_mov_b32_e32 v150, v45
	v_mov_b32_e32 v151, v46
	v_mov_b32_e32 v152, v47
	v_cvt_pk_bf16_f32 v44, v44, v45
	v_cvt_pk_bf16_f32 v45, v46, v47
	v_sub_f32_e32 v52, v52, v245
	v_sub_f32_e32 v53, v53, v245
	v_sub_f32_e32 v54, v54, v245
	v_sub_f32_e32 v55, v55, v245
	v_exp_f32_e32 v52, v52
	v_exp_f32_e32 v53, v53
	v_exp_f32_e32 v54, v54
	v_exp_f32_e32 v55, v55
	v_add_f32_e32 v149, v149, v48
	v_add_f32_e32 v150, v150, v49
	v_add_f32_e32 v151, v151, v50
	v_add_f32_e32 v152, v152, v51
	v_cvt_pk_bf16_f32 v46, v48, v49
	v_cvt_pk_bf16_f32 v47, v50, v51
	v_sub_f32_e32 v56, v56, v245
	v_sub_f32_e32 v57, v57, v245
	v_sub_f32_e32 v58, v58, v245
	v_sub_f32_e32 v59, v59, v245
	v_exp_f32_e32 v56, v56
	v_exp_f32_e32 v57, v57
	v_exp_f32_e32 v58, v58
	v_exp_f32_e32 v59, v59
	v_add_f32_e32 v149, v149, v52
	v_add_f32_e32 v150, v150, v53
	v_add_f32_e32 v151, v151, v54
	v_add_f32_e32 v152, v152, v55
	v_cvt_pk_bf16_f32 v52, v52, v53
	v_cvt_pk_bf16_f32 v53, v54, v55
	v_sub_f32_e32 v60, v60, v245
	v_sub_f32_e32 v61, v61, v245
	v_sub_f32_e32 v62, v62, v245
	v_sub_f32_e32 v63, v63, v245
	v_exp_f32_e32 v60, v60
	v_exp_f32_e32 v61, v61
	v_exp_f32_e32 v62, v62
	v_exp_f32_e32 v63, v63
	v_add_f32_e32 v149, v149, v56
	v_add_f32_e32 v150, v150, v57
	v_add_f32_e32 v151, v151, v58
	v_add_f32_e32 v152, v152, v59
	v_cvt_pk_bf16_f32 v54, v56, v57
	v_cvt_pk_bf16_f32 v55, v58, v59
	v_sub_f32_e32 v64, v64, v245
	v_sub_f32_e32 v65, v65, v245
	v_sub_f32_e32 v66, v66, v245
	v_sub_f32_e32 v67, v67, v245
	v_exp_f32_e32 v64, v64
	v_exp_f32_e32 v65, v65
	v_exp_f32_e32 v66, v66
	v_exp_f32_e32 v67, v67
	v_add_f32_e32 v149, v149, v60
	v_add_f32_e32 v150, v150, v61
	v_add_f32_e32 v151, v151, v62
	v_add_f32_e32 v152, v152, v63
	v_cvt_pk_bf16_f32 v60, v60, v61
	v_cvt_pk_bf16_f32 v61, v62, v63
	v_sub_f32_e32 v68, v68, v245
	v_sub_f32_e32 v69, v69, v245
	v_sub_f32_e32 v70, v70, v245
	v_sub_f32_e32 v71, v71, v245
	v_exp_f32_e32 v68, v68
	v_exp_f32_e32 v69, v69
	v_exp_f32_e32 v70, v70
	v_exp_f32_e32 v71, v71
	v_add_f32_e32 v149, v149, v64
	v_add_f32_e32 v150, v150, v65
	v_add_f32_e32 v151, v151, v66
	v_add_f32_e32 v152, v152, v67
	v_cvt_pk_bf16_f32 v62, v64, v65
	v_cvt_pk_bf16_f32 v63, v66, v67
	v_sub_f32_e32 v72, v72, v245
	v_sub_f32_e32 v73, v73, v245
	v_sub_f32_e32 v74, v74, v245
	v_sub_f32_e32 v75, v75, v245
	v_exp_f32_e32 v72, v72
	v_exp_f32_e32 v73, v73
	v_exp_f32_e32 v74, v74
	v_exp_f32_e32 v75, v75
	v_add_f32_e32 v149, v149, v68
	v_add_f32_e32 v150, v150, v69
	v_add_f32_e32 v151, v151, v70
	v_add_f32_e32 v152, v152, v71
	v_cvt_pk_bf16_f32 v68, v68, v69
	v_cvt_pk_bf16_f32 v69, v70, v71
	v_sub_f32_e32 v76, v76, v245
	v_sub_f32_e32 v77, v77, v245
	v_sub_f32_e32 v78, v78, v245
	v_sub_f32_e32 v79, v79, v245
	v_exp_f32_e32 v76, v76
	v_exp_f32_e32 v77, v77
	v_exp_f32_e32 v78, v78
	v_exp_f32_e32 v79, v79
	v_add_f32_e32 v149, v149, v72
	v_add_f32_e32 v150, v150, v73
	v_add_f32_e32 v151, v151, v74
	v_add_f32_e32 v152, v152, v75
	v_cvt_pk_bf16_f32 v70, v72, v73
	v_cvt_pk_bf16_f32 v71, v74, v75
	s_nop 0
	v_add_f32_e32 v149, v149, v76
	v_add_f32_e32 v150, v150, v77
	v_add_f32_e32 v151, v151, v78
	v_add_f32_e32 v152, v152, v79
	v_cvt_pk_bf16_f32 v76, v76, v77
	v_cvt_pk_bf16_f32 v77, v78, v79
	v_mov_b32_e32 v78, 0
	v_mov_b32_e32 v79, 0
	v_add_f32_e32 v149, v149, v150
	v_add_f32_e32 v151, v151, v152
	v_add_f32_e32 v246, v149, v151
	s_waitcnt lgkmcnt(0)
	v_mfma_f32_16x16x32_bf16 v[80:83], v[4:7], v[44:47], 0
	v_mfma_f32_16x16x32_bf16 v[84:87], v[8:11], v[44:47], 0
	v_mfma_f32_16x16x32_bf16 v[88:91], v[12:15], v[44:47], 0
	v_mfma_f32_16x16x32_bf16 v[92:95], v[16:19], v[44:47], 0
	s_cmp_gt_u32 s6, 4
	s_cselect_b32 s74, 0, 0xffff0000
	v_add_u32_e32 v146, s74, v225
	ds_read_b64 v[4:5], v146 offset:49152
	ds_read_b64 v[8:9], v146 offset:53248
	ds_read_b64 v[12:13], v146 offset:57344
	ds_read_b64 v[16:17], v146 offset:61440
	s_cmp_gt_u32 s6, 5
	s_cselect_b32 s74, 0, 0xffff0000
	v_add_u32_e32 v146, s74, v226
	ds_read_b64 v[6:7], v146 offset:49152
	ds_read_b64 v[10:11], v146 offset:53248
	ds_read_b64 v[14:15], v146 offset:57344
	ds_read_b64 v[18:19], v146 offset:61440
	v_mfma_f32_16x16x32_bf16 v[80:83], v[20:23], v[52:55], v[80:83]
	v_mfma_f32_16x16x32_bf16 v[84:87], v[24:27], v[52:55], v[84:87]
	v_mfma_f32_16x16x32_bf16 v[88:91], v[28:31], v[52:55], v[88:91]
	v_mfma_f32_16x16x32_bf16 v[92:95], v[32:35], v[52:55], v[92:95]
	s_cmp_gt_u32 s6, 6
	s_cselect_b32 s74, 0, 0xffff0000
	v_add_u32_e32 v146, s74, v227
	ds_read_b64 v[20:21], v146 offset:49152
	ds_read_b64 v[24:25], v146 offset:53248
	ds_read_b64 v[28:29], v146 offset:57344
	ds_read_b64 v[32:33], v146 offset:61440
	s_cmp_gt_u32 s6, 7
	s_cselect_b32 s74, 0, 0xffff0000
	v_add_u32_e32 v146, s74, v228
	ds_read_b64 v[22:23], v146 offset:49152
	ds_read_b64 v[26:27], v146 offset:53248
	ds_read_b64 v[30:31], v146 offset:57344
	ds_read_b64 v[34:35], v146 offset:61440
	ds_bpermute_b32 v148, v239, v246
	s_waitcnt lgkmcnt(9)
	v_mfma_f32_16x16x32_bf16 v[80:83], v[4:7], v[60:63], v[80:83]
	v_mfma_f32_16x16x32_bf16 v[84:87], v[8:11], v[60:63], v[84:87]
	v_mfma_f32_16x16x32_bf16 v[88:91], v[12:15], v[60:63], v[88:91]
	v_mfma_f32_16x16x32_bf16 v[92:95], v[16:19], v[60:63], v[92:95]
	s_cmp_gt_u32 s6, 8
	s_cselect_b32 s74, 0, 0xffff0000
	v_add_u32_e32 v146, s74, v229
	ds_read_b64 v[4:5], v146 offset:49152
	ds_read_b64 v[8:9], v146 offset:53248
	ds_read_b64 v[12:13], v146 offset:57344
	ds_read_b64 v[16:17], v146 offset:61440
	v_mov_b32_e32 v6, 0
	v_mov_b32_e32 v7, 0
	v_mov_b32_e32 v10, 0
	v_mov_b32_e32 v11, 0
	v_mov_b32_e32 v14, 0
	v_mov_b32_e32 v15, 0
	v_mov_b32_e32 v18, 0
	v_mov_b32_e32 v19, 0
	s_waitcnt lgkmcnt(5)
	v_mfma_f32_16x16x32_bf16 v[80:83], v[20:23], v[68:71], v[80:83]
	v_mfma_f32_16x16x32_bf16 v[84:87], v[24:27], v[68:71], v[84:87]
	v_mfma_f32_16x16x32_bf16 v[88:91], v[28:31], v[68:71], v[88:91]
	v_mfma_f32_16x16x32_bf16 v[92:95], v[32:35], v[68:71], v[92:95]
	s_waitcnt lgkmcnt(0)
	v_add_f32_e32 v246, v246, v148
	s_nop 0
	v_mfma_f32_16x16x32_bf16 v[80:83], v[4:7], v[76:79], v[80:83]
	v_mfma_f32_16x16x32_bf16 v[84:87], v[8:11], v[76:79], v[84:87]
	v_mfma_f32_16x16x32_bf16 v[88:91], v[12:15], v[76:79], v[88:91]
	v_mfma_f32_16x16x32_bf16 v[92:95], v[16:19], v[76:79], v[92:95]
	ds_bpermute_b32 v148, v240, v246
	s_waitcnt lgkmcnt(0)
	v_add_f32_e32 v246, v246, v148
	v_rcp_f32_e32 v149, v246
	v_log_f32_e32 v150, v246
	s_nop 0
	v_add_f32_e32 v151, v245, v150
	v_mul_f32_e32 v151, 0x3f317218, v151
	v_max_f32_e32 v152, v120, v151
	v_sub_f32_e32 v153, v120, v152
	v_sub_f32_e32 v154, v151, v152
	v_mul_f32_e32 v153, 0x3fb8aa3b, v153
	v_mul_f32_e32 v154, 0x3fb8aa3b, v154
	v_exp_f32_e32 v153, v153
	v_exp_f32_e32 v154, v154
	s_nop 0
	v_add_f32_e32 v155, v153, v154
	v_rcp_f32_e32 v146, v155
	v_log_f32_e32 v150, v155
	s_nop 0
	v_mul_f32_e32 v154, v154, v146
	v_mul_f32_e32 v146, v153, v146
	v_mul_f32_e32 v147, v149, v154
	v_mul_f32_e32 v150, 0x3f317218, v150
	v_add_f32_e32 v140, v152, v150
	v_mul_f32_e32 v80, v80, v147
	v_mul_f32_e32 v81, v81, v147
	v_mul_f32_e32 v82, v82, v147
	v_mul_f32_e32 v83, v83, v147
	v_mul_f32_e32 v84, v84, v147
	v_mul_f32_e32 v85, v85, v147
	v_mul_f32_e32 v86, v86, v147
	v_mul_f32_e32 v87, v87, v147
	v_mul_f32_e32 v88, v88, v147
	v_mul_f32_e32 v89, v89, v147
	v_mul_f32_e32 v90, v90, v147
	v_mul_f32_e32 v91, v91, v147
	v_mul_f32_e32 v92, v92, v147
	v_mul_f32_e32 v93, v93, v147
	v_mul_f32_e32 v94, v94, v147
	v_mul_f32_e32 v95, v95, v147
	v_lshlrev_b32_e32 v141, 16, v112
	v_and_b32_e32 v142, 0xffff0000, v112
	v_lshlrev_b32_e32 v143, 16, v113
	v_and_b32_e32 v144, 0xffff0000, v113
	v_fmac_f32_e32 v80, v146, v141
	v_fmac_f32_e32 v81, v146, v142
	v_fmac_f32_e32 v82, v146, v143
	v_fmac_f32_e32 v83, v146, v144
	v_cvt_pk_bf16_f32 v132, v80, v81
	v_cvt_pk_bf16_f32 v133, v82, v83
	v_lshlrev_b32_e32 v141, 16, v114
	v_and_b32_e32 v142, 0xffff0000, v114
	v_lshlrev_b32_e32 v143, 16, v115
	v_and_b32_e32 v144, 0xffff0000, v115
	v_fmac_f32_e32 v84, v146, v141
	v_fmac_f32_e32 v85, v146, v142
	v_fmac_f32_e32 v86, v146, v143
	v_fmac_f32_e32 v87, v146, v144
	v_cvt_pk_bf16_f32 v134, v84, v85
	v_cvt_pk_bf16_f32 v135, v86, v87
	v_lshlrev_b32_e32 v141, 16, v116
	v_and_b32_e32 v142, 0xffff0000, v116
	v_lshlrev_b32_e32 v143, 16, v117
	v_and_b32_e32 v144, 0xffff0000, v117
	v_fmac_f32_e32 v88, v146, v141
	v_fmac_f32_e32 v89, v146, v142
	v_fmac_f32_e32 v90, v146, v143
	v_fmac_f32_e32 v91, v146, v144
	v_cvt_pk_bf16_f32 v136, v88, v89
	v_cvt_pk_bf16_f32 v137, v90, v91
	v_lshlrev_b32_e32 v141, 16, v118
	v_and_b32_e32 v142, 0xffff0000, v118
	v_lshlrev_b32_e32 v143, 16, v119
	v_and_b32_e32 v144, 0xffff0000, v119
	v_fmac_f32_e32 v92, v146, v141
	v_fmac_f32_e32 v93, v146, v142
	v_fmac_f32_e32 v94, v146, v143
	v_fmac_f32_e32 v95, v146, v144
	v_cvt_pk_bf16_f32 v138, v92, v93
	v_cvt_pk_bf16_f32 v139, v94, v95
	s_mov_b64 s[26:27], s[86:87]
	s_mov_b64 s[28:29], s[88:89]
	s_mov_b64 s[86:87], s[12:13]
	s_mov_b64 s[88:89], s[14:15]
	s_mov_b32 s4, s83
	s_mov_b32 s5, s84
	s_waitcnt vmcnt(0)
	s_barrier
	ds_read_b128 v[4:7], v230 offset:0
	ds_read_b128 v[8:11], v231 offset:0
	ds_read_b128 v[12:15], v230 offset:2048
	ds_read_b128 v[16:19], v231 offset:2048
	ds_read_b128 v[20:23], v230 offset:4096
	ds_read_b128 v[24:27], v231 offset:4096
	ds_read_b128 v[28:31], v230 offset:6144
	ds_read_b128 v[32:35], v231 offset:6144
	ds_read_b128 v[36:39], v230 offset:8192
	ds_read_b128 v[40:43], v231 offset:8192
	global_store_dwordx2 v237, v[132:133], s[26:27]
	global_store_dwordx2 v237, v[134:135], s[26:27] offset:32
	global_store_dwordx2 v237, v[136:137], s[26:27] offset:64
	global_store_dwordx2 v237, v[138:139], s[26:27] offset:96
	s_mov_b64 s[90:91], exec
	s_mov_b64 exec, 0xffff
	global_store_dword v238, v140, s[28:29]
	s_mov_b64 exec, s[90:91]
	s_add_u32 s84, s5, s4
	s_xor_b32 s83, s4, 1
	s_mul_i32 s74, s84, 256
	s_lshl_b32 s75, s83, 7
	s_add_u32 s74, s74, s75
	s_lshl_b32 s75, s74, 7
	s_add_u32 s16, s60, s75
	s_addc_u32 s17, s61, 0
	s_lshl_b32 s75, s74, 1
	s_add_u32 s24, s64, s75
	s_addc_u32 s25, s65, 0
	s_add_u32 m0, s70, 0x8000
	s_nop 0
	global_load_lds_dwordx4 v232, s[16:17] nt
	s_add_u32 m0, s70, 0xa000
	s_nop 0
	global_load_lds_dwordx4 v233, s[16:17] nt
	s_add_u32 m0, s70, 0x18000
	s_nop 0
	global_load_lds_dwordx4 v234, s[24:25] nt
	s_add_u32 m0, s70, 0x1a000
	s_nop 0
	global_load_lds_dwordx4 v235, s[24:25] nt
	s_lshl_b32 s74, s83, 11
	s_add_u32 s74, s74, s84
	s_lshl_b32 s75, s74, 7
	s_add_u32 s10, s30, s75
	s_addc_u32 s11, s31, 0
	s_add_u32 s12, s34, s75
	s_addc_u32 s13, s35, 0
	s_lshl_b32 s75, s74, 2
	s_add_u32 s14, s58, s75
	s_addc_u32 s15, s59, 0
	global_load_dwordx4 v[96:99], v236, s[10:11]
	global_load_dwordx4 v[100:103], v236, s[10:11] offset:64
	global_load_dwordx2 v[112:113], v237, s[12:13]
	global_load_dwordx2 v[114:115], v237, s[12:13] offset:32
	global_load_dwordx2 v[116:117], v237, s[12:13] offset:64
	global_load_dwordx2 v[118:119], v237, s[12:13] offset:96
	global_load_dword v120, v238, s[14:15]
	s_waitcnt lgkmcnt(0)
	v_mfma_f32_16x16x32_bf16 v[44:47], v[4:7], v[104:107], 0
	v_mfma_f32_16x16x32_bf16 v[48:51], v[12:15], v[104:107], 0
	v_mfma_f32_16x16x32_bf16 v[52:55], v[20:23], v[104:107], 0
	v_mfma_f32_16x16x32_bf16 v[56:59], v[28:31], v[104:107], 0
	v_mfma_f32_16x16x32_bf16 v[60:63], v[36:39], v[104:107], 0
	v_mfma_f32_16x16x32_bf16 v[44:47], v[8:11], v[108:111], v[44:47]
	v_mfma_f32_16x16x32_bf16 v[48:51], v[16:19], v[108:111], v[48:51]
	v_mfma_f32_16x16x32_bf16 v[52:55], v[24:27], v[108:111], v[52:55]
	v_mfma_f32_16x16x32_bf16 v[56:59], v[32:35], v[108:111], v[56:59]
	v_mfma_f32_16x16x32_bf16 v[60:63], v[40:43], v[108:111], v[60:63]
	ds_read_b128 v[4:7], v230 offset:10240
	ds_read_b128 v[8:11], v231 offset:10240
	ds_read_b128 v[12:15], v230 offset:12288
	ds_read_b128 v[16:19], v231 offset:12288
	ds_read_b128 v[20:23], v230 offset:14336
	ds_read_b128 v[24:27], v231 offset:14336
	ds_read_b128 v[28:31], v230 offset:16384
	ds_read_b128 v[32:35], v231 offset:16384
	s_nop 1
	v_fma_f32 v44, v44, s79, v185
	v_fma_f32 v45, v45, s79, v186
	v_fma_f32 v46, v46, s79, v187
	v_fma_f32 v47, v47, s79, v188
	v_fma_f32 v48, v48, s79, v189
	v_fma_f32 v49, v49, s79, v190
	v_fma_f32 v50, v50, s79, v191
	v_fma_f32 v51, v51, s79, v192
	v_fma_f32 v52, v52, s79, v193
	v_fma_f32 v53, v53, s79, v194
	v_fma_f32 v54, v54, s79, v195
	v_fma_f32 v55, v55, s79, v196
	v_fma_f32 v56, v56, s79, v197
	v_fma_f32 v57, v57, s79, v198
	v_fma_f32 v58, v58, s79, v199
	v_fma_f32 v59, v59, s79, v200
	v_fma_f32 v60, v60, s79, v201
	v_fma_f32 v61, v61, s79, v202
	v_fma_f32 v62, v62, s79, v203
	v_fma_f32 v63, v63, s79, v204
	s_waitcnt lgkmcnt(0)
	v_mfma_f32_16x16x32_bf16 v[64:67], v[4:7], v[104:107], 0
	v_mfma_f32_16x16x32_bf16 v[68:71], v[12:15], v[104:107], 0
	v_mfma_f32_16x16x32_bf16 v[72:75], v[20:23], v[104:107], 0
	v_mfma_f32_16x16x32_bf16 v[76:79], v[28:31], v[104:107], 0
	v_mfma_f32_16x16x32_bf16 v[64:67], v[8:11], v[108:111], v[64:67]
	v_mfma_f32_16x16x32_bf16 v[68:71], v[16:19], v[108:111], v[68:71]
	v_mfma_f32_16x16x32_bf16 v[72:75], v[24:27], v[108:111], v[72:75]
	v_mfma_f32_16x16x32_bf16 v[76:79], v[32:35], v[108:111], v[76:79]
	ds_read_b64 v[4:5], v221 offset:0
	ds_read_b64 v[8:9], v221 offset:4096
	ds_read_b64 v[12:13], v221 offset:8192
	ds_read_b64 v[16:17], v221 offset:12288
	ds_read_b64 v[6:7], v222 offset:0
	ds_read_b64 v[10:11], v222 offset:4096
	ds_read_b64 v[14:15], v222 offset:8192
	ds_read_b64 v[18:19], v222 offset:12288
	s_nop 1
	v_fma_f32 v64, v64, s79, v205
	v_fma_f32 v65, v65, s79, v206
	v_fma_f32 v66, v66, s79, v207
	v_fma_f32 v67, v67, s79, v208
	v_fma_f32 v68, v68, s79, v209
	v_fma_f32 v69, v69, s79, v210
	v_fma_f32 v70, v70, s79, v211
	v_fma_f32 v71, v71, s79, v212
	v_fma_f32 v72, v72, s79, v213
	v_fma_f32 v73, v73, s79, v214
	v_fma_f32 v74, v74, s79, v215
	v_fma_f32 v75, v75, s79, v216
	v_fma_f32 v76, v76, s79, v217
	v_fma_f32 v77, v77, s79, v218
	v_fma_f32 v78, v78, s79, v219
	v_fma_f32 v79, v79, s79, v220
	ds_read_b64 v[20:21], v223 offset:0
	ds_read_b64 v[24:25], v223 offset:4096
	ds_read_b64 v[28:29], v223 offset:8192
	ds_read_b64 v[32:33], v223 offset:12288
	ds_read_b64 v[22:23], v224 offset:0
	ds_read_b64 v[26:27], v224 offset:4096
	ds_read_b64 v[30:31], v224 offset:8192
	ds_read_b64 v[34:35], v224 offset:12288
	s_cmp_lg_u32 s4, 0
	s_cbranch_scc1 .Lat991_i1_nomask
	s_cmp_le_u32 s6, 0
	s_cbranch_scc1 .Lat991_i1_nomask
	v_mov_b32_e32 v44, v244
	v_mov_b32_e32 v45, v244
	v_mov_b32_e32 v46, v244
	v_mov_b32_e32 v47, v244
	s_cmp_le_u32 s6, 1
	s_cbranch_scc1 .Lat991_i1_nomask
	v_mov_b32_e32 v48, v244
	v_mov_b32_e32 v49, v244
	v_mov_b32_e32 v50, v244
	v_mov_b32_e32 v51, v244
	s_cmp_le_u32 s6, 2
	s_cbranch_scc1 .Lat991_i1_nomask
	v_mov_b32_e32 v52, v244
	v_mov_b32_e32 v53, v244
	v_mov_b32_e32 v54, v244
	v_mov_b32_e32 v55, v244
	s_cmp_le_u32 s6, 3
	s_cbranch_scc1 .Lat991_i1_nomask
	v_mov_b32_e32 v56, v244
	v_mov_b32_e32 v57, v244
	v_mov_b32_e32 v58, v244
	v_mov_b32_e32 v59, v244
	s_cmp_le_u32 s6, 4
	s_cbranch_scc1 .Lat991_i1_nomask
	v_mov_b32_e32 v60, v244
	v_mov_b32_e32 v61, v244
	v_mov_b32_e32 v62, v244
	v_mov_b32_e32 v63, v244
	s_cmp_le_u32 s6, 5
	s_cbranch_scc1 .Lat991_i1_nomask
	v_mov_b32_e32 v64, v244
	v_mov_b32_e32 v65, v244
	v_mov_b32_e32 v66, v244
	v_mov_b32_e32 v67, v244
	s_cmp_le_u32 s6, 6
	s_cbranch_scc1 .Lat991_i1_nomask
	v_mov_b32_e32 v68, v244
	v_mov_b32_e32 v69, v244
	v_mov_b32_e32 v70, v244
	v_mov_b32_e32 v71, v244
	s_cmp_le_u32 s6, 7
	s_cbranch_scc1 .Lat991_i1_nomask
	v_mov_b32_e32 v72, v244
	v_mov_b32_e32 v73, v244
	v_mov_b32_e32 v74, v244
	v_mov_b32_e32 v75, v244
.Lat991_i1_nomask:
	v_max3_f32 v245, v44, v45, v46
	v_max3_f32 v245, v245, v47, v48
	v_max3_f32 v245, v245, v49, v50
	v_max3_f32 v245, v245, v51, v52
	v_max3_f32 v245, v245, v53, v54
	v_max3_f32 v245, v245, v55, v56
	v_max3_f32 v245, v245, v57, v58
	v_max3_f32 v245, v245, v59, v60
	v_max3_f32 v245, v245, v61, v62
	v_max3_f32 v245, v245, v63, v64
	v_max3_f32 v245, v245, v65, v66
	v_max3_f32 v245, v245, v67, v68
	v_max3_f32 v245, v245, v69, v70
	v_max3_f32 v245, v245, v71, v72
	v_max3_f32 v245, v245, v73, v74
	v_max3_f32 v245, v245, v75, v76
	v_max3_f32 v245, v245, v77, v78
	v_max_f32_e32 v245, v245, v79
	ds_bpermute_b32 v148, v239, v245
	s_waitcnt lgkmcnt(0)
	v_max_f32_e32 v245, v245, v148
	ds_bpermute_b32 v148, v240, v245
	s_waitcnt lgkmcnt(0)
	v_max_f32_e32 v245, v245, v148
	v_sub_f32_e32 v44, v44, v245
	v_sub_f32_e32 v45, v45, v245
	v_sub_f32_e32 v46, v46, v245
	v_sub_f32_e32 v47, v47, v245
	v_exp_f32_e32 v44, v44
	v_exp_f32_e32 v45, v45
	v_exp_f32_e32 v46, v46
	v_exp_f32_e32 v47, v47
	v_sub_f32_e32 v48, v48, v245
	v_sub_f32_e32 v49, v49, v245
	v_sub_f32_e32 v50, v50, v245
	v_sub_f32_e32 v51, v51, v245
	v_exp_f32_e32 v48, v48
	v_exp_f32_e32 v49, v49
	v_exp_f32_e32 v50, v50
	v_exp_f32_e32 v51, v51
	v_mov_b32_e32 v149, v44
	v_mov_b32_e32 v150, v45
	v_mov_b32_e32 v151, v46
	v_mov_b32_e32 v152, v47
	v_cvt_pk_bf16_f32 v44, v44, v45
	v_cvt_pk_bf16_f32 v45, v46, v47
	v_sub_f32_e32 v52, v52, v245
	v_sub_f32_e32 v53, v53, v245
	v_sub_f32_e32 v54, v54, v245
	v_sub_f32_e32 v55, v55, v245
	v_exp_f32_e32 v52, v52
	v_exp_f32_e32 v53, v53
	v_exp_f32_e32 v54, v54
	v_exp_f32_e32 v55, v55
	v_add_f32_e32 v149, v149, v48
	v_add_f32_e32 v150, v150, v49
	v_add_f32_e32 v151, v151, v50
	v_add_f32_e32 v152, v152, v51
	v_cvt_pk_bf16_f32 v46, v48, v49
	v_cvt_pk_bf16_f32 v47, v50, v51
	v_sub_f32_e32 v56, v56, v245
	v_sub_f32_e32 v57, v57, v245
	v_sub_f32_e32 v58, v58, v245
	v_sub_f32_e32 v59, v59, v245
	v_exp_f32_e32 v56, v56
	v_exp_f32_e32 v57, v57
	v_exp_f32_e32 v58, v58
	v_exp_f32_e32 v59, v59
	v_add_f32_e32 v149, v149, v52
	v_add_f32_e32 v150, v150, v53
	v_add_f32_e32 v151, v151, v54
	v_add_f32_e32 v152, v152, v55
	v_cvt_pk_bf16_f32 v52, v52, v53
	v_cvt_pk_bf16_f32 v53, v54, v55
	v_sub_f32_e32 v60, v60, v245
	v_sub_f32_e32 v61, v61, v245
	v_sub_f32_e32 v62, v62, v245
	v_sub_f32_e32 v63, v63, v245
	v_exp_f32_e32 v60, v60
	v_exp_f32_e32 v61, v61
	v_exp_f32_e32 v62, v62
	v_exp_f32_e32 v63, v63
	v_add_f32_e32 v149, v149, v56
	v_add_f32_e32 v150, v150, v57
	v_add_f32_e32 v151, v151, v58
	v_add_f32_e32 v152, v152, v59
	v_cvt_pk_bf16_f32 v54, v56, v57
	v_cvt_pk_bf16_f32 v55, v58, v59
	v_sub_f32_e32 v64, v64, v245
	v_sub_f32_e32 v65, v65, v245
	v_sub_f32_e32 v66, v66, v245
	v_sub_f32_e32 v67, v67, v245
	v_exp_f32_e32 v64, v64
	v_exp_f32_e32 v65, v65
	v_exp_f32_e32 v66, v66
	v_exp_f32_e32 v67, v67
	v_add_f32_e32 v149, v149, v60
	v_add_f32_e32 v150, v150, v61
	v_add_f32_e32 v151, v151, v62
	v_add_f32_e32 v152, v152, v63
	v_cvt_pk_bf16_f32 v60, v60, v61
	v_cvt_pk_bf16_f32 v61, v62, v63
	v_sub_f32_e32 v68, v68, v245
	v_sub_f32_e32 v69, v69, v245
	v_sub_f32_e32 v70, v70, v245
	v_sub_f32_e32 v71, v71, v245
	v_exp_f32_e32 v68, v68
	v_exp_f32_e32 v69, v69
	v_exp_f32_e32 v70, v70
	v_exp_f32_e32 v71, v71
	v_add_f32_e32 v149, v149, v64
	v_add_f32_e32 v150, v150, v65
	v_add_f32_e32 v151, v151, v66
	v_add_f32_e32 v152, v152, v67
	v_cvt_pk_bf16_f32 v62, v64, v65
	v_cvt_pk_bf16_f32 v63, v66, v67
	v_sub_f32_e32 v72, v72, v245
	v_sub_f32_e32 v73, v73, v245
	v_sub_f32_e32 v74, v74, v245
	v_sub_f32_e32 v75, v75, v245
	v_exp_f32_e32 v72, v72
	v_exp_f32_e32 v73, v73
	v_exp_f32_e32 v74, v74
	v_exp_f32_e32 v75, v75
	v_add_f32_e32 v149, v149, v68
	v_add_f32_e32 v150, v150, v69
	v_add_f32_e32 v151, v151, v70
	v_add_f32_e32 v152, v152, v71
	v_cvt_pk_bf16_f32 v68, v68, v69
	v_cvt_pk_bf16_f32 v69, v70, v71
	v_sub_f32_e32 v76, v76, v245
	v_sub_f32_e32 v77, v77, v245
	v_sub_f32_e32 v78, v78, v245
	v_sub_f32_e32 v79, v79, v245
	v_exp_f32_e32 v76, v76
	v_exp_f32_e32 v77, v77
	v_exp_f32_e32 v78, v78
	v_exp_f32_e32 v79, v79
	v_add_f32_e32 v149, v149, v72
	v_add_f32_e32 v150, v150, v73
	v_add_f32_e32 v151, v151, v74
	v_add_f32_e32 v152, v152, v75
	v_cvt_pk_bf16_f32 v70, v72, v73
	v_cvt_pk_bf16_f32 v71, v74, v75
	s_nop 0
	v_add_f32_e32 v149, v149, v76
	v_add_f32_e32 v150, v150, v77
	v_add_f32_e32 v151, v151, v78
	v_add_f32_e32 v152, v152, v79
	v_cvt_pk_bf16_f32 v76, v76, v77
	v_cvt_pk_bf16_f32 v77, v78, v79
	v_mov_b32_e32 v78, 0
	v_mov_b32_e32 v79, 0
	v_add_f32_e32 v149, v149, v150
	v_add_f32_e32 v151, v151, v152
	v_add_f32_e32 v246, v149, v151
	s_waitcnt lgkmcnt(0)
	v_mfma_f32_16x16x32_bf16 v[80:83], v[4:7], v[44:47], 0
	v_mfma_f32_16x16x32_bf16 v[84:87], v[8:11], v[44:47], 0
	v_mfma_f32_16x16x32_bf16 v[88:91], v[12:15], v[44:47], 0
	v_mfma_f32_16x16x32_bf16 v[92:95], v[16:19], v[44:47], 0
	ds_read_b64 v[4:5], v225 offset:0
	ds_read_b64 v[8:9], v225 offset:4096
	ds_read_b64 v[12:13], v225 offset:8192
	ds_read_b64 v[16:17], v225 offset:12288
	ds_read_b64 v[6:7], v226 offset:0
	ds_read_b64 v[10:11], v226 offset:4096
	ds_read_b64 v[14:15], v226 offset:8192
	ds_read_b64 v[18:19], v226 offset:12288
	v_mfma_f32_16x16x32_bf16 v[80:83], v[20:23], v[52:55], v[80:83]
	v_mfma_f32_16x16x32_bf16 v[84:87], v[24:27], v[52:55], v[84:87]
	v_mfma_f32_16x16x32_bf16 v[88:91], v[28:31], v[52:55], v[88:91]
	v_mfma_f32_16x16x32_bf16 v[92:95], v[32:35], v[52:55], v[92:95]
	ds_read_b64 v[20:21], v227 offset:0
	ds_read_b64 v[24:25], v227 offset:4096
	ds_read_b64 v[28:29], v227 offset:8192
	ds_read_b64 v[32:33], v227 offset:12288
	ds_read_b64 v[22:23], v228 offset:0
	ds_read_b64 v[26:27], v228 offset:4096
	ds_read_b64 v[30:31], v228 offset:8192
	ds_read_b64 v[34:35], v228 offset:12288
	ds_bpermute_b32 v148, v239, v246
	s_waitcnt lgkmcnt(9)
	v_mfma_f32_16x16x32_bf16 v[80:83], v[4:7], v[60:63], v[80:83]
	v_mfma_f32_16x16x32_bf16 v[84:87], v[8:11], v[60:63], v[84:87]
	v_mfma_f32_16x16x32_bf16 v[88:91], v[12:15], v[60:63], v[88:91]
	v_mfma_f32_16x16x32_bf16 v[92:95], v[16:19], v[60:63], v[92:95]
	ds_read_b64 v[4:5], v229 offset:0
	ds_read_b64 v[8:9], v229 offset:4096
	ds_read_b64 v[12:13], v229 offset:8192
	ds_read_b64 v[16:17], v229 offset:12288
	v_mov_b32_e32 v6, 0
	v_mov_b32_e32 v7, 0
	v_mov_b32_e32 v10, 0
	v_mov_b32_e32 v11, 0
	v_mov_b32_e32 v14, 0
	v_mov_b32_e32 v15, 0
	v_mov_b32_e32 v18, 0
	v_mov_b32_e32 v19, 0
	s_waitcnt lgkmcnt(5)
	v_mfma_f32_16x16x32_bf16 v[80:83], v[20:23], v[68:71], v[80:83]
	v_mfma_f32_16x16x32_bf16 v[84:87], v[24:27], v[68:71], v[84:87]
	v_mfma_f32_16x16x32_bf16 v[88:91], v[28:31], v[68:71], v[88:91]
	v_mfma_f32_16x16x32_bf16 v[92:95], v[32:35], v[68:71], v[92:95]
	s_waitcnt lgkmcnt(0)
	v_add_f32_e32 v246, v246, v148
	s_nop 0
	v_mfma_f32_16x16x32_bf16 v[80:83], v[4:7], v[76:79], v[80:83]
	v_mfma_f32_16x16x32_bf16 v[84:87], v[8:11], v[76:79], v[84:87]
	v_mfma_f32_16x16x32_bf16 v[88:91], v[12:15], v[76:79], v[88:91]
	v_mfma_f32_16x16x32_bf16 v[92:95], v[16:19], v[76:79], v[92:95]
	ds_bpermute_b32 v148, v240, v246
	s_waitcnt lgkmcnt(0)
	v_add_f32_e32 v246, v246, v148
	v_rcp_f32_e32 v149, v246
	v_log_f32_e32 v150, v246
	s_nop 0
	v_add_f32_e32 v151, v245, v150
	v_mul_f32_e32 v151, 0x3f317218, v151
	v_max_f32_e32 v152, v121, v151
	v_sub_f32_e32 v153, v121, v152
	v_sub_f32_e32 v154, v151, v152
	v_mul_f32_e32 v153, 0x3fb8aa3b, v153
	v_mul_f32_e32 v154, 0x3fb8aa3b, v154
	v_exp_f32_e32 v153, v153
	v_exp_f32_e32 v154, v154
	s_nop 0
	v_add_f32_e32 v155, v153, v154
	v_rcp_f32_e32 v146, v155
	v_log_f32_e32 v150, v155
	s_nop 0
	v_mul_f32_e32 v154, v154, v146
	v_mul_f32_e32 v146, v153, v146
	v_mul_f32_e32 v147, v149, v154
	v_mul_f32_e32 v150, 0x3f317218, v150
	v_add_f32_e32 v140, v152, v150
	v_mul_f32_e32 v80, v80, v147
	v_mul_f32_e32 v81, v81, v147
	v_mul_f32_e32 v82, v82, v147
	v_mul_f32_e32 v83, v83, v147
	v_mul_f32_e32 v84, v84, v147
	v_mul_f32_e32 v85, v85, v147
	v_mul_f32_e32 v86, v86, v147
	v_mul_f32_e32 v87, v87, v147
	v_mul_f32_e32 v88, v88, v147
	v_mul_f32_e32 v89, v89, v147
	v_mul_f32_e32 v90, v90, v147
	v_mul_f32_e32 v91, v91, v147
	v_mul_f32_e32 v92, v92, v147
	v_mul_f32_e32 v93, v93, v147
	v_mul_f32_e32 v94, v94, v147
	v_mul_f32_e32 v95, v95, v147
	v_lshlrev_b32_e32 v141, 16, v122
	v_and_b32_e32 v142, 0xffff0000, v122
	v_lshlrev_b32_e32 v143, 16, v123
	v_and_b32_e32 v144, 0xffff0000, v123
	v_fmac_f32_e32 v80, v146, v141
	v_fmac_f32_e32 v81, v146, v142
	v_fmac_f32_e32 v82, v146, v143
	v_fmac_f32_e32 v83, v146, v144
	v_cvt_pk_bf16_f32 v132, v80, v81
	v_cvt_pk_bf16_f32 v133, v82, v83
	v_lshlrev_b32_e32 v141, 16, v124
	v_and_b32_e32 v142, 0xffff0000, v124
	v_lshlrev_b32_e32 v143, 16, v125
	v_and_b32_e32 v144, 0xffff0000, v125
	v_fmac_f32_e32 v84, v146, v141
	v_fmac_f32_e32 v85, v146, v142
	v_fmac_f32_e32 v86, v146, v143
	v_fmac_f32_e32 v87, v146, v144
	v_cvt_pk_bf16_f32 v134, v84, v85
	v_cvt_pk_bf16_f32 v135, v86, v87
	v_lshlrev_b32_e32 v141, 16, v126
	v_and_b32_e32 v142, 0xffff0000, v126
	v_lshlrev_b32_e32 v143, 16, v127
	v_and_b32_e32 v144, 0xffff0000, v127
	v_fmac_f32_e32 v88, v146, v141
	v_fmac_f32_e32 v89, v146, v142
	v_fmac_f32_e32 v90, v146, v143
	v_fmac_f32_e32 v91, v146, v144
	v_cvt_pk_bf16_f32 v136, v88, v89
	v_cvt_pk_bf16_f32 v137, v90, v91
	v_lshlrev_b32_e32 v141, 16, v128
	v_and_b32_e32 v142, 0xffff0000, v128
	v_lshlrev_b32_e32 v143, 16, v129
	v_and_b32_e32 v144, 0xffff0000, v129
	v_fmac_f32_e32 v92, v146, v141
	v_fmac_f32_e32 v93, v146, v142
	v_fmac_f32_e32 v94, v146, v143
	v_fmac_f32_e32 v95, v146, v144
	v_cvt_pk_bf16_f32 v138, v92, v93
	v_cvt_pk_bf16_f32 v139, v94, v95
	s_mov_b64 s[26:27], s[86:87]
	s_mov_b64 s[28:29], s[88:89]
	s_mov_b64 s[86:87], s[12:13]
	s_mov_b64 s[88:89], s[14:15]
	s_mov_b32 s4, s83
	s_mov_b32 s5, s84
	s_waitcnt vmcnt(0)
	s_barrier
	ds_read_b128 v[4:7], v230 offset:16384
	ds_read_b128 v[8:11], v231 offset:16384
	ds_read_b128 v[12:15], v230 offset:18432
	ds_read_b128 v[16:19], v231 offset:18432
	ds_read_b128 v[20:23], v230 offset:20480
	ds_read_b128 v[24:27], v231 offset:20480
	ds_read_b128 v[28:31], v230 offset:22528
	ds_read_b128 v[32:35], v231 offset:22528
	ds_read_b128 v[36:39], v230 offset:24576
	ds_read_b128 v[40:43], v231 offset:24576
	global_store_dwordx2 v237, v[132:133], s[26:27]
	global_store_dwordx2 v237, v[134:135], s[26:27] offset:32
	global_store_dwordx2 v237, v[136:137], s[26:27] offset:64
	global_store_dwordx2 v237, v[138:139], s[26:27] offset:96
	s_mov_b64 s[90:91], exec
	s_mov_b64 exec, 0xffff
	global_store_dword v238, v140, s[28:29]
	s_mov_b64 exec, s[90:91]
	s_add_u32 s84, s5, s4
	s_xor_b32 s83, s4, 1
	s_mul_i32 s74, s84, 256
	s_lshl_b32 s75, s83, 7
	s_add_u32 s74, s74, s75
	s_lshl_b32 s75, s74, 7
	s_add_u32 s16, s60, s75
	s_addc_u32 s17, s61, 0
	s_lshl_b32 s75, s74, 1
	s_add_u32 s24, s64, s75
	s_addc_u32 s25, s65, 0
	s_add_u32 m0, s70, 0xc000
	s_nop 0
	global_load_lds_dwordx4 v232, s[16:17] nt
	s_add_u32 m0, s70, 0xe000
	s_nop 0
	global_load_lds_dwordx4 v233, s[16:17] nt
	s_add_u32 m0, s70, 0x1c000
	s_nop 0
	global_load_lds_dwordx4 v234, s[24:25] nt
	s_add_u32 m0, s70, 0x1e000
	s_nop 0
	global_load_lds_dwordx4 v235, s[24:25] nt
	s_lshl_b32 s74, s83, 11
	s_add_u32 s74, s74, s84
	s_lshl_b32 s75, s74, 7
	s_add_u32 s10, s30, s75
	s_addc_u32 s11, s31, 0
	s_add_u32 s12, s34, s75
	s_addc_u32 s13, s35, 0
	s_lshl_b32 s75, s74, 2
	s_add_u32 s14, s58, s75
	s_addc_u32 s15, s59, 0
	global_load_dwordx4 v[104:107], v236, s[10:11]
	global_load_dwordx4 v[108:111], v236, s[10:11] offset:64
	global_load_dwordx2 v[122:123], v237, s[12:13]
	global_load_dwordx2 v[124:125], v237, s[12:13] offset:32
	global_load_dwordx2 v[126:127], v237, s[12:13] offset:64
	global_load_dwordx2 v[128:129], v237, s[12:13] offset:96
	global_load_dword v121, v238, s[14:15]
	s_waitcnt lgkmcnt(0)
	v_mfma_f32_16x16x32_bf16 v[44:47], v[4:7], v[96:99], 0
	v_mfma_f32_16x16x32_bf16 v[48:51], v[12:15], v[96:99], 0
	v_mfma_f32_16x16x32_bf16 v[52:55], v[20:23], v[96:99], 0
	v_mfma_f32_16x16x32_bf16 v[56:59], v[28:31], v[96:99], 0
	v_mfma_f32_16x16x32_bf16 v[60:63], v[36:39], v[96:99], 0
	v_mfma_f32_16x16x32_bf16 v[44:47], v[8:11], v[100:103], v[44:47]
	v_mfma_f32_16x16x32_bf16 v[48:51], v[16:19], v[100:103], v[48:51]
	v_mfma_f32_16x16x32_bf16 v[52:55], v[24:27], v[100:103], v[52:55]
	v_mfma_f32_16x16x32_bf16 v[56:59], v[32:35], v[100:103], v[56:59]
	v_mfma_f32_16x16x32_bf16 v[60:63], v[40:43], v[100:103], v[60:63]
	ds_read_b128 v[4:7], v230 offset:26624
	ds_read_b128 v[8:11], v231 offset:26624
	ds_read_b128 v[12:15], v230 offset:28672
	ds_read_b128 v[16:19], v231 offset:28672
	ds_read_b128 v[20:23], v230 offset:30720
	ds_read_b128 v[24:27], v231 offset:30720
	ds_read_b128 v[28:31], v230 offset:32768
	ds_read_b128 v[32:35], v231 offset:32768
	s_nop 1
	v_fma_f32 v44, v44, s79, v185
	v_fma_f32 v45, v45, s79, v186
	v_fma_f32 v46, v46, s79, v187
	v_fma_f32 v47, v47, s79, v188
	v_fma_f32 v48, v48, s79, v189
	v_fma_f32 v49, v49, s79, v190
	v_fma_f32 v50, v50, s79, v191
	v_fma_f32 v51, v51, s79, v192
	v_fma_f32 v52, v52, s79, v193
	v_fma_f32 v53, v53, s79, v194
	v_fma_f32 v54, v54, s79, v195
	v_fma_f32 v55, v55, s79, v196
	v_fma_f32 v56, v56, s79, v197
	v_fma_f32 v57, v57, s79, v198
	v_fma_f32 v58, v58, s79, v199
	v_fma_f32 v59, v59, s79, v200
	v_fma_f32 v60, v60, s79, v201
	v_fma_f32 v61, v61, s79, v202
	v_fma_f32 v62, v62, s79, v203
	v_fma_f32 v63, v63, s79, v204
	s_waitcnt lgkmcnt(0)
	v_mfma_f32_16x16x32_bf16 v[64:67], v[4:7], v[96:99], 0
	v_mfma_f32_16x16x32_bf16 v[68:71], v[12:15], v[96:99], 0
	v_mfma_f32_16x16x32_bf16 v[72:75], v[20:23], v[96:99], 0
	v_mfma_f32_16x16x32_bf16 v[76:79], v[28:31], v[96:99], 0
	v_mfma_f32_16x16x32_bf16 v[64:67], v[8:11], v[100:103], v[64:67]
	v_mfma_f32_16x16x32_bf16 v[68:71], v[16:19], v[100:103], v[68:71]
	v_mfma_f32_16x16x32_bf16 v[72:75], v[24:27], v[100:103], v[72:75]
	v_mfma_f32_16x16x32_bf16 v[76:79], v[32:35], v[100:103], v[76:79]
	ds_read_b64 v[4:5], v221 offset:16384
	ds_read_b64 v[8:9], v221 offset:20480
	ds_read_b64 v[12:13], v221 offset:24576
	ds_read_b64 v[16:17], v221 offset:28672
	ds_read_b64 v[6:7], v222 offset:16384
	ds_read_b64 v[10:11], v222 offset:20480
	ds_read_b64 v[14:15], v222 offset:24576
	ds_read_b64 v[18:19], v222 offset:28672
	s_nop 1
	v_fma_f32 v64, v64, s79, v205
	v_fma_f32 v65, v65, s79, v206
	v_fma_f32 v66, v66, s79, v207
	v_fma_f32 v67, v67, s79, v208
	v_fma_f32 v68, v68, s79, v209
	v_fma_f32 v69, v69, s79, v210
	v_fma_f32 v70, v70, s79, v211
	v_fma_f32 v71, v71, s79, v212
	v_fma_f32 v72, v72, s79, v213
	v_fma_f32 v73, v73, s79, v214
	v_fma_f32 v74, v74, s79, v215
	v_fma_f32 v75, v75, s79, v216
	v_fma_f32 v76, v76, s79, v217
	v_fma_f32 v77, v77, s79, v218
	v_fma_f32 v78, v78, s79, v219
	v_fma_f32 v79, v79, s79, v220
	ds_read_b64 v[20:21], v223 offset:16384
	ds_read_b64 v[24:25], v223 offset:20480
	ds_read_b64 v[28:29], v223 offset:24576
	ds_read_b64 v[32:33], v223 offset:28672
	ds_read_b64 v[22:23], v224 offset:16384
	ds_read_b64 v[26:27], v224 offset:20480
	ds_read_b64 v[30:31], v224 offset:24576
	ds_read_b64 v[34:35], v224 offset:28672
	s_cmp_lg_u32 s4, 0
	s_cbranch_scc1 .Lat991_i2_nomask
	s_cmp_le_u32 s6, 0
	s_cbranch_scc1 .Lat991_i2_nomask
	v_mov_b32_e32 v44, v244
	v_mov_b32_e32 v45, v244
	v_mov_b32_e32 v46, v244
	v_mov_b32_e32 v47, v244
	s_cmp_le_u32 s6, 1
	s_cbranch_scc1 .Lat991_i2_nomask
	v_mov_b32_e32 v48, v244
	v_mov_b32_e32 v49, v244
	v_mov_b32_e32 v50, v244
	v_mov_b32_e32 v51, v244
	s_cmp_le_u32 s6, 2
	s_cbranch_scc1 .Lat991_i2_nomask
	v_mov_b32_e32 v52, v244
	v_mov_b32_e32 v53, v244
	v_mov_b32_e32 v54, v244
	v_mov_b32_e32 v55, v244
	s_cmp_le_u32 s6, 3
	s_cbranch_scc1 .Lat991_i2_nomask
	v_mov_b32_e32 v56, v244
	v_mov_b32_e32 v57, v244
	v_mov_b32_e32 v58, v244
	v_mov_b32_e32 v59, v244
	s_cmp_le_u32 s6, 4
	s_cbranch_scc1 .Lat991_i2_nomask
	v_mov_b32_e32 v60, v244
	v_mov_b32_e32 v61, v244
	v_mov_b32_e32 v62, v244
	v_mov_b32_e32 v63, v244
	s_cmp_le_u32 s6, 5
	s_cbranch_scc1 .Lat991_i2_nomask
	v_mov_b32_e32 v64, v244
	v_mov_b32_e32 v65, v244
	v_mov_b32_e32 v66, v244
	v_mov_b32_e32 v67, v244
	s_cmp_le_u32 s6, 6
	s_cbranch_scc1 .Lat991_i2_nomask
	v_mov_b32_e32 v68, v244
	v_mov_b32_e32 v69, v244
	v_mov_b32_e32 v70, v244
	v_mov_b32_e32 v71, v244
	s_cmp_le_u32 s6, 7
	s_cbranch_scc1 .Lat991_i2_nomask
	v_mov_b32_e32 v72, v244
	v_mov_b32_e32 v73, v244
	v_mov_b32_e32 v74, v244
	v_mov_b32_e32 v75, v244
.Lat991_i2_nomask:
	v_max3_f32 v245, v44, v45, v46
	v_max3_f32 v245, v245, v47, v48
	v_max3_f32 v245, v245, v49, v50
	v_max3_f32 v245, v245, v51, v52
	v_max3_f32 v245, v245, v53, v54
	v_max3_f32 v245, v245, v55, v56
	v_max3_f32 v245, v245, v57, v58
	v_max3_f32 v245, v245, v59, v60
	v_max3_f32 v245, v245, v61, v62
	v_max3_f32 v245, v245, v63, v64
	v_max3_f32 v245, v245, v65, v66
	v_max3_f32 v245, v245, v67, v68
	v_max3_f32 v245, v245, v69, v70
	v_max3_f32 v245, v245, v71, v72
	v_max3_f32 v245, v245, v73, v74
	v_max3_f32 v245, v245, v75, v76
	v_max3_f32 v245, v245, v77, v78
	v_max_f32_e32 v245, v245, v79
	ds_bpermute_b32 v148, v239, v245
	s_waitcnt lgkmcnt(0)
	v_max_f32_e32 v245, v245, v148
	ds_bpermute_b32 v148, v240, v245
	s_waitcnt lgkmcnt(0)
	v_max_f32_e32 v245, v245, v148
	v_sub_f32_e32 v44, v44, v245
	v_sub_f32_e32 v45, v45, v245
	v_sub_f32_e32 v46, v46, v245
	v_sub_f32_e32 v47, v47, v245
	v_exp_f32_e32 v44, v44
	v_exp_f32_e32 v45, v45
	v_exp_f32_e32 v46, v46
	v_exp_f32_e32 v47, v47
	v_sub_f32_e32 v48, v48, v245
	v_sub_f32_e32 v49, v49, v245
	v_sub_f32_e32 v50, v50, v245
	v_sub_f32_e32 v51, v51, v245
	v_exp_f32_e32 v48, v48
	v_exp_f32_e32 v49, v49
	v_exp_f32_e32 v50, v50
	v_exp_f32_e32 v51, v51
	v_mov_b32_e32 v149, v44
	v_mov_b32_e32 v150, v45
	v_mov_b32_e32 v151, v46
	v_mov_b32_e32 v152, v47
	v_cvt_pk_bf16_f32 v44, v44, v45
	v_cvt_pk_bf16_f32 v45, v46, v47
	v_sub_f32_e32 v52, v52, v245
	v_sub_f32_e32 v53, v53, v245
	v_sub_f32_e32 v54, v54, v245
	v_sub_f32_e32 v55, v55, v245
	v_exp_f32_e32 v52, v52
	v_exp_f32_e32 v53, v53
	v_exp_f32_e32 v54, v54
	v_exp_f32_e32 v55, v55
	v_add_f32_e32 v149, v149, v48
	v_add_f32_e32 v150, v150, v49
	v_add_f32_e32 v151, v151, v50
	v_add_f32_e32 v152, v152, v51
	v_cvt_pk_bf16_f32 v46, v48, v49
	v_cvt_pk_bf16_f32 v47, v50, v51
	v_sub_f32_e32 v56, v56, v245
	v_sub_f32_e32 v57, v57, v245
	v_sub_f32_e32 v58, v58, v245
	v_sub_f32_e32 v59, v59, v245
	v_exp_f32_e32 v56, v56
	v_exp_f32_e32 v57, v57
	v_exp_f32_e32 v58, v58
	v_exp_f32_e32 v59, v59
	v_add_f32_e32 v149, v149, v52
	v_add_f32_e32 v150, v150, v53
	v_add_f32_e32 v151, v151, v54
	v_add_f32_e32 v152, v152, v55
	v_cvt_pk_bf16_f32 v52, v52, v53
	v_cvt_pk_bf16_f32 v53, v54, v55
	v_sub_f32_e32 v60, v60, v245
	v_sub_f32_e32 v61, v61, v245
	v_sub_f32_e32 v62, v62, v245
	v_sub_f32_e32 v63, v63, v245
	v_exp_f32_e32 v60, v60
	v_exp_f32_e32 v61, v61
	v_exp_f32_e32 v62, v62
	v_exp_f32_e32 v63, v63
	v_add_f32_e32 v149, v149, v56
	v_add_f32_e32 v150, v150, v57
	v_add_f32_e32 v151, v151, v58
	v_add_f32_e32 v152, v152, v59
	v_cvt_pk_bf16_f32 v54, v56, v57
	v_cvt_pk_bf16_f32 v55, v58, v59
	v_sub_f32_e32 v64, v64, v245
	v_sub_f32_e32 v65, v65, v245
	v_sub_f32_e32 v66, v66, v245
	v_sub_f32_e32 v67, v67, v245
	v_exp_f32_e32 v64, v64
	v_exp_f32_e32 v65, v65
	v_exp_f32_e32 v66, v66
	v_exp_f32_e32 v67, v67
	v_add_f32_e32 v149, v149, v60
	v_add_f32_e32 v150, v150, v61
	v_add_f32_e32 v151, v151, v62
	v_add_f32_e32 v152, v152, v63
	v_cvt_pk_bf16_f32 v60, v60, v61
	v_cvt_pk_bf16_f32 v61, v62, v63
	v_sub_f32_e32 v68, v68, v245
	v_sub_f32_e32 v69, v69, v245
	v_sub_f32_e32 v70, v70, v245
	v_sub_f32_e32 v71, v71, v245
	v_exp_f32_e32 v68, v68
	v_exp_f32_e32 v69, v69
	v_exp_f32_e32 v70, v70
	v_exp_f32_e32 v71, v71
	v_add_f32_e32 v149, v149, v64
	v_add_f32_e32 v150, v150, v65
	v_add_f32_e32 v151, v151, v66
	v_add_f32_e32 v152, v152, v67
	v_cvt_pk_bf16_f32 v62, v64, v65
	v_cvt_pk_bf16_f32 v63, v66, v67
	v_sub_f32_e32 v72, v72, v245
	v_sub_f32_e32 v73, v73, v245
	v_sub_f32_e32 v74, v74, v245
	v_sub_f32_e32 v75, v75, v245
	v_exp_f32_e32 v72, v72
	v_exp_f32_e32 v73, v73
	v_exp_f32_e32 v74, v74
	v_exp_f32_e32 v75, v75
	v_add_f32_e32 v149, v149, v68
	v_add_f32_e32 v150, v150, v69
	v_add_f32_e32 v151, v151, v70
	v_add_f32_e32 v152, v152, v71
	v_cvt_pk_bf16_f32 v68, v68, v69
	v_cvt_pk_bf16_f32 v69, v70, v71
	v_sub_f32_e32 v76, v76, v245
	v_sub_f32_e32 v77, v77, v245
	v_sub_f32_e32 v78, v78, v245
	v_sub_f32_e32 v79, v79, v245
	v_exp_f32_e32 v76, v76
	v_exp_f32_e32 v77, v77
	v_exp_f32_e32 v78, v78
	v_exp_f32_e32 v79, v79
	v_add_f32_e32 v149, v149, v72
	v_add_f32_e32 v150, v150, v73
	v_add_f32_e32 v151, v151, v74
	v_add_f32_e32 v152, v152, v75
	v_cvt_pk_bf16_f32 v70, v72, v73
	v_cvt_pk_bf16_f32 v71, v74, v75
	s_nop 0
	v_add_f32_e32 v149, v149, v76
	v_add_f32_e32 v150, v150, v77
	v_add_f32_e32 v151, v151, v78
	v_add_f32_e32 v152, v152, v79
	v_cvt_pk_bf16_f32 v76, v76, v77
	v_cvt_pk_bf16_f32 v77, v78, v79
	v_mov_b32_e32 v78, 0
	v_mov_b32_e32 v79, 0
	v_add_f32_e32 v149, v149, v150
	v_add_f32_e32 v151, v151, v152
	v_add_f32_e32 v246, v149, v151
	s_waitcnt lgkmcnt(0)
	v_mfma_f32_16x16x32_bf16 v[80:83], v[4:7], v[44:47], 0
	v_mfma_f32_16x16x32_bf16 v[84:87], v[8:11], v[44:47], 0
	v_mfma_f32_16x16x32_bf16 v[88:91], v[12:15], v[44:47], 0
	v_mfma_f32_16x16x32_bf16 v[92:95], v[16:19], v[44:47], 0
	ds_read_b64 v[4:5], v225 offset:16384
	ds_read_b64 v[8:9], v225 offset:20480
	ds_read_b64 v[12:13], v225 offset:24576
	ds_read_b64 v[16:17], v225 offset:28672
	ds_read_b64 v[6:7], v226 offset:16384
	ds_read_b64 v[10:11], v226 offset:20480
	ds_read_b64 v[14:15], v226 offset:24576
	ds_read_b64 v[18:19], v226 offset:28672
	v_mfma_f32_16x16x32_bf16 v[80:83], v[20:23], v[52:55], v[80:83]
	v_mfma_f32_16x16x32_bf16 v[84:87], v[24:27], v[52:55], v[84:87]
	v_mfma_f32_16x16x32_bf16 v[88:91], v[28:31], v[52:55], v[88:91]
	v_mfma_f32_16x16x32_bf16 v[92:95], v[32:35], v[52:55], v[92:95]
	ds_read_b64 v[20:21], v227 offset:16384
	ds_read_b64 v[24:25], v227 offset:20480
	ds_read_b64 v[28:29], v227 offset:24576
	ds_read_b64 v[32:33], v227 offset:28672
	ds_read_b64 v[22:23], v228 offset:16384
	ds_read_b64 v[26:27], v228 offset:20480
	ds_read_b64 v[30:31], v228 offset:24576
	ds_read_b64 v[34:35], v228 offset:28672
	ds_bpermute_b32 v148, v239, v246
	s_waitcnt lgkmcnt(9)
	v_mfma_f32_16x16x32_bf16 v[80:83], v[4:7], v[60:63], v[80:83]
	v_mfma_f32_16x16x32_bf16 v[84:87], v[8:11], v[60:63], v[84:87]
	v_mfma_f32_16x16x32_bf16 v[88:91], v[12:15], v[60:63], v[88:91]
	v_mfma_f32_16x16x32_bf16 v[92:95], v[16:19], v[60:63], v[92:95]
	ds_read_b64 v[4:5], v229 offset:16384
	ds_read_b64 v[8:9], v229 offset:20480
	ds_read_b64 v[12:13], v229 offset:24576
	ds_read_b64 v[16:17], v229 offset:28672
	v_mov_b32_e32 v6, 0
	v_mov_b32_e32 v7, 0
	v_mov_b32_e32 v10, 0
	v_mov_b32_e32 v11, 0
	v_mov_b32_e32 v14, 0
	v_mov_b32_e32 v15, 0
	v_mov_b32_e32 v18, 0
	v_mov_b32_e32 v19, 0
	s_waitcnt lgkmcnt(5)
	v_mfma_f32_16x16x32_bf16 v[80:83], v[20:23], v[68:71], v[80:83]
	v_mfma_f32_16x16x32_bf16 v[84:87], v[24:27], v[68:71], v[84:87]
	v_mfma_f32_16x16x32_bf16 v[88:91], v[28:31], v[68:71], v[88:91]
	v_mfma_f32_16x16x32_bf16 v[92:95], v[32:35], v[68:71], v[92:95]
	s_waitcnt lgkmcnt(0)
	v_add_f32_e32 v246, v246, v148
	s_nop 0
	v_mfma_f32_16x16x32_bf16 v[80:83], v[4:7], v[76:79], v[80:83]
	v_mfma_f32_16x16x32_bf16 v[84:87], v[8:11], v[76:79], v[84:87]
	v_mfma_f32_16x16x32_bf16 v[88:91], v[12:15], v[76:79], v[88:91]
	v_mfma_f32_16x16x32_bf16 v[92:95], v[16:19], v[76:79], v[92:95]
	ds_bpermute_b32 v148, v240, v246
	s_waitcnt lgkmcnt(0)
	v_add_f32_e32 v246, v246, v148
	v_rcp_f32_e32 v149, v246
	v_log_f32_e32 v150, v246
	s_nop 0
	v_add_f32_e32 v151, v245, v150
	v_mul_f32_e32 v151, 0x3f317218, v151
	v_max_f32_e32 v152, v120, v151
	v_sub_f32_e32 v153, v120, v152
	v_sub_f32_e32 v154, v151, v152
	v_mul_f32_e32 v153, 0x3fb8aa3b, v153
	v_mul_f32_e32 v154, 0x3fb8aa3b, v154
	v_exp_f32_e32 v153, v153
	v_exp_f32_e32 v154, v154
	s_nop 0
	v_add_f32_e32 v155, v153, v154
	v_rcp_f32_e32 v146, v155
	v_log_f32_e32 v150, v155
	s_nop 0
	v_mul_f32_e32 v154, v154, v146
	v_mul_f32_e32 v146, v153, v146
	v_mul_f32_e32 v147, v149, v154
	v_mul_f32_e32 v150, 0x3f317218, v150
	v_add_f32_e32 v140, v152, v150
	v_mul_f32_e32 v80, v80, v147
	v_mul_f32_e32 v81, v81, v147
	v_mul_f32_e32 v82, v82, v147
	v_mul_f32_e32 v83, v83, v147
	v_mul_f32_e32 v84, v84, v147
	v_mul_f32_e32 v85, v85, v147
	v_mul_f32_e32 v86, v86, v147
	v_mul_f32_e32 v87, v87, v147
	v_mul_f32_e32 v88, v88, v147
	v_mul_f32_e32 v89, v89, v147
	v_mul_f32_e32 v90, v90, v147
	v_mul_f32_e32 v91, v91, v147
	v_mul_f32_e32 v92, v92, v147
	v_mul_f32_e32 v93, v93, v147
	v_mul_f32_e32 v94, v94, v147
	v_mul_f32_e32 v95, v95, v147
	v_lshlrev_b32_e32 v141, 16, v112
	v_and_b32_e32 v142, 0xffff0000, v112
	v_lshlrev_b32_e32 v143, 16, v113
	v_and_b32_e32 v144, 0xffff0000, v113
	v_fmac_f32_e32 v80, v146, v141
	v_fmac_f32_e32 v81, v146, v142
	v_fmac_f32_e32 v82, v146, v143
	v_fmac_f32_e32 v83, v146, v144
	v_cvt_pk_bf16_f32 v132, v80, v81
	v_cvt_pk_bf16_f32 v133, v82, v83
	v_lshlrev_b32_e32 v141, 16, v114
	v_and_b32_e32 v142, 0xffff0000, v114
	v_lshlrev_b32_e32 v143, 16, v115
	v_and_b32_e32 v144, 0xffff0000, v115
	v_fmac_f32_e32 v84, v146, v141
	v_fmac_f32_e32 v85, v146, v142
	v_fmac_f32_e32 v86, v146, v143
	v_fmac_f32_e32 v87, v146, v144
	v_cvt_pk_bf16_f32 v134, v84, v85
	v_cvt_pk_bf16_f32 v135, v86, v87
	v_lshlrev_b32_e32 v141, 16, v116
	v_and_b32_e32 v142, 0xffff0000, v116
	v_lshlrev_b32_e32 v143, 16, v117
	v_and_b32_e32 v144, 0xffff0000, v117
	v_fmac_f32_e32 v88, v146, v141
	v_fmac_f32_e32 v89, v146, v142
	v_fmac_f32_e32 v90, v146, v143
	v_fmac_f32_e32 v91, v146, v144
	v_cvt_pk_bf16_f32 v136, v88, v89
	v_cvt_pk_bf16_f32 v137, v90, v91
	v_lshlrev_b32_e32 v141, 16, v118
	v_and_b32_e32 v142, 0xffff0000, v118
	v_lshlrev_b32_e32 v143, 16, v119
	v_and_b32_e32 v144, 0xffff0000, v119
	v_fmac_f32_e32 v92, v146, v141
	v_fmac_f32_e32 v93, v146, v142
	v_fmac_f32_e32 v94, v146, v143
	v_fmac_f32_e32 v95, v146, v144
	v_cvt_pk_bf16_f32 v138, v92, v93
	v_cvt_pk_bf16_f32 v139, v94, v95
	s_mov_b64 s[26:27], s[86:87]
	s_mov_b64 s[28:29], s[88:89]
	s_mov_b64 s[86:87], s[12:13]
	s_mov_b64 s[88:89], s[14:15]
	s_mov_b32 s4, s83
	s_mov_b32 s5, s84
	s_waitcnt vmcnt(0)
	s_barrier
	ds_read_b128 v[4:7], v230 offset:32768
	ds_read_b128 v[8:11], v231 offset:32768
	ds_read_b128 v[12:15], v230 offset:34816
	ds_read_b128 v[16:19], v231 offset:34816
	ds_read_b128 v[20:23], v230 offset:36864
	ds_read_b128 v[24:27], v231 offset:36864
	ds_read_b128 v[28:31], v230 offset:38912
	ds_read_b128 v[32:35], v231 offset:38912
	ds_read_b128 v[36:39], v230 offset:40960
	ds_read_b128 v[40:43], v231 offset:40960
	global_store_dwordx2 v237, v[132:133], s[26:27]
	global_store_dwordx2 v237, v[134:135], s[26:27] offset:32
	global_store_dwordx2 v237, v[136:137], s[26:27] offset:64
	global_store_dwordx2 v237, v[138:139], s[26:27] offset:96
	s_mov_b64 s[90:91], exec
	s_mov_b64 exec, 0xffff
	global_store_dword v238, v140, s[28:29]
	s_mov_b64 exec, s[90:91]
	s_cmp_eq_u32 s7, 1
	s_cbranch_scc1 .Lat991_i3_nonext
	s_add_u32 s84, s5, s4
	s_xor_b32 s83, s4, 1
	s_mul_i32 s74, s84, 256
	s_lshl_b32 s75, s83, 7
	s_add_u32 s74, s74, s75
	s_lshl_b32 s75, s74, 7
	s_add_u32 s16, s60, s75
	s_addc_u32 s17, s61, 0
	s_lshl_b32 s75, s74, 1
	s_add_u32 s24, s64, s75
	s_addc_u32 s25, s65, 0
	s_add_u32 m0, s70, 0x0
	s_nop 0
	global_load_lds_dwordx4 v232, s[16:17] nt
	s_add_u32 m0, s70, 0x2000
	s_nop 0
	global_load_lds_dwordx4 v233, s[16:17] nt
	s_add_u32 m0, s70, 0x10000
	s_nop 0
	global_load_lds_dwordx4 v234, s[24:25] nt
	s_add_u32 m0, s70, 0x12000
	s_nop 0
	global_load_lds_dwordx4 v235, s[24:25] nt
	s_lshl_b32 s74, s83, 11
	s_add_u32 s74, s74, s84
	s_lshl_b32 s75, s74, 7
	s_add_u32 s10, s30, s75
	s_addc_u32 s11, s31, 0
	s_add_u32 s12, s34, s75
	s_addc_u32 s13, s35, 0
	s_lshl_b32 s75, s74, 2
	s_add_u32 s14, s58, s75
	s_addc_u32 s15, s59, 0
	global_load_dwordx4 v[96:99], v236, s[10:11]
	global_load_dwordx4 v[100:103], v236, s[10:11] offset:64
	global_load_dwordx2 v[112:113], v237, s[12:13]
	global_load_dwordx2 v[114:115], v237, s[12:13] offset:32
	global_load_dwordx2 v[116:117], v237, s[12:13] offset:64
	global_load_dwordx2 v[118:119], v237, s[12:13] offset:96
	global_load_dword v120, v238, s[14:15]
